# P10 set-up sorts: xor-1/2/4/8 lane exchanges as DPP moves instead of ds_bpermute round trips (xor-16/32 stay on ds_bpermute, LDS waits in the region made full)
# baseline (speedup 1.0000x reference)
.LBB0_933:
	s_andn2_b64 vcc, exec, s[0:1]
	s_cbranch_vccnz .LBB0_1015
	s_add_u32 s12, s72, 0x2b00000
	s_addc_u32 s0, s73, 0
	s_add_u32 s2, s72, 0x1eb00000
	s_addc_u32 s3, s73, 0
	s_lshl_b32 s1, s90, 6
	s_lshl_b32 s4, s91, 3
	s_add_i32 s22, s1, s4
	s_load_dwordx2 s[16:17], s[68:69], 0x78
	s_waitcnt lgkmcnt(0)
	s_lshl_b32 s1, s91, 14
	v_and_b32_e32 v78, 63, v0
	s_ashr_i32 s23, s22, 31
	s_load_dwordx2 s[18:19], s[68:69], 0x80
	s_waitcnt lgkmcnt(0)
	v_mov_b32_e32 v46, v78
	s_add_i32 s26, s1, 0
	s_lshl_b64 s[24:25], s[22:23], 9
	s_load_dwordx2 s[20:21], s[68:69], 0x88
	s_waitcnt lgkmcnt(0)
	s_add_u32 s4, s2, s24
	v_lshlrev_b32_e32 v44, 4, v46
	v_ashrrev_i32_e32 v47, 31, v46
	v_ashrrev_i32_e32 v45, 31, v44
	s_addc_u32 s5, s3, s25
	v_lshlrev_b64 v[50:51], 2, v[46:47]
	v_lshl_add_u64 v[48:49], v[44:45], 1, s[70:71]
	v_lshl_add_u64 v[4:5], s[4:5], 0, v[50:51]
	s_lshl_b64 s[4:5], s[22:23], 12
	v_lshl_add_u64 v[14:15], v[48:49], 0, s[4:5]
	global_load_dword v16, v[4:5], off
	global_load_dword v17, v[4:5], off offset:256
	global_load_dwordx4 v[0:3], v[14:15], off
	global_load_dwordx4 v[6:9], v[14:15], off offset:16
	global_load_dwordx4 v[10:13], v[14:15], off offset:2048
	global_load_dwordx4 v[28:31], v[14:15], off offset:2064
	s_or_b32 s4, s22, 1
	s_ashr_i32 s5, s4, 31
	s_lshl_b64 s[6:7], s[4:5], 9
	s_add_u32 s6, s2, s6
	s_addc_u32 s7, s3, s7
	s_lshl_b64 s[4:5], s[4:5], 12
	v_lshl_add_u64 v[4:5], s[6:7], 0, v[50:51]
	v_lshl_add_u64 v[14:15], v[48:49], 0, s[4:5]
	global_load_dword v56, v[4:5], off
	global_load_dword v62, v[4:5], off offset:256
	global_load_dwordx4 v[32:35], v[14:15], off offset:16
	global_load_dwordx4 v[40:43], v[14:15], off
	v_add_u32_e32 v55, 64, v46
	s_mov_b32 s1, 0xc0f00000
	v_mov_b32_e32 v52, 0x40f00000
	v_add_u32_e32 v64, s26, v44
	s_movk_i32 s4, 0x80
	v_lshlrev_b32_e32 v45, 3, v46
	s_mov_b32 s15, 0x20000
	s_brev_b32 s14, -2
	v_lshlrev_b32_e32 v109, 2, v46
	v_mov_b32_e32 v91, 0
	s_mov_b32 s23, 0
	v_mov_b32_e32 v90, 0x7f7f7f7f
	s_waitcnt vmcnt(0)
	v_lshl_or_b32 v54, v16, 10, v46
	v_lshl_or_b32 v53, v17, 10, v55
	v_lshlrev_b32_e32 v4, 16, v0
	v_and_b32_e32 v0, 0xffff0000, v0
	v_lshlrev_b32_e32 v5, 16, v1
	v_and_b32_e32 v1, 0xffff0000, v1
	v_lshlrev_b32_e32 v19, 16, v7
	v_and_b32_e32 v7, 0xffff0000, v7
	v_lshlrev_b32_e32 v20, 16, v8
	v_and_b32_e32 v8, 0xffff0000, v8
	v_lshlrev_b32_e32 v16, 16, v2
	v_lshlrev_b32_e32 v17, 16, v3
	v_add_f32_e32 v21, v0, v0
	v_add_f32_e32 v22, v1, v1
	v_add_f32_e32 v7, v7, v7
	v_add_f32_e32 v8, v8, v8
	v_and_b32_e32 v2, 0xffff0000, v2
	v_add_f32_e32 v23, v16, v16
	v_add_f32_e32 v25, v17, v17
	v_med3_f32 v16, v21, s1, v52
	v_med3_f32 v17, v22, s1, v52
	v_med3_f32 v21, v7, s1, v52
	v_med3_f32 v22, v8, s1, v52
	v_lshlrev_b32_e32 v7, 16, v9
	v_and_b32_e32 v8, 0xffff0000, v9
	v_and_b32_e32 v9, 0xffff0000, v10
	v_lshlrev_b32_e32 v18, 16, v6
	v_add_f32_e32 v24, v2, v2
	v_add_f32_e32 v8, v8, v8
	v_add_f32_e32 v9, v9, v9
	v_and_b32_e32 v3, 0xffff0000, v3
	v_and_b32_e32 v6, 0xffff0000, v6
	v_add_f32_e32 v5, v5, v5
	v_add_f32_e32 v27, v18, v18
	v_add_f32_e32 v36, v19, v19
	v_med3_f32 v2, v23, s1, v52
	v_med3_f32 v18, v24, s1, v52
	v_med3_f32 v23, v8, s1, v52
	v_lshlrev_b32_e32 v8, 16, v10
	v_med3_f32 v24, v9, s1, v52
	v_lshlrev_b32_e32 v9, 16, v11
	v_and_b32_e32 v10, 0xffff0000, v11
	v_and_b32_e32 v11, 0xffff0000, v12
	v_add_f32_e32 v26, v3, v3
	v_add_f32_e32 v6, v6, v6
	v_add_f32_e32 v37, v20, v20
	v_med3_f32 v1, v5, s1, v52
	v_med3_f32 v5, v36, s1, v52
	v_add_f32_e32 v10, v10, v10
	v_add_f32_e32 v11, v11, v11
	v_lshlrev_b32_e32 v36, 16, v30
	v_med3_f32 v3, v25, s1, v52
	v_med3_f32 v19, v26, s1, v52
	v_med3_f32 v20, v6, s1, v52
	v_med3_f32 v6, v37, s1, v52
	v_med3_f32 v25, v10, s1, v52
	v_lshlrev_b32_e32 v10, 16, v12
	v_med3_f32 v26, v11, s1, v52
	v_lshlrev_b32_e32 v11, 16, v13
	v_and_b32_e32 v12, 0xffff0000, v13
	v_and_b32_e32 v13, 0xffff0000, v28
	v_add_f32_e32 v47, v36, v36
	global_load_dwordx4 v[36:39], v[14:15], off offset:2064
	global_load_dwordx4 v[58:61], v[14:15], off offset:2048
	v_and_b32_e32 v15, 0xffff0000, v30
	v_add_f32_e32 v4, v4, v4
	v_add_f32_e32 v12, v12, v12
	v_add_f32_e32 v13, v13, v13
	v_add_f32_e32 v15, v15, v15
	v_med3_f32 v0, v4, s1, v52
	v_med3_f32 v4, v27, s1, v52
	v_med3_f32 v27, v12, s1, v52
	v_lshlrev_b32_e32 v12, 16, v28
	v_med3_f32 v28, v13, s1, v52
	v_lshlrev_b32_e32 v13, 16, v29
	v_and_b32_e32 v29, 0xffff0000, v29
	v_med3_f32 v30, v15, s1, v52
	v_lshlrev_b32_e32 v15, 16, v31
	v_and_b32_e32 v31, 0xffff0000, v31
	v_add_f32_e32 v7, v7, v7
	v_add_f32_e32 v8, v8, v8
	v_add_f32_e32 v9, v9, v9
	v_add_f32_e32 v10, v10, v10
	v_add_f32_e32 v11, v11, v11
	v_add_f32_e32 v12, v12, v12
	v_add_f32_e32 v13, v13, v13
	v_add_f32_e32 v29, v29, v29
	v_add_f32_e32 v15, v15, v15
	v_add_f32_e32 v31, v31, v31
	v_med3_f32 v7, v7, s1, v52
	v_med3_f32 v8, v8, s1, v52
	v_med3_f32 v9, v9, s1, v52
	v_med3_f32 v10, v10, s1, v52
	v_med3_f32 v11, v11, s1, v52
	v_med3_f32 v12, v12, s1, v52
	v_med3_f32 v13, v13, s1, v52
	v_med3_f32 v29, v29, s1, v52
	v_med3_f32 v14, v47, s1, v52
	v_med3_f32 v15, v15, s1, v52
	v_med3_f32 v31, v31, s1, v52
	v_cvt_scalef32_2xpk16_fp6_f32 v[0:5], v[0:15], v[16:31], 1.0
	ds_write_b128 v64, v[0:3] offset:4096
	v_lshlrev_b32_e32 v0, 10, v56
	v_or3_b32 v57, v46, v0, s4
	v_lshlrev_b32_e32 v0, 10, v62
	v_or3_b32 v56, v55, v0, s4
	s_or_b32 s4, s22, 2
	s_ashr_i32 s5, s4, 31
	s_lshl_b64 s[6:7], s[4:5], 9
	s_add_u32 s6, s2, s6
	s_addc_u32 s7, s3, s7
	v_lshl_add_u64 v[6:7], s[6:7], 0, v[50:51]
	global_load_dword v65, v[6:7], off
	global_load_dword v72, v[6:7], off offset:256
	s_lshl_b64 s[4:5], s[4:5], 12
	v_lshl_add_u64 v[70:71], v[48:49], 0, s[4:5]
	global_load_dwordx4 v[66:69], v[70:71], off
	v_add_u32_e32 v47, s26, v45
	ds_write_b64 v47, v[4:5] offset:5120
	v_and_b32_e32 v1, 0xffff0000, v40
	v_and_b32_e32 v2, 0xffff0000, v41
	v_and_b32_e32 v3, 0xffff0000, v42
	v_and_b32_e32 v4, 0xffff0000, v43
	v_and_b32_e32 v5, 0xffff0000, v32
	v_and_b32_e32 v6, 0xffff0000, v33
	v_and_b32_e32 v7, 0xffff0000, v34
	v_and_b32_e32 v8, 0xffff0000, v35
	v_add_f32_e32 v1, v1, v1
	v_add_f32_e32 v2, v2, v2
	v_add_f32_e32 v3, v3, v3
	v_add_f32_e32 v4, v4, v4
	v_add_f32_e32 v5, v5, v5
	v_add_f32_e32 v6, v6, v6
	v_add_f32_e32 v7, v7, v7
	v_add_f32_e32 v8, v8, v8
	v_lshlrev_b32_e32 v0, 16, v40
	v_med3_f32 v16, v1, s1, v52
	v_lshlrev_b32_e32 v1, 16, v41
	v_med3_f32 v17, v2, s1, v52
	v_lshlrev_b32_e32 v2, 16, v42
	v_med3_f32 v18, v3, s1, v52
	v_lshlrev_b32_e32 v3, 16, v43
	s_waitcnt vmcnt(0)
	v_and_b32_e32 v13, 0xffff0000, v36
	v_and_b32_e32 v9, 0xffff0000, v58
	v_and_b32_e32 v10, 0xffff0000, v59
	v_and_b32_e32 v11, 0xffff0000, v60
	v_and_b32_e32 v12, 0xffff0000, v61
	v_and_b32_e32 v14, 0xffff0000, v37
	v_and_b32_e32 v15, 0xffff0000, v38
	v_add_f32_e32 v9, v9, v9
	v_add_f32_e32 v10, v10, v10
	v_add_f32_e32 v11, v11, v11
	v_add_f32_e32 v12, v12, v12
	v_add_f32_e32 v13, v13, v13
	v_add_f32_e32 v14, v14, v14
	v_add_f32_e32 v15, v15, v15
	v_med3_f32 v19, v4, s1, v52
	v_lshlrev_b32_e32 v4, 16, v32
	v_med3_f32 v20, v5, s1, v52
	v_lshlrev_b32_e32 v5, 16, v33
	v_med3_f32 v21, v6, s1, v52
	v_lshlrev_b32_e32 v6, 16, v34
	v_med3_f32 v22, v7, s1, v52
	v_lshlrev_b32_e32 v7, 16, v35
	v_med3_f32 v23, v8, s1, v52
	v_lshlrev_b32_e32 v8, 16, v58
	v_med3_f32 v24, v9, s1, v52
	v_lshlrev_b32_e32 v9, 16, v59
	v_med3_f32 v25, v10, s1, v52
	v_lshlrev_b32_e32 v10, 16, v60
	v_med3_f32 v26, v11, s1, v52
	v_lshlrev_b32_e32 v11, 16, v61
	v_med3_f32 v27, v12, s1, v52
	v_lshlrev_b32_e32 v12, 16, v36
	v_med3_f32 v28, v13, s1, v52
	v_lshlrev_b32_e32 v13, 16, v37
	v_med3_f32 v29, v14, s1, v52
	v_lshlrev_b32_e32 v14, 16, v38
	v_med3_f32 v30, v15, s1, v52
	v_lshlrev_b32_e32 v15, 16, v39
	v_and_b32_e32 v31, 0xffff0000, v39
	v_add_f32_e32 v0, v0, v0
	v_add_f32_e32 v1, v1, v1
	v_add_f32_e32 v2, v2, v2
	v_add_f32_e32 v3, v3, v3
	v_add_f32_e32 v4, v4, v4
	v_add_f32_e32 v5, v5, v5
	v_add_f32_e32 v6, v6, v6
	v_add_f32_e32 v7, v7, v7
	v_add_f32_e32 v8, v8, v8
	v_add_f32_e32 v9, v9, v9
	v_add_f32_e32 v10, v10, v10
	v_add_f32_e32 v11, v11, v11
	v_add_f32_e32 v12, v12, v12
	v_add_f32_e32 v13, v13, v13
	v_add_f32_e32 v14, v14, v14
	v_add_f32_e32 v15, v15, v15
	v_add_f32_e32 v31, v31, v31
	v_med3_f32 v0, v0, s1, v52
	v_med3_f32 v1, v1, s1, v52
	v_med3_f32 v2, v2, s1, v52
	v_med3_f32 v3, v3, s1, v52
	v_med3_f32 v4, v4, s1, v52
	v_med3_f32 v5, v5, s1, v52
	v_med3_f32 v6, v6, s1, v52
	v_med3_f32 v7, v7, s1, v52
	v_med3_f32 v8, v8, s1, v52
	v_med3_f32 v9, v9, s1, v52
	v_med3_f32 v10, v10, s1, v52
	v_med3_f32 v11, v11, s1, v52
	v_med3_f32 v12, v12, s1, v52
	v_med3_f32 v13, v13, s1, v52
	v_med3_f32 v14, v14, s1, v52
	v_med3_f32 v15, v15, s1, v52
	v_med3_f32 v31, v31, s1, v52
	v_cvt_scalef32_2xpk16_fp6_f32 v[0:5], v[0:15], v[16:31], 1.0
	global_load_dwordx4 v[40:43], v[70:71], off offset:16
	global_load_dwordx4 v[60:63], v[70:71], off offset:2048
	ds_write_b128 v64, v[0:3] offset:5632
	ds_write_b64 v47, v[4:5] offset:6656
	v_lshlrev_b32_e32 v0, 10, v65
	s_movk_i32 s4, 0x100
	v_or3_b32 v59, v46, v0, s4
	v_lshlrev_b32_e32 v0, 10, v72
	global_load_dwordx4 v[28:31], v[70:71], off offset:2064
	v_or3_b32 v58, v55, v0, s4
	s_or_b32 s4, s22, 3
	s_ashr_i32 s5, s4, 31
	s_lshl_b64 s[6:7], s[4:5], 9
	s_add_u32 s6, s2, s6
	s_addc_u32 s7, s3, s7
	v_lshl_add_u64 v[6:7], s[6:7], 0, v[50:51]
	global_load_dword v65, v[6:7], off
	global_load_dword v74, v[6:7], off offset:256
	v_and_b32_e32 v1, 0xffff0000, v66
	v_and_b32_e32 v2, 0xffff0000, v67
	v_and_b32_e32 v3, 0xffff0000, v68
	s_lshl_b64 s[4:5], s[4:5], 12
	v_add_f32_e32 v1, v1, v1
	v_add_f32_e32 v2, v2, v2
	v_add_f32_e32 v3, v3, v3
	v_lshl_add_u64 v[14:15], v[48:49], 0, s[4:5]
	v_lshlrev_b32_e32 v0, 16, v66
	v_med3_f32 v16, v1, s1, v52
	v_lshlrev_b32_e32 v1, 16, v67
	v_med3_f32 v17, v2, s1, v52
	v_lshlrev_b32_e32 v2, 16, v68
	v_med3_f32 v18, v3, s1, v52
	v_lshlrev_b32_e32 v3, 16, v69
	v_and_b32_e32 v4, 0xffff0000, v69
	global_load_dwordx4 v[32:35], v[14:15], off offset:16
	global_load_dwordx4 v[66:69], v[14:15], off
	global_load_dwordx4 v[36:39], v[14:15], off offset:2064
	global_load_dwordx4 v[70:73], v[14:15], off offset:2048
	v_add_f32_e32 v4, v4, v4
	v_med3_f32 v19, v4, s1, v52
	v_add_f32_e32 v0, v0, v0
	v_add_f32_e32 v1, v1, v1
	v_add_f32_e32 v2, v2, v2
	v_add_f32_e32 v3, v3, v3
	v_med3_f32 v0, v0, s1, v52
	v_med3_f32 v1, v1, s1, v52
	v_med3_f32 v2, v2, s1, v52
	v_med3_f32 v3, v3, s1, v52
	s_movk_i32 s4, 0x180
	s_waitcnt vmcnt(0)
	v_and_b32_e32 v5, 0xffff0000, v40
	v_and_b32_e32 v6, 0xffff0000, v41
	v_and_b32_e32 v7, 0xffff0000, v42
	v_and_b32_e32 v8, 0xffff0000, v43
	v_and_b32_e32 v9, 0xffff0000, v60
	v_and_b32_e32 v10, 0xffff0000, v61
	v_and_b32_e32 v11, 0xffff0000, v62
	v_and_b32_e32 v12, 0xffff0000, v63
	v_and_b32_e32 v13, 0xffff0000, v28
	v_and_b32_e32 v15, 0xffff0000, v30
	v_add_f32_e32 v5, v5, v5
	v_add_f32_e32 v6, v6, v6
	v_add_f32_e32 v7, v7, v7
	v_add_f32_e32 v8, v8, v8
	v_add_f32_e32 v9, v9, v9
	v_add_f32_e32 v10, v10, v10
	v_add_f32_e32 v11, v11, v11
	v_add_f32_e32 v12, v12, v12
	v_add_f32_e32 v13, v13, v13
	v_add_f32_e32 v15, v15, v15
	v_lshlrev_b32_e32 v4, 16, v40
	v_med3_f32 v20, v5, s1, v52
	v_lshlrev_b32_e32 v5, 16, v41
	v_med3_f32 v21, v6, s1, v52
	v_lshlrev_b32_e32 v6, 16, v42
	v_med3_f32 v22, v7, s1, v52
	v_lshlrev_b32_e32 v7, 16, v43
	v_med3_f32 v23, v8, s1, v52
	v_lshlrev_b32_e32 v8, 16, v60
	v_med3_f32 v24, v9, s1, v52
	v_lshlrev_b32_e32 v9, 16, v61
	v_med3_f32 v25, v10, s1, v52
	v_lshlrev_b32_e32 v10, 16, v62
	v_med3_f32 v26, v11, s1, v52
	v_lshlrev_b32_e32 v11, 16, v63
	v_med3_f32 v27, v12, s1, v52
	v_lshlrev_b32_e32 v12, 16, v28
	v_med3_f32 v28, v13, s1, v52
	v_lshlrev_b32_e32 v13, 16, v29
	v_and_b32_e32 v29, 0xffff0000, v29
	v_lshlrev_b32_e32 v14, 16, v30
	v_med3_f32 v30, v15, s1, v52
	v_lshlrev_b32_e32 v15, 16, v31
	v_and_b32_e32 v31, 0xffff0000, v31
	v_add_f32_e32 v4, v4, v4
	v_add_f32_e32 v5, v5, v5
	v_add_f32_e32 v6, v6, v6
	v_add_f32_e32 v7, v7, v7
	v_add_f32_e32 v8, v8, v8
	v_add_f32_e32 v9, v9, v9
	v_add_f32_e32 v10, v10, v10
	v_add_f32_e32 v11, v11, v11
	v_add_f32_e32 v12, v12, v12
	v_add_f32_e32 v13, v13, v13
	v_add_f32_e32 v29, v29, v29
	v_add_f32_e32 v14, v14, v14
	v_add_f32_e32 v15, v15, v15
	v_add_f32_e32 v31, v31, v31
	v_med3_f32 v4, v4, s1, v52
	v_med3_f32 v5, v5, s1, v52
	v_med3_f32 v6, v6, s1, v52
	v_med3_f32 v7, v7, s1, v52
	v_med3_f32 v8, v8, s1, v52
	v_med3_f32 v9, v9, s1, v52
	v_med3_f32 v10, v10, s1, v52
	v_med3_f32 v11, v11, s1, v52
	v_med3_f32 v12, v12, s1, v52
	v_med3_f32 v13, v13, s1, v52
	v_med3_f32 v29, v29, s1, v52
	v_med3_f32 v14, v14, s1, v52
	v_med3_f32 v15, v15, s1, v52
	v_med3_f32 v31, v31, s1, v52
	v_cvt_scalef32_2xpk16_fp6_f32 v[0:5], v[0:15], v[16:31], 1.0
	ds_write_b128 v64, v[0:3] offset:7168
	ds_write_b64 v47, v[4:5] offset:8192
	v_lshlrev_b32_e32 v0, 10, v65
	v_or3_b32 v61, v46, v0, s4
	v_lshlrev_b32_e32 v0, 10, v74
	v_or3_b32 v60, v55, v0, s4
	s_or_b32 s4, s22, 4
	s_ashr_i32 s5, s4, 31
	s_lshl_b64 s[6:7], s[4:5], 9
	s_add_u32 s6, s2, s6
	s_addc_u32 s7, s3, s7
	v_lshl_add_u64 v[6:7], s[6:7], 0, v[50:51]
	global_load_dword v62, v[6:7], off
	global_load_dword v65, v[6:7], off offset:256
	v_and_b32_e32 v1, 0xffff0000, v66
	v_and_b32_e32 v2, 0xffff0000, v67
	v_and_b32_e32 v3, 0xffff0000, v68
	s_lshl_b64 s[4:5], s[4:5], 12
	v_add_f32_e32 v1, v1, v1
	v_add_f32_e32 v2, v2, v2
	v_add_f32_e32 v3, v3, v3
	v_lshl_add_u64 v[74:75], v[48:49], 0, s[4:5]
	v_lshlrev_b32_e32 v0, 16, v66
	v_med3_f32 v16, v1, s1, v52
	v_lshlrev_b32_e32 v1, 16, v67
	v_med3_f32 v17, v2, s1, v52
	v_lshlrev_b32_e32 v2, 16, v68
	v_med3_f32 v18, v3, s1, v52
	v_lshlrev_b32_e32 v3, 16, v69
	v_and_b32_e32 v4, 0xffff0000, v69
	global_load_dwordx4 v[66:69], v[74:75], off
	v_and_b32_e32 v8, 0xffff0000, v35
	v_and_b32_e32 v9, 0xffff0000, v70
	v_and_b32_e32 v10, 0xffff0000, v71
	v_and_b32_e32 v11, 0xffff0000, v72
	v_add_f32_e32 v8, v8, v8
	v_add_f32_e32 v9, v9, v9
	v_add_f32_e32 v10, v10, v10
	v_add_f32_e32 v11, v11, v11
	v_med3_f32 v23, v8, s1, v52
	v_lshlrev_b32_e32 v8, 16, v70
	global_load_dwordx4 v[40:43], v[74:75], off offset:16
	v_med3_f32 v24, v9, s1, v52
	v_lshlrev_b32_e32 v9, 16, v71
	v_med3_f32 v25, v10, s1, v52
	v_lshlrev_b32_e32 v10, 16, v72
	v_med3_f32 v26, v11, s1, v52
	v_lshlrev_b32_e32 v11, 16, v73
	v_and_b32_e32 v12, 0xffff0000, v73
	global_load_dwordx4 v[70:73], v[74:75], off offset:2048
	v_and_b32_e32 v5, 0xffff0000, v32
	v_and_b32_e32 v6, 0xffff0000, v33
	v_and_b32_e32 v7, 0xffff0000, v34
	v_and_b32_e32 v13, 0xffff0000, v36
	v_and_b32_e32 v14, 0xffff0000, v37
	v_and_b32_e32 v15, 0xffff0000, v38
	v_add_f32_e32 v4, v4, v4
	v_add_f32_e32 v5, v5, v5
	v_add_f32_e32 v6, v6, v6
	v_add_f32_e32 v7, v7, v7
	v_add_f32_e32 v12, v12, v12
	v_add_f32_e32 v13, v13, v13
	v_add_f32_e32 v14, v14, v14
	v_add_f32_e32 v15, v15, v15
	v_med3_f32 v19, v4, s1, v52
	v_lshlrev_b32_e32 v4, 16, v32
	v_med3_f32 v20, v5, s1, v52
	v_lshlrev_b32_e32 v5, 16, v33
	v_med3_f32 v21, v6, s1, v52
	v_lshlrev_b32_e32 v6, 16, v34
	v_med3_f32 v22, v7, s1, v52
	v_lshlrev_b32_e32 v7, 16, v35
	v_med3_f32 v27, v12, s1, v52
	v_lshlrev_b32_e32 v12, 16, v36
	v_med3_f32 v28, v13, s1, v52
	v_lshlrev_b32_e32 v13, 16, v37
	v_med3_f32 v29, v14, s1, v52
	v_lshlrev_b32_e32 v14, 16, v38
	v_med3_f32 v30, v15, s1, v52
	v_lshlrev_b32_e32 v15, 16, v39
	v_and_b32_e32 v31, 0xffff0000, v39
	v_add_f32_e32 v0, v0, v0
	v_add_f32_e32 v1, v1, v1
	v_add_f32_e32 v2, v2, v2
	v_add_f32_e32 v3, v3, v3
	v_add_f32_e32 v4, v4, v4
	v_add_f32_e32 v5, v5, v5
	v_add_f32_e32 v6, v6, v6
	v_add_f32_e32 v7, v7, v7
	v_add_f32_e32 v8, v8, v8
	v_add_f32_e32 v9, v9, v9
	v_add_f32_e32 v10, v10, v10
	v_add_f32_e32 v11, v11, v11
	v_add_f32_e32 v12, v12, v12
	v_add_f32_e32 v13, v13, v13
	v_add_f32_e32 v14, v14, v14
	v_add_f32_e32 v15, v15, v15
	v_add_f32_e32 v31, v31, v31
	v_med3_f32 v0, v0, s1, v52
	v_med3_f32 v1, v1, s1, v52
	v_med3_f32 v2, v2, s1, v52
	v_med3_f32 v3, v3, s1, v52
	v_med3_f32 v4, v4, s1, v52
	v_med3_f32 v5, v5, s1, v52
	v_med3_f32 v6, v6, s1, v52
	v_med3_f32 v7, v7, s1, v52
	v_med3_f32 v8, v8, s1, v52
	v_med3_f32 v9, v9, s1, v52
	v_med3_f32 v10, v10, s1, v52
	v_med3_f32 v11, v11, s1, v52
	v_med3_f32 v12, v12, s1, v52
	v_med3_f32 v13, v13, s1, v52
	v_med3_f32 v14, v14, s1, v52
	v_med3_f32 v15, v15, s1, v52
	v_med3_f32 v31, v31, s1, v52
	v_cvt_scalef32_2xpk16_fp6_f32 v[0:5], v[0:15], v[16:31], 1.0
	ds_write_b128 v64, v[0:3] offset:8704
	ds_write_b64 v47, v[4:5] offset:9728
	s_waitcnt vmcnt(0)
	v_lshlrev_b32_e32 v0, 10, v62
	s_movk_i32 s4, 0x200
	v_or3_b32 v63, v46, v0, s4
	v_lshlrev_b32_e32 v0, 10, v65
	global_load_dwordx4 v[28:31], v[74:75], off offset:2064
	v_or3_b32 v62, v55, v0, s4
	s_or_b32 s4, s22, 5
	s_ashr_i32 s5, s4, 31
	s_lshl_b64 s[6:7], s[4:5], 9
	s_add_u32 s6, s2, s6
	s_addc_u32 s7, s3, s7
	v_lshl_add_u64 v[6:7], s[6:7], 0, v[50:51]
	global_load_dword v65, v[6:7], off
	global_load_dword v74, v[6:7], off offset:256
	v_and_b32_e32 v1, 0xffff0000, v66
	v_and_b32_e32 v2, 0xffff0000, v67
	v_and_b32_e32 v3, 0xffff0000, v68
	s_lshl_b64 s[4:5], s[4:5], 12
	v_add_f32_e32 v1, v1, v1
	v_add_f32_e32 v2, v2, v2
	v_add_f32_e32 v3, v3, v3
	v_lshl_add_u64 v[14:15], v[48:49], 0, s[4:5]
	v_lshlrev_b32_e32 v0, 16, v66
	v_med3_f32 v16, v1, s1, v52
	v_lshlrev_b32_e32 v1, 16, v67
	v_med3_f32 v17, v2, s1, v52
	v_lshlrev_b32_e32 v2, 16, v68
	v_med3_f32 v18, v3, s1, v52
	v_lshlrev_b32_e32 v3, 16, v69
	v_and_b32_e32 v4, 0xffff0000, v69
	global_load_dwordx4 v[32:35], v[14:15], off offset:16
	global_load_dwordx4 v[66:69], v[14:15], off
	v_and_b32_e32 v8, 0xffff0000, v43
	v_and_b32_e32 v9, 0xffff0000, v70
	v_and_b32_e32 v10, 0xffff0000, v71
	v_and_b32_e32 v11, 0xffff0000, v72
	v_add_f32_e32 v8, v8, v8
	v_add_f32_e32 v9, v9, v9
	v_add_f32_e32 v10, v10, v10
	v_add_f32_e32 v11, v11, v11
	v_med3_f32 v23, v8, s1, v52
	v_lshlrev_b32_e32 v8, 16, v70
	v_med3_f32 v24, v9, s1, v52
	v_lshlrev_b32_e32 v9, 16, v71
	v_med3_f32 v25, v10, s1, v52
	v_lshlrev_b32_e32 v10, 16, v72
	v_med3_f32 v26, v11, s1, v52
	v_lshlrev_b32_e32 v11, 16, v73
	v_and_b32_e32 v12, 0xffff0000, v73
	global_load_dwordx4 v[36:39], v[14:15], off offset:2064
	global_load_dwordx4 v[70:73], v[14:15], off offset:2048
	v_and_b32_e32 v5, 0xffff0000, v40
	v_and_b32_e32 v6, 0xffff0000, v41
	v_and_b32_e32 v7, 0xffff0000, v42
	v_add_f32_e32 v4, v4, v4
	v_add_f32_e32 v5, v5, v5
	v_add_f32_e32 v6, v6, v6
	v_add_f32_e32 v7, v7, v7
	v_add_f32_e32 v12, v12, v12
	v_med3_f32 v19, v4, s1, v52
	v_lshlrev_b32_e32 v4, 16, v40
	v_med3_f32 v20, v5, s1, v52
	v_lshlrev_b32_e32 v5, 16, v41
	v_med3_f32 v21, v6, s1, v52
	v_lshlrev_b32_e32 v6, 16, v42
	v_med3_f32 v22, v7, s1, v52
	v_lshlrev_b32_e32 v7, 16, v43
	v_med3_f32 v27, v12, s1, v52
	v_add_f32_e32 v0, v0, v0
	v_add_f32_e32 v1, v1, v1
	v_add_f32_e32 v2, v2, v2
	v_add_f32_e32 v3, v3, v3
	v_add_f32_e32 v4, v4, v4
	v_add_f32_e32 v5, v5, v5
	v_add_f32_e32 v6, v6, v6
	v_add_f32_e32 v7, v7, v7
	v_add_f32_e32 v8, v8, v8
	v_add_f32_e32 v9, v9, v9
	v_add_f32_e32 v10, v10, v10
	v_add_f32_e32 v11, v11, v11
	v_med3_f32 v0, v0, s1, v52
	v_med3_f32 v1, v1, s1, v52
	v_med3_f32 v2, v2, s1, v52
	v_med3_f32 v3, v3, s1, v52
	v_med3_f32 v4, v4, s1, v52
	v_med3_f32 v5, v5, s1, v52
	v_med3_f32 v6, v6, s1, v52
	s_waitcnt vmcnt(0)
	v_and_b32_e32 v13, 0xffff0000, v28
	v_and_b32_e32 v15, 0xffff0000, v30
	v_add_f32_e32 v13, v13, v13
	v_add_f32_e32 v15, v15, v15
	v_lshlrev_b32_e32 v12, 16, v28
	v_med3_f32 v28, v13, s1, v52
	v_lshlrev_b32_e32 v13, 16, v29
	v_and_b32_e32 v29, 0xffff0000, v29
	v_lshlrev_b32_e32 v14, 16, v30
	v_med3_f32 v30, v15, s1, v52
	v_lshlrev_b32_e32 v15, 16, v31
	v_and_b32_e32 v31, 0xffff0000, v31
	v_add_f32_e32 v12, v12, v12
	v_add_f32_e32 v13, v13, v13
	v_add_f32_e32 v29, v29, v29
	v_add_f32_e32 v14, v14, v14
	v_add_f32_e32 v15, v15, v15
	v_add_f32_e32 v31, v31, v31
	v_med3_f32 v7, v7, s1, v52
	v_med3_f32 v8, v8, s1, v52
	v_med3_f32 v9, v9, s1, v52
	v_med3_f32 v10, v10, s1, v52
	v_med3_f32 v11, v11, s1, v52
	v_med3_f32 v12, v12, s1, v52
	v_med3_f32 v13, v13, s1, v52
	v_med3_f32 v29, v29, s1, v52
	v_med3_f32 v14, v14, s1, v52
	v_med3_f32 v15, v15, s1, v52
	v_med3_f32 v31, v31, s1, v52
	v_cvt_scalef32_2xpk16_fp6_f32 v[0:5], v[0:15], v[16:31], 1.0
	ds_write_b128 v64, v[0:3] offset:10240
	ds_write_b64 v47, v[4:5] offset:11264
	v_lshlrev_b32_e32 v0, 10, v65
	s_movk_i32 s4, 0x280
	v_or3_b32 v41, v46, v0, s4
	v_lshlrev_b32_e32 v0, 10, v74
	v_or3_b32 v40, v55, v0, s4
	s_or_b32 s4, s22, 6
	s_ashr_i32 s5, s4, 31
	s_lshl_b64 s[6:7], s[4:5], 9
	s_add_u32 s6, s2, s6
	s_addc_u32 s7, s3, s7
	v_lshl_add_u64 v[6:7], s[6:7], 0, v[50:51]
	global_load_dword v65, v[6:7], off
	global_load_dword v74, v[6:7], off offset:256
	v_and_b32_e32 v1, 0xffff0000, v66
	v_and_b32_e32 v2, 0xffff0000, v67
	v_and_b32_e32 v3, 0xffff0000, v68
	s_lshl_b64 s[4:5], s[4:5], 12
	v_add_f32_e32 v1, v1, v1
	v_add_f32_e32 v2, v2, v2
	v_add_f32_e32 v3, v3, v3
	v_lshl_add_u64 v[42:43], v[48:49], 0, s[4:5]
	v_lshlrev_b32_e32 v0, 16, v66
	v_med3_f32 v16, v1, s1, v52
	v_lshlrev_b32_e32 v1, 16, v67
	v_med3_f32 v17, v2, s1, v52
	v_lshlrev_b32_e32 v2, 16, v68
	v_med3_f32 v18, v3, s1, v52
	v_lshlrev_b32_e32 v3, 16, v69
	v_and_b32_e32 v4, 0xffff0000, v69
	global_load_dwordx4 v[66:69], v[42:43], off
	v_and_b32_e32 v5, 0xffff0000, v32
	v_and_b32_e32 v6, 0xffff0000, v33
	v_and_b32_e32 v7, 0xffff0000, v34
	v_and_b32_e32 v8, 0xffff0000, v35
	v_and_b32_e32 v9, 0xffff0000, v70
	v_and_b32_e32 v10, 0xffff0000, v71
	v_and_b32_e32 v11, 0xffff0000, v72
	v_add_f32_e32 v4, v4, v4
	v_add_f32_e32 v5, v5, v5
	v_add_f32_e32 v6, v6, v6
	v_add_f32_e32 v7, v7, v7
	v_add_f32_e32 v8, v8, v8
	v_add_f32_e32 v9, v9, v9
	v_add_f32_e32 v10, v10, v10
	v_add_f32_e32 v11, v11, v11
	v_med3_f32 v19, v4, s1, v52
	v_lshlrev_b32_e32 v4, 16, v32
	v_med3_f32 v20, v5, s1, v52
	v_lshlrev_b32_e32 v5, 16, v33
	v_med3_f32 v21, v6, s1, v52
	v_lshlrev_b32_e32 v6, 16, v34
	v_med3_f32 v22, v7, s1, v52
	v_lshlrev_b32_e32 v7, 16, v35
	v_med3_f32 v23, v8, s1, v52
	v_lshlrev_b32_e32 v8, 16, v70
	global_load_dwordx4 v[32:35], v[42:43], off offset:16
	v_med3_f32 v24, v9, s1, v52
	v_lshlrev_b32_e32 v9, 16, v71
	v_med3_f32 v25, v10, s1, v52
	v_lshlrev_b32_e32 v10, 16, v72
	v_med3_f32 v26, v11, s1, v52
	v_lshlrev_b32_e32 v11, 16, v73
	v_and_b32_e32 v12, 0xffff0000, v73
	global_load_dwordx4 v[70:73], v[42:43], off offset:2048
	v_and_b32_e32 v13, 0xffff0000, v36
	v_and_b32_e32 v14, 0xffff0000, v37
	v_and_b32_e32 v15, 0xffff0000, v38
	v_add_f32_e32 v12, v12, v12
	v_add_f32_e32 v13, v13, v13
	v_add_f32_e32 v14, v14, v14
	v_add_f32_e32 v15, v15, v15
	v_med3_f32 v27, v12, s1, v52
	v_lshlrev_b32_e32 v12, 16, v36
	v_med3_f32 v28, v13, s1, v52
	v_lshlrev_b32_e32 v13, 16, v37
	v_med3_f32 v29, v14, s1, v52
	v_lshlrev_b32_e32 v14, 16, v38
	v_med3_f32 v30, v15, s1, v52
	v_lshlrev_b32_e32 v15, 16, v39
	v_and_b32_e32 v31, 0xffff0000, v39
	v_add_f32_e32 v0, v0, v0
	v_add_f32_e32 v1, v1, v1
	v_add_f32_e32 v2, v2, v2
	v_add_f32_e32 v3, v3, v3
	v_add_f32_e32 v4, v4, v4
	v_add_f32_e32 v5, v5, v5
	v_add_f32_e32 v6, v6, v6
	v_add_f32_e32 v7, v7, v7
	v_add_f32_e32 v8, v8, v8
	v_add_f32_e32 v9, v9, v9
	v_add_f32_e32 v10, v10, v10
	v_add_f32_e32 v11, v11, v11
	v_add_f32_e32 v12, v12, v12
	v_add_f32_e32 v13, v13, v13
	v_add_f32_e32 v14, v14, v14
	v_add_f32_e32 v15, v15, v15
	v_add_f32_e32 v31, v31, v31
	v_med3_f32 v0, v0, s1, v52
	v_med3_f32 v1, v1, s1, v52
	v_med3_f32 v2, v2, s1, v52
	v_med3_f32 v3, v3, s1, v52
	v_med3_f32 v4, v4, s1, v52
	v_med3_f32 v5, v5, s1, v52
	v_med3_f32 v6, v6, s1, v52
	v_med3_f32 v7, v7, s1, v52
	v_med3_f32 v8, v8, s1, v52
	v_med3_f32 v9, v9, s1, v52
	v_med3_f32 v10, v10, s1, v52
	v_med3_f32 v11, v11, s1, v52
	v_med3_f32 v12, v12, s1, v52
	v_med3_f32 v13, v13, s1, v52
	v_med3_f32 v14, v14, s1, v52
	v_med3_f32 v15, v15, s1, v52
	v_med3_f32 v31, v31, s1, v52
	v_cvt_scalef32_2xpk16_fp6_f32 v[0:5], v[0:15], v[16:31], 1.0
	ds_write_b128 v64, v[0:3] offset:11776
	ds_write_b64 v47, v[4:5] offset:12800
	s_waitcnt vmcnt(0)
	v_lshlrev_b32_e32 v0, 10, v65
	s_movk_i32 s4, 0x300
	v_or3_b32 v37, v46, v0, s4
	v_lshlrev_b32_e32 v0, 10, v74
	v_or3_b32 v36, v55, v0, s4
	s_or_b32 s4, s22, 7
	global_load_dwordx4 v[28:31], v[42:43], off offset:2064
	s_ashr_i32 s5, s4, 31
	s_lshl_b64 s[6:7], s[4:5], 9
	s_add_u32 s2, s2, s6
	s_addc_u32 s3, s3, s7
	v_lshl_add_u64 v[6:7], s[2:3], 0, v[50:51]
	v_and_b32_e32 v1, 0xffff0000, v66
	v_and_b32_e32 v2, 0xffff0000, v67
	v_and_b32_e32 v3, 0xffff0000, v68
	v_and_b32_e32 v4, 0xffff0000, v69
	global_load_dword v38, v[6:7], off
	global_load_dword v39, v[6:7], off offset:256
	s_lshl_b64 s[2:3], s[4:5], 12
	v_add_f32_e32 v1, v1, v1
	v_and_b32_e32 v5, 0xffff0000, v32
	v_and_b32_e32 v6, 0xffff0000, v33
	v_and_b32_e32 v7, 0xffff0000, v34
	v_and_b32_e32 v8, 0xffff0000, v35
	v_add_f32_e32 v2, v2, v2
	v_add_f32_e32 v3, v3, v3
	v_add_f32_e32 v4, v4, v4
	v_lshl_add_u64 v[12:13], v[48:49], 0, s[2:3]
	v_and_b32_e32 v9, 0xffff0000, v70
	v_and_b32_e32 v10, 0xffff0000, v71
	v_and_b32_e32 v11, 0xffff0000, v72
	v_add_f32_e32 v5, v5, v5
	v_add_f32_e32 v6, v6, v6
	v_add_f32_e32 v7, v7, v7
	v_add_f32_e32 v8, v8, v8
	v_add_f32_e32 v9, v9, v9
	v_add_f32_e32 v10, v10, v10
	v_add_f32_e32 v11, v11, v11
	v_lshlrev_b32_e32 v0, 16, v66
	v_med3_f32 v16, v1, s1, v52
	v_lshlrev_b32_e32 v1, 16, v67
	v_med3_f32 v17, v2, s1, v52
	v_lshlrev_b32_e32 v2, 16, v68
	v_med3_f32 v18, v3, s1, v52
	v_lshlrev_b32_e32 v3, 16, v69
	v_med3_f32 v19, v4, s1, v52
	v_lshlrev_b32_e32 v4, 16, v32
	global_load_dwordx4 v[48:51], v[12:13], off offset:16
	global_load_dwordx4 v[66:69], v[12:13], off
	v_med3_f32 v20, v5, s1, v52
	v_lshlrev_b32_e32 v5, 16, v33
	v_med3_f32 v21, v6, s1, v52
	v_lshlrev_b32_e32 v6, 16, v34
	v_med3_f32 v22, v7, s1, v52
	v_lshlrev_b32_e32 v7, 16, v35
	v_med3_f32 v23, v8, s1, v52
	v_lshlrev_b32_e32 v8, 16, v70
	v_med3_f32 v24, v9, s1, v52
	v_lshlrev_b32_e32 v9, 16, v71
	v_med3_f32 v25, v10, s1, v52
	v_lshlrev_b32_e32 v10, 16, v72
	v_med3_f32 v26, v11, s1, v52
	v_lshlrev_b32_e32 v11, 16, v73
	v_and_b32_e32 v14, 0xffff0000, v73
	global_load_dwordx4 v[32:35], v[12:13], off offset:2064
	global_load_dwordx4 v[70:73], v[12:13], off offset:2048
	v_add_f32_e32 v14, v14, v14
	v_med3_f32 v27, v14, s1, v52
	v_add_f32_e32 v0, v0, v0
	v_add_f32_e32 v1, v1, v1
	v_add_f32_e32 v2, v2, v2
	v_add_f32_e32 v3, v3, v3
	v_add_f32_e32 v4, v4, v4
	v_add_f32_e32 v5, v5, v5
	v_add_f32_e32 v6, v6, v6
	v_add_f32_e32 v7, v7, v7
	v_add_f32_e32 v8, v8, v8
	v_add_f32_e32 v9, v9, v9
	v_add_f32_e32 v10, v10, v10
	v_add_f32_e32 v11, v11, v11
	v_med3_f32 v0, v0, s1, v52
	v_med3_f32 v1, v1, s1, v52
	v_med3_f32 v2, v2, s1, v52
	v_med3_f32 v3, v3, s1, v52
	v_med3_f32 v4, v4, s1, v52
	v_med3_f32 v5, v5, s1, v52
	v_med3_f32 v6, v6, s1, v52
	v_med3_f32 v7, v7, s1, v52
	v_med3_f32 v8, v8, s1, v52
	s_waitcnt vmcnt(0)
	v_lshlrev_b32_e32 v14, 16, v28
	v_add_f32_e32 v12, v14, v14
	v_and_b32_e32 v13, 0xffff0000, v28
	v_and_b32_e32 v14, 0xffff0000, v29
	v_and_b32_e32 v15, 0xffff0000, v30
	v_add_f32_e32 v13, v13, v13
	v_add_f32_e32 v14, v14, v14
	v_add_f32_e32 v15, v15, v15
	v_med3_f32 v28, v13, s1, v52
	v_lshlrev_b32_e32 v13, 16, v29
	v_med3_f32 v29, v14, s1, v52
	v_lshlrev_b32_e32 v14, 16, v30
	v_med3_f32 v30, v15, s1, v52
	v_lshlrev_b32_e32 v15, 16, v31
	v_and_b32_e32 v31, 0xffff0000, v31
	v_add_f32_e32 v13, v13, v13
	v_add_f32_e32 v14, v14, v14
	v_add_f32_e32 v15, v15, v15
	v_add_f32_e32 v31, v31, v31
	v_med3_f32 v9, v9, s1, v52
	v_med3_f32 v10, v10, s1, v52
	v_med3_f32 v11, v11, s1, v52
	v_med3_f32 v12, v12, s1, v52
	v_med3_f32 v13, v13, s1, v52
	v_med3_f32 v14, v14, s1, v52
	v_med3_f32 v15, v15, s1, v52
	v_med3_f32 v31, v31, s1, v52
	v_cvt_scalef32_2xpk16_fp6_f32 v[0:5], v[0:15], v[16:31], 1.0
	ds_write_b128 v64, v[0:3] offset:13312
	ds_write_b64 v47, v[4:5] offset:14336
	v_lshlrev_b32_e32 v0, 10, v38
	s_movk_i32 s2, 0x380
	v_or3_b32 v38, v46, v0, s2
	v_lshlrev_b32_e32 v0, 10, v39
	v_or3_b32 v39, v55, v0, s2
	s_and_b32 s13, s0, 0xffff
	v_mov_b32_e32 v55, v91
	v_and_b32_e32 v5, 0xffff0000, v48
	v_and_b32_e32 v1, 0xffff0000, v66
	v_and_b32_e32 v2, 0xffff0000, v67
	v_and_b32_e32 v3, 0xffff0000, v68
	v_and_b32_e32 v4, 0xffff0000, v69
	v_and_b32_e32 v6, 0xffff0000, v49
	v_and_b32_e32 v7, 0xffff0000, v50
	v_and_b32_e32 v8, 0xffff0000, v51
	v_add_f32_e32 v1, v1, v1
	v_add_f32_e32 v2, v2, v2
	v_add_f32_e32 v3, v3, v3
	v_add_f32_e32 v4, v4, v4
	v_add_f32_e32 v5, v5, v5
	v_add_f32_e32 v6, v6, v6
	v_add_f32_e32 v7, v7, v7
	v_add_f32_e32 v8, v8, v8
	v_and_b32_e32 v13, 0xffff0000, v32
	v_and_b32_e32 v9, 0xffff0000, v70
	v_and_b32_e32 v10, 0xffff0000, v71
	v_and_b32_e32 v11, 0xffff0000, v72
	v_and_b32_e32 v12, 0xffff0000, v73
	v_and_b32_e32 v14, 0xffff0000, v33
	v_and_b32_e32 v15, 0xffff0000, v34
	v_add_f32_e32 v9, v9, v9
	v_add_f32_e32 v10, v10, v10
	v_add_f32_e32 v11, v11, v11
	v_add_f32_e32 v12, v12, v12
	v_add_f32_e32 v13, v13, v13
	v_add_f32_e32 v14, v14, v14
	v_add_f32_e32 v15, v15, v15
	v_lshlrev_b32_e32 v0, 16, v66
	v_med3_f32 v16, v1, s1, v52
	v_lshlrev_b32_e32 v1, 16, v67
	v_med3_f32 v17, v2, s1, v52
	v_lshlrev_b32_e32 v2, 16, v68
	v_med3_f32 v18, v3, s1, v52
	v_lshlrev_b32_e32 v3, 16, v69
	v_med3_f32 v19, v4, s1, v52
	v_lshlrev_b32_e32 v4, 16, v48
	v_med3_f32 v20, v5, s1, v52
	v_lshlrev_b32_e32 v5, 16, v49
	v_med3_f32 v21, v6, s1, v52
	v_lshlrev_b32_e32 v6, 16, v50
	v_med3_f32 v22, v7, s1, v52
	v_lshlrev_b32_e32 v7, 16, v51
	v_med3_f32 v23, v8, s1, v52
	v_lshlrev_b32_e32 v8, 16, v70
	v_med3_f32 v24, v9, s1, v52
	v_lshlrev_b32_e32 v9, 16, v71
	v_med3_f32 v25, v10, s1, v52
	v_lshlrev_b32_e32 v10, 16, v72
	v_med3_f32 v26, v11, s1, v52
	v_lshlrev_b32_e32 v11, 16, v73
	v_med3_f32 v27, v12, s1, v52
	v_lshlrev_b32_e32 v12, 16, v32
	v_med3_f32 v28, v13, s1, v52
	v_lshlrev_b32_e32 v13, 16, v33
	v_med3_f32 v29, v14, s1, v52
	v_lshlrev_b32_e32 v14, 16, v34
	v_med3_f32 v30, v15, s1, v52
	v_lshlrev_b32_e32 v15, 16, v35
	v_and_b32_e32 v31, 0xffff0000, v35
	v_add_f32_e32 v0, v0, v0
	v_add_f32_e32 v1, v1, v1
	v_add_f32_e32 v2, v2, v2
	v_add_f32_e32 v3, v3, v3
	v_add_f32_e32 v4, v4, v4
	v_add_f32_e32 v5, v5, v5
	v_add_f32_e32 v6, v6, v6
	v_add_f32_e32 v7, v7, v7
	v_add_f32_e32 v8, v8, v8
	v_add_f32_e32 v9, v9, v9
	v_add_f32_e32 v10, v10, v10
	v_add_f32_e32 v11, v11, v11
	v_add_f32_e32 v12, v12, v12
	v_add_f32_e32 v13, v13, v13
	v_add_f32_e32 v14, v14, v14
	v_add_f32_e32 v15, v15, v15
	v_add_f32_e32 v31, v31, v31
	v_med3_f32 v0, v0, s1, v52
	v_med3_f32 v1, v1, s1, v52
	v_med3_f32 v2, v2, s1, v52
	v_med3_f32 v3, v3, s1, v52
	v_med3_f32 v4, v4, s1, v52
	v_med3_f32 v5, v5, s1, v52
	v_med3_f32 v6, v6, s1, v52
	v_med3_f32 v7, v7, s1, v52
	v_med3_f32 v8, v8, s1, v52
	v_med3_f32 v9, v9, s1, v52
	v_med3_f32 v10, v10, s1, v52
	v_med3_f32 v11, v11, s1, v52
	v_med3_f32 v12, v12, s1, v52
	v_med3_f32 v13, v13, s1, v52
	v_med3_f32 v14, v14, s1, v52
	v_med3_f32 v15, v15, s1, v52
	v_med3_f32 v31, v31, s1, v52
	v_cvt_scalef32_2xpk16_fp6_f32 v[0:5], v[0:15], v[16:31], 1.0
	ds_write_b128 v64, v[0:3] offset:14848
	ds_write_b64 v47, v[4:5] offset:15872
	v_mbcnt_lo_u32_b32 v0, -1, 0
	v_mbcnt_hi_u32_b32 v1, -1, v0
	v_and_b32_e32 v0, 64, v1
	v_xor_b32_e32 v3, 1, v1
	v_add_u32_e32 v2, 64, v0
	v_cmp_lt_i32_e32 vcc, v3, v2
	v_and_b32_e32 v4, 2, v46
	v_and_b32_e32 v5, 1, v46
	v_cndmask_b32_e32 v3, v1, v3, vcc
	v_lshlrev_b32_e32 v79, 2, v3
	s_nop 1
	v_mov_b32_dpp v3, v54 quad_perm:[1,0,3,2] row_mask:0xf bank_mask:0xf
	v_cmp_eq_u32_e32 vcc, 0, v5
	v_cmp_ne_u32_e64 s[0:1], 0, v4
	s_nop 1
	v_mov_b32_dpp v6, v53 quad_perm:[1,0,3,2] row_mask:0xf bank_mask:0xf
	s_xor_b64 s[0:1], vcc, s[0:1]
	s_waitcnt lgkmcnt(0)
	v_min_u32_e32 v5, v54, v3
	v_max_u32_e32 v3, v54, v3
	v_cndmask_b32_e64 v3, v3, v5, s[0:1]
	s_nop 1
	v_mov_b32_dpp v5, v57 quad_perm:[1,0,3,2] row_mask:0xf bank_mask:0xf
	v_min_u32_e32 v7, v53, v6
	v_max_u32_e32 v6, v53, v6
	v_cndmask_b32_e64 v6, v6, v7, s[0:1]
	s_nop 1
	v_mov_b32_dpp v7, v56 quad_perm:[1,0,3,2] row_mask:0xf bank_mask:0xf
	s_waitcnt lgkmcnt(0)
	v_min_u32_e32 v8, v57, v5
	v_max_u32_e32 v5, v57, v5
	v_cndmask_b32_e64 v5, v5, v8, s[0:1]
	s_nop 1
	v_mov_b32_dpp v8, v59 quad_perm:[1,0,3,2] row_mask:0xf bank_mask:0xf
	s_waitcnt lgkmcnt(0)
	v_min_u32_e32 v9, v56, v7
	v_max_u32_e32 v7, v56, v7
	v_cndmask_b32_e64 v7, v7, v9, s[0:1]
	s_nop 1
	v_mov_b32_dpp v9, v58 quad_perm:[1,0,3,2] row_mask:0xf bank_mask:0xf
	s_waitcnt lgkmcnt(0)
	v_min_u32_e32 v10, v59, v8
	v_max_u32_e32 v8, v59, v8
	v_cndmask_b32_e64 v8, v8, v10, s[0:1]
	s_nop 1
	v_mov_b32_dpp v10, v61 quad_perm:[1,0,3,2] row_mask:0xf bank_mask:0xf
	s_waitcnt lgkmcnt(0)
	v_min_u32_e32 v11, v58, v9
	v_max_u32_e32 v9, v58, v9
	v_cndmask_b32_e64 v9, v9, v11, s[0:1]
	s_nop 1
	v_mov_b32_dpp v11, v60 quad_perm:[1,0,3,2] row_mask:0xf bank_mask:0xf
	s_waitcnt lgkmcnt(0)
	v_min_u32_e32 v12, v61, v10
	v_max_u32_e32 v10, v61, v10
	v_cndmask_b32_e64 v10, v10, v12, s[0:1]
	s_nop 1
	v_mov_b32_dpp v12, v63 quad_perm:[1,0,3,2] row_mask:0xf bank_mask:0xf
	s_waitcnt lgkmcnt(0)
	v_min_u32_e32 v13, v60, v11
	v_max_u32_e32 v11, v60, v11
	v_cndmask_b32_e64 v11, v11, v13, s[0:1]
	s_nop 1
	v_mov_b32_dpp v13, v62 quad_perm:[1,0,3,2] row_mask:0xf bank_mask:0xf
	s_waitcnt lgkmcnt(0)
	v_min_u32_e32 v14, v63, v12
	v_max_u32_e32 v12, v63, v12
	v_cndmask_b32_e64 v12, v12, v14, s[0:1]
	s_nop 1
	v_mov_b32_dpp v14, v41 quad_perm:[1,0,3,2] row_mask:0xf bank_mask:0xf
	s_waitcnt lgkmcnt(0)
	v_min_u32_e32 v15, v62, v13
	v_max_u32_e32 v13, v62, v13
	v_cndmask_b32_e64 v13, v13, v15, s[0:1]
	s_nop 1
	v_mov_b32_dpp v15, v40 quad_perm:[1,0,3,2] row_mask:0xf bank_mask:0xf
	s_waitcnt lgkmcnt(0)
	v_min_u32_e32 v16, v41, v14
	v_max_u32_e32 v14, v41, v14
	v_cndmask_b32_e64 v14, v14, v16, s[0:1]
	s_nop 1
	v_mov_b32_dpp v16, v37 quad_perm:[1,0,3,2] row_mask:0xf bank_mask:0xf
	s_waitcnt lgkmcnt(0)
	v_min_u32_e32 v17, v40, v15
	v_max_u32_e32 v15, v40, v15
	v_xor_b32_e32 v21, 2, v1
	v_cndmask_b32_e64 v15, v15, v17, s[0:1]
	s_nop 1
	v_mov_b32_dpp v17, v36 quad_perm:[1,0,3,2] row_mask:0xf bank_mask:0xf
	s_waitcnt lgkmcnt(0)
	v_min_u32_e32 v18, v37, v16
	v_max_u32_e32 v16, v37, v16
	v_cmp_lt_i32_e64 s[2:3], v21, v2
	v_cndmask_b32_e64 v16, v16, v18, s[0:1]
	s_nop 1
	v_mov_b32_dpp v18, v38 quad_perm:[1,0,3,2] row_mask:0xf bank_mask:0xf
	v_cndmask_b32_e64 v21, v1, v21, s[2:3]
	s_nop 1
	v_mov_b32_dpp v20, v39 quad_perm:[1,0,3,2] row_mask:0xf bank_mask:0xf
	v_lshlrev_b32_e32 v80, 2, v21
	s_nop 1
	v_mov_b32_dpp v21, v3 quad_perm:[2,3,0,1] row_mask:0xf bank_mask:0xf
	s_waitcnt lgkmcnt(0)
	v_min_u32_e32 v19, v36, v17
	v_max_u32_e32 v17, v36, v17
	v_cndmask_b32_e64 v17, v17, v19, s[0:1]
	s_waitcnt lgkmcnt(0)
	v_min_u32_e32 v19, v38, v18
	v_max_u32_e32 v18, v38, v18
	v_cndmask_b32_e64 v18, v18, v19, s[0:1]
	s_waitcnt lgkmcnt(0)
	v_min_u32_e32 v19, v39, v20
	v_max_u32_e32 v20, v39, v20
	v_cndmask_b32_e64 v19, v20, v19, s[0:1]
	v_and_b32_e32 v20, 4, v46
	v_cmp_eq_u32_e64 s[0:1], 0, v4
	s_waitcnt lgkmcnt(0)
	v_min_u32_e32 v4, v3, v21
	v_max_u32_e32 v3, v3, v21
	s_nop 1
	v_mov_b32_dpp v21, v6 quad_perm:[2,3,0,1] row_mask:0xf bank_mask:0xf
	v_cmp_ne_u32_e64 s[2:3], 0, v20
	s_xor_b64 s[4:5], s[0:1], s[2:3]
	v_cndmask_b32_e64 v3, v3, v4, s[4:5]
	s_nop 1
	v_mov_b32_dpp v4, v5 quad_perm:[2,3,0,1] row_mask:0xf bank_mask:0xf
	s_waitcnt lgkmcnt(0)
	v_min_u32_e32 v22, v6, v21
	v_max_u32_e32 v6, v6, v21
	s_nop 1
	v_mov_b32_dpp v21, v7 quad_perm:[2,3,0,1] row_mask:0xf bank_mask:0xf
	v_cndmask_b32_e64 v6, v6, v22, s[4:5]
	s_waitcnt lgkmcnt(0)
	v_min_u32_e32 v22, v5, v4
	v_max_u32_e32 v4, v5, v4
	s_nop 1
	v_mov_b32_dpp v5, v8 quad_perm:[2,3,0,1] row_mask:0xf bank_mask:0xf
	v_cndmask_b32_e64 v4, v4, v22, s[4:5]
	s_waitcnt lgkmcnt(0)
	v_min_u32_e32 v22, v7, v21
	v_max_u32_e32 v7, v7, v21
	s_nop 1
	v_mov_b32_dpp v21, v9 quad_perm:[2,3,0,1] row_mask:0xf bank_mask:0xf
	v_cndmask_b32_e64 v7, v7, v22, s[4:5]
	s_waitcnt lgkmcnt(0)
	v_min_u32_e32 v22, v8, v5
	v_max_u32_e32 v5, v8, v5
	s_nop 1
	v_mov_b32_dpp v8, v10 quad_perm:[2,3,0,1] row_mask:0xf bank_mask:0xf
	v_cndmask_b32_e64 v5, v5, v22, s[4:5]
	s_waitcnt lgkmcnt(0)
	v_min_u32_e32 v22, v9, v21
	v_max_u32_e32 v9, v9, v21
	s_nop 1
	v_mov_b32_dpp v21, v11 quad_perm:[2,3,0,1] row_mask:0xf bank_mask:0xf
	v_cndmask_b32_e64 v9, v9, v22, s[4:5]
	s_waitcnt lgkmcnt(0)
	v_min_u32_e32 v22, v10, v8
	v_max_u32_e32 v8, v10, v8
	s_nop 1
	v_mov_b32_dpp v10, v12 quad_perm:[2,3,0,1] row_mask:0xf bank_mask:0xf
	v_cndmask_b32_e64 v8, v8, v22, s[4:5]
	s_waitcnt lgkmcnt(0)
	v_min_u32_e32 v22, v11, v21
	v_max_u32_e32 v11, v11, v21
	s_nop 1
	v_mov_b32_dpp v21, v13 quad_perm:[2,3,0,1] row_mask:0xf bank_mask:0xf
	v_cndmask_b32_e64 v11, v11, v22, s[4:5]
	s_waitcnt lgkmcnt(0)
	v_min_u32_e32 v22, v12, v10
	v_max_u32_e32 v10, v12, v10
	s_nop 1
	v_mov_b32_dpp v12, v14 quad_perm:[2,3,0,1] row_mask:0xf bank_mask:0xf
	v_cndmask_b32_e64 v10, v10, v22, s[4:5]
	s_waitcnt lgkmcnt(0)
	v_min_u32_e32 v22, v13, v21
	v_max_u32_e32 v13, v13, v21
	s_nop 1
	v_mov_b32_dpp v21, v15 quad_perm:[2,3,0,1] row_mask:0xf bank_mask:0xf
	v_cndmask_b32_e64 v13, v13, v22, s[4:5]
	s_waitcnt lgkmcnt(0)
	v_min_u32_e32 v22, v14, v12
	v_max_u32_e32 v12, v14, v12
	s_nop 1
	v_mov_b32_dpp v14, v16 quad_perm:[2,3,0,1] row_mask:0xf bank_mask:0xf
	v_cndmask_b32_e64 v12, v12, v22, s[4:5]
	s_waitcnt lgkmcnt(0)
	v_min_u32_e32 v22, v15, v21
	v_max_u32_e32 v15, v15, v21
	s_nop 1
	v_mov_b32_dpp v21, v17 quad_perm:[2,3,0,1] row_mask:0xf bank_mask:0xf
	v_cndmask_b32_e64 v15, v15, v22, s[4:5]
	s_waitcnt lgkmcnt(0)
	v_min_u32_e32 v22, v16, v14
	v_max_u32_e32 v14, v16, v14
	s_nop 1
	v_mov_b32_dpp v16, v18 quad_perm:[2,3,0,1] row_mask:0xf bank_mask:0xf
	v_cndmask_b32_e64 v14, v14, v22, s[4:5]
	s_waitcnt lgkmcnt(0)
	v_min_u32_e32 v22, v17, v21
	v_max_u32_e32 v17, v17, v21
	s_nop 1
	v_mov_b32_dpp v21, v19 quad_perm:[2,3,0,1] row_mask:0xf bank_mask:0xf
	v_cndmask_b32_e64 v17, v17, v22, s[4:5]
	s_waitcnt lgkmcnt(0)
	v_min_u32_e32 v22, v18, v16
	v_max_u32_e32 v16, v18, v16
	s_nop 1
	v_mov_b32_dpp v18, v3 quad_perm:[1,0,3,2] row_mask:0xf bank_mask:0xf
	v_cndmask_b32_e64 v16, v16, v22, s[4:5]
	s_waitcnt lgkmcnt(0)
	v_min_u32_e32 v22, v19, v21
	v_max_u32_e32 v19, v19, v21
	v_cndmask_b32_e64 v19, v19, v22, s[4:5]
	s_nop 1
	v_mov_b32_dpp v22, v6 quad_perm:[1,0,3,2] row_mask:0xf bank_mask:0xf
	s_waitcnt lgkmcnt(0)
	v_min_u32_e32 v21, v3, v18
	v_max_u32_e32 v3, v3, v18
	s_nop 1
	v_mov_b32_dpp v18, v4 quad_perm:[1,0,3,2] row_mask:0xf bank_mask:0xf
	s_xor_b64 s[2:3], vcc, s[2:3]
	v_cndmask_b32_e64 v3, v3, v21, s[2:3]
	s_waitcnt lgkmcnt(0)
	v_min_u32_e32 v21, v6, v22
	v_max_u32_e32 v6, v6, v22
	v_cndmask_b32_e64 v6, v6, v21, s[2:3]
	s_nop 1
	v_mov_b32_dpp v21, v7 quad_perm:[1,0,3,2] row_mask:0xf bank_mask:0xf
	s_waitcnt lgkmcnt(0)
	v_min_u32_e32 v22, v4, v18
	v_max_u32_e32 v4, v4, v18
	s_nop 1
	v_mov_b32_dpp v18, v5 quad_perm:[1,0,3,2] row_mask:0xf bank_mask:0xf
	v_cndmask_b32_e64 v4, v4, v22, s[2:3]
	s_waitcnt lgkmcnt(0)
	v_min_u32_e32 v22, v7, v21
	v_max_u32_e32 v7, v7, v21
	s_nop 1
	v_mov_b32_dpp v21, v9 quad_perm:[1,0,3,2] row_mask:0xf bank_mask:0xf
	v_cndmask_b32_e64 v7, v7, v22, s[2:3]
	s_waitcnt lgkmcnt(0)
	v_min_u32_e32 v22, v5, v18
	v_max_u32_e32 v5, v5, v18
	s_nop 1
	v_mov_b32_dpp v18, v8 quad_perm:[1,0,3,2] row_mask:0xf bank_mask:0xf
	v_cndmask_b32_e64 v5, v5, v22, s[2:3]
	s_waitcnt lgkmcnt(0)
	v_min_u32_e32 v22, v9, v21
	v_max_u32_e32 v9, v9, v21
	s_nop 1
	v_mov_b32_dpp v21, v11 quad_perm:[1,0,3,2] row_mask:0xf bank_mask:0xf
	v_cndmask_b32_e64 v9, v9, v22, s[2:3]
	s_waitcnt lgkmcnt(0)
	v_min_u32_e32 v22, v8, v18
	v_max_u32_e32 v8, v8, v18
	s_nop 1
	v_mov_b32_dpp v18, v10 quad_perm:[1,0,3,2] row_mask:0xf bank_mask:0xf
	v_cndmask_b32_e64 v8, v8, v22, s[2:3]
	s_waitcnt lgkmcnt(0)
	v_min_u32_e32 v22, v11, v21
	v_max_u32_e32 v11, v11, v21
	s_nop 1
	v_mov_b32_dpp v21, v13 quad_perm:[1,0,3,2] row_mask:0xf bank_mask:0xf
	v_cndmask_b32_e64 v11, v11, v22, s[2:3]
	s_waitcnt lgkmcnt(0)
	v_min_u32_e32 v22, v10, v18
	v_max_u32_e32 v10, v10, v18
	s_nop 1
	v_mov_b32_dpp v18, v12 quad_perm:[1,0,3,2] row_mask:0xf bank_mask:0xf
	v_cndmask_b32_e64 v10, v10, v22, s[2:3]
	s_waitcnt lgkmcnt(0)
	v_min_u32_e32 v22, v13, v21
	v_max_u32_e32 v13, v13, v21
	s_nop 1
	v_mov_b32_dpp v21, v15 quad_perm:[1,0,3,2] row_mask:0xf bank_mask:0xf
	v_cndmask_b32_e64 v13, v13, v22, s[2:3]
	s_waitcnt lgkmcnt(0)
	v_min_u32_e32 v22, v12, v18
	v_max_u32_e32 v12, v12, v18
	s_nop 1
	v_mov_b32_dpp v18, v14 quad_perm:[1,0,3,2] row_mask:0xf bank_mask:0xf
	v_cndmask_b32_e64 v12, v12, v22, s[2:3]
	s_waitcnt lgkmcnt(0)
	v_min_u32_e32 v22, v15, v21
	v_max_u32_e32 v15, v15, v21
	s_nop 1
	v_mov_b32_dpp v21, v17 quad_perm:[1,0,3,2] row_mask:0xf bank_mask:0xf
	v_cndmask_b32_e64 v15, v15, v22, s[2:3]
	s_waitcnt lgkmcnt(0)
	v_min_u32_e32 v22, v14, v18
	v_max_u32_e32 v14, v14, v18
	s_nop 1
	v_mov_b32_dpp v18, v16 quad_perm:[1,0,3,2] row_mask:0xf bank_mask:0xf
	v_cndmask_b32_e64 v14, v14, v22, s[2:3]
	s_waitcnt lgkmcnt(0)
	v_min_u32_e32 v22, v17, v21
	v_max_u32_e32 v17, v17, v21
	v_cndmask_b32_e64 v17, v17, v22, s[2:3]
	s_waitcnt lgkmcnt(0)
	v_min_u32_e32 v22, v16, v18
	v_max_u32_e32 v16, v16, v18
	v_cndmask_b32_e64 v16, v16, v22, s[2:3]
	v_xor_b32_e32 v22, 4, v1
	s_nop 1
	v_mov_b32_dpp v21, v19 quad_perm:[1,0,3,2] row_mask:0xf bank_mask:0xf
	v_cmp_lt_i32_e64 s[4:5], v22, v2
	v_and_or_b32 v0, v46, 63, v0
	v_lshlrev_b32_e32 v0, 2, v0
	v_cndmask_b32_e64 v22, v1, v22, s[4:5]
	v_lshlrev_b32_e32 v81, 2, v22
	s_nop 1
	v_mov_b32_dpp v22, v3 row_shl:4 row_mask:0xf bank_mask:0x5
	v_mov_b32_dpp v22, v3 row_shr:4 row_mask:0xf bank_mask:0xa
	s_waitcnt lgkmcnt(0)
	v_min_u32_e32 v18, v19, v21
	v_max_u32_e32 v19, v19, v21
	s_nop 1
	v_mov_b32_dpp v21, v6 row_shl:4 row_mask:0xf bank_mask:0x5
	v_mov_b32_dpp v21, v6 row_shr:4 row_mask:0xf bank_mask:0xa
	v_cndmask_b32_e64 v18, v19, v18, s[2:3]
	v_and_b32_e32 v19, 8, v46
	v_cmp_eq_u32_e64 s[2:3], 0, v20
	v_cmp_ne_u32_e64 s[4:5], 0, v19
	s_waitcnt lgkmcnt(0)
	v_min_u32_e32 v20, v3, v22
	v_max_u32_e32 v3, v3, v22
	s_xor_b64 s[6:7], s[2:3], s[4:5]
	v_cndmask_b32_e64 v3, v3, v20, s[6:7]
	s_nop 1
	v_mov_b32_dpp v20, v4 row_shl:4 row_mask:0xf bank_mask:0x5
	v_mov_b32_dpp v20, v4 row_shr:4 row_mask:0xf bank_mask:0xa
	s_waitcnt lgkmcnt(0)
	v_min_u32_e32 v22, v6, v21
	v_max_u32_e32 v6, v6, v21
	s_nop 1
	v_mov_b32_dpp v21, v7 row_shl:4 row_mask:0xf bank_mask:0x5
	v_mov_b32_dpp v21, v7 row_shr:4 row_mask:0xf bank_mask:0xa
	v_cndmask_b32_e64 v6, v6, v22, s[6:7]
	s_waitcnt lgkmcnt(0)
	v_min_u32_e32 v22, v4, v20
	v_max_u32_e32 v4, v4, v20
	s_nop 1
	v_mov_b32_dpp v20, v5 row_shl:4 row_mask:0xf bank_mask:0x5
	v_mov_b32_dpp v20, v5 row_shr:4 row_mask:0xf bank_mask:0xa
	v_cndmask_b32_e64 v4, v4, v22, s[6:7]
	s_waitcnt lgkmcnt(0)
	v_min_u32_e32 v22, v7, v21
	v_max_u32_e32 v7, v7, v21
	s_nop 1
	v_mov_b32_dpp v21, v9 row_shl:4 row_mask:0xf bank_mask:0x5
	v_mov_b32_dpp v21, v9 row_shr:4 row_mask:0xf bank_mask:0xa
	v_cndmask_b32_e64 v7, v7, v22, s[6:7]
	s_waitcnt lgkmcnt(0)
	v_min_u32_e32 v22, v5, v20
	v_max_u32_e32 v5, v5, v20
	s_nop 1
	v_mov_b32_dpp v20, v8 row_shl:4 row_mask:0xf bank_mask:0x5
	v_mov_b32_dpp v20, v8 row_shr:4 row_mask:0xf bank_mask:0xa
	v_cndmask_b32_e64 v5, v5, v22, s[6:7]
	s_waitcnt lgkmcnt(0)
	v_min_u32_e32 v22, v9, v21
	v_max_u32_e32 v9, v9, v21
	s_nop 1
	v_mov_b32_dpp v21, v11 row_shl:4 row_mask:0xf bank_mask:0x5
	v_mov_b32_dpp v21, v11 row_shr:4 row_mask:0xf bank_mask:0xa
	v_cndmask_b32_e64 v9, v9, v22, s[6:7]
	s_waitcnt lgkmcnt(0)
	v_min_u32_e32 v22, v8, v20
	v_max_u32_e32 v8, v8, v20
	s_nop 1
	v_mov_b32_dpp v20, v10 row_shl:4 row_mask:0xf bank_mask:0x5
	v_mov_b32_dpp v20, v10 row_shr:4 row_mask:0xf bank_mask:0xa
	v_cndmask_b32_e64 v8, v8, v22, s[6:7]
	s_waitcnt lgkmcnt(0)
	v_min_u32_e32 v22, v11, v21
	v_max_u32_e32 v11, v11, v21
	s_nop 1
	v_mov_b32_dpp v21, v13 row_shl:4 row_mask:0xf bank_mask:0x5
	v_mov_b32_dpp v21, v13 row_shr:4 row_mask:0xf bank_mask:0xa
	v_cndmask_b32_e64 v11, v11, v22, s[6:7]
	s_waitcnt lgkmcnt(0)
	v_min_u32_e32 v22, v10, v20
	v_max_u32_e32 v10, v10, v20
	s_nop 1
	v_mov_b32_dpp v20, v12 row_shl:4 row_mask:0xf bank_mask:0x5
	v_mov_b32_dpp v20, v12 row_shr:4 row_mask:0xf bank_mask:0xa
	v_cndmask_b32_e64 v10, v10, v22, s[6:7]
	s_waitcnt lgkmcnt(0)
	v_min_u32_e32 v22, v13, v21
	v_max_u32_e32 v13, v13, v21
	s_nop 1
	v_mov_b32_dpp v21, v15 row_shl:4 row_mask:0xf bank_mask:0x5
	v_mov_b32_dpp v21, v15 row_shr:4 row_mask:0xf bank_mask:0xa
	v_cndmask_b32_e64 v13, v13, v22, s[6:7]
	s_waitcnt lgkmcnt(0)
	v_min_u32_e32 v22, v12, v20
	v_max_u32_e32 v12, v12, v20
	s_nop 1
	v_mov_b32_dpp v20, v14 row_shl:4 row_mask:0xf bank_mask:0x5
	v_mov_b32_dpp v20, v14 row_shr:4 row_mask:0xf bank_mask:0xa
	v_cndmask_b32_e64 v12, v12, v22, s[6:7]
	s_waitcnt lgkmcnt(0)
	v_min_u32_e32 v22, v15, v21
	v_max_u32_e32 v15, v15, v21
	s_nop 1
	v_mov_b32_dpp v21, v17 row_shl:4 row_mask:0xf bank_mask:0x5
	v_mov_b32_dpp v21, v17 row_shr:4 row_mask:0xf bank_mask:0xa
	v_cndmask_b32_e64 v15, v15, v22, s[6:7]
	s_waitcnt lgkmcnt(0)
	v_min_u32_e32 v22, v14, v20
	v_max_u32_e32 v14, v14, v20
	s_nop 1
	v_mov_b32_dpp v20, v16 row_shl:4 row_mask:0xf bank_mask:0x5
	v_mov_b32_dpp v20, v16 row_shr:4 row_mask:0xf bank_mask:0xa
	v_cndmask_b32_e64 v14, v14, v22, s[6:7]
	s_waitcnt lgkmcnt(0)
	v_min_u32_e32 v22, v17, v21
	v_max_u32_e32 v17, v17, v21
	s_nop 1
	v_mov_b32_dpp v21, v18 row_shl:4 row_mask:0xf bank_mask:0x5
	v_mov_b32_dpp v21, v18 row_shr:4 row_mask:0xf bank_mask:0xa
	v_cndmask_b32_e64 v17, v17, v22, s[6:7]
	s_waitcnt lgkmcnt(0)
	v_min_u32_e32 v22, v16, v20
	v_max_u32_e32 v16, v16, v20
	s_nop 1
	v_mov_b32_dpp v20, v3 quad_perm:[2,3,0,1] row_mask:0xf bank_mask:0xf
	v_cndmask_b32_e64 v16, v16, v22, s[6:7]
	s_waitcnt lgkmcnt(0)
	v_min_u32_e32 v22, v18, v21
	v_max_u32_e32 v18, v18, v21
	v_cndmask_b32_e64 v18, v18, v22, s[6:7]
	s_nop 1
	v_mov_b32_dpp v22, v6 quad_perm:[2,3,0,1] row_mask:0xf bank_mask:0xf
	s_waitcnt lgkmcnt(0)
	v_min_u32_e32 v21, v3, v20
	v_max_u32_e32 v3, v3, v20
	s_xor_b64 s[6:7], s[0:1], s[4:5]
	s_nop 1
	v_mov_b32_dpp v20, v4 quad_perm:[2,3,0,1] row_mask:0xf bank_mask:0xf
	v_cndmask_b32_e64 v3, v3, v21, s[6:7]
	s_waitcnt lgkmcnt(0)
	v_min_u32_e32 v21, v6, v22
	v_max_u32_e32 v6, v6, v22
	v_cndmask_b32_e64 v6, v6, v21, s[6:7]
	s_nop 1
	v_mov_b32_dpp v21, v7 quad_perm:[2,3,0,1] row_mask:0xf bank_mask:0xf
	s_waitcnt lgkmcnt(0)
	v_min_u32_e32 v22, v4, v20
	v_max_u32_e32 v4, v4, v20
	s_nop 1
	v_mov_b32_dpp v20, v5 quad_perm:[2,3,0,1] row_mask:0xf bank_mask:0xf
	v_cndmask_b32_e64 v4, v4, v22, s[6:7]
	s_waitcnt lgkmcnt(0)
	v_min_u32_e32 v22, v7, v21
	v_max_u32_e32 v7, v7, v21
	s_nop 1
	v_mov_b32_dpp v21, v9 quad_perm:[2,3,0,1] row_mask:0xf bank_mask:0xf
	v_cndmask_b32_e64 v7, v7, v22, s[6:7]
	s_waitcnt lgkmcnt(0)
	v_min_u32_e32 v22, v5, v20
	v_max_u32_e32 v5, v5, v20
	s_nop 1
	v_mov_b32_dpp v20, v8 quad_perm:[2,3,0,1] row_mask:0xf bank_mask:0xf
	v_cndmask_b32_e64 v5, v5, v22, s[6:7]
	s_waitcnt lgkmcnt(0)
	v_min_u32_e32 v22, v9, v21
	v_max_u32_e32 v9, v9, v21
	s_nop 1
	v_mov_b32_dpp v21, v11 quad_perm:[2,3,0,1] row_mask:0xf bank_mask:0xf
	v_cndmask_b32_e64 v9, v9, v22, s[6:7]
	s_waitcnt lgkmcnt(0)
	v_min_u32_e32 v22, v8, v20
	v_max_u32_e32 v8, v8, v20
	s_nop 1
	v_mov_b32_dpp v20, v10 quad_perm:[2,3,0,1] row_mask:0xf bank_mask:0xf
	v_cndmask_b32_e64 v8, v8, v22, s[6:7]
	s_waitcnt lgkmcnt(0)
	v_min_u32_e32 v22, v11, v21
	v_max_u32_e32 v11, v11, v21
	s_nop 1
	v_mov_b32_dpp v21, v13 quad_perm:[2,3,0,1] row_mask:0xf bank_mask:0xf
	v_cndmask_b32_e64 v11, v11, v22, s[6:7]
	s_waitcnt lgkmcnt(0)
	v_min_u32_e32 v22, v10, v20
	v_max_u32_e32 v10, v10, v20
	s_nop 1
	v_mov_b32_dpp v20, v12 quad_perm:[2,3,0,1] row_mask:0xf bank_mask:0xf
	v_cndmask_b32_e64 v10, v10, v22, s[6:7]
	s_waitcnt lgkmcnt(0)
	v_min_u32_e32 v22, v13, v21
	v_max_u32_e32 v13, v13, v21
	s_nop 1
	v_mov_b32_dpp v21, v15 quad_perm:[2,3,0,1] row_mask:0xf bank_mask:0xf
	v_cndmask_b32_e64 v13, v13, v22, s[6:7]
	s_waitcnt lgkmcnt(0)
	v_min_u32_e32 v22, v12, v20
	v_max_u32_e32 v12, v12, v20
	s_nop 1
	v_mov_b32_dpp v20, v14 quad_perm:[2,3,0,1] row_mask:0xf bank_mask:0xf
	v_cndmask_b32_e64 v12, v12, v22, s[6:7]
	s_waitcnt lgkmcnt(0)
	v_min_u32_e32 v22, v15, v21
	v_max_u32_e32 v15, v15, v21
	s_nop 1
	v_mov_b32_dpp v21, v17 quad_perm:[2,3,0,1] row_mask:0xf bank_mask:0xf
	v_cndmask_b32_e64 v15, v15, v22, s[6:7]
	s_waitcnt lgkmcnt(0)
	v_min_u32_e32 v22, v14, v20
	v_max_u32_e32 v14, v14, v20
	s_nop 1
	v_mov_b32_dpp v20, v16 quad_perm:[2,3,0,1] row_mask:0xf bank_mask:0xf
	v_cndmask_b32_e64 v14, v14, v22, s[6:7]
	s_waitcnt lgkmcnt(0)
	v_min_u32_e32 v22, v17, v21
	v_max_u32_e32 v17, v17, v21
	s_nop 1
	v_mov_b32_dpp v21, v18 quad_perm:[2,3,0,1] row_mask:0xf bank_mask:0xf
	v_cndmask_b32_e64 v17, v17, v22, s[6:7]
	s_waitcnt lgkmcnt(0)
	v_min_u32_e32 v22, v16, v20
	v_max_u32_e32 v16, v16, v20
	s_nop 1
	v_mov_b32_dpp v20, v3 quad_perm:[1,0,3,2] row_mask:0xf bank_mask:0xf
	v_cndmask_b32_e64 v16, v16, v22, s[6:7]
	s_waitcnt lgkmcnt(0)
	v_min_u32_e32 v22, v18, v21
	v_max_u32_e32 v18, v18, v21
	v_cndmask_b32_e64 v18, v18, v22, s[6:7]
	s_nop 1
	v_mov_b32_dpp v22, v6 quad_perm:[1,0,3,2] row_mask:0xf bank_mask:0xf
	s_waitcnt lgkmcnt(0)
	v_min_u32_e32 v21, v3, v20
	v_max_u32_e32 v3, v3, v20
	s_nop 1
	v_mov_b32_dpp v20, v4 quad_perm:[1,0,3,2] row_mask:0xf bank_mask:0xf
	s_xor_b64 s[4:5], vcc, s[4:5]
	v_cndmask_b32_e64 v3, v3, v21, s[4:5]
	s_waitcnt lgkmcnt(0)
	v_min_u32_e32 v21, v6, v22
	v_max_u32_e32 v6, v6, v22
	v_cndmask_b32_e64 v6, v6, v21, s[4:5]
	s_nop 1
	v_mov_b32_dpp v21, v7 quad_perm:[1,0,3,2] row_mask:0xf bank_mask:0xf
	s_waitcnt lgkmcnt(0)
	v_min_u32_e32 v22, v4, v20
	v_max_u32_e32 v4, v4, v20
	s_nop 1
	v_mov_b32_dpp v20, v5 quad_perm:[1,0,3,2] row_mask:0xf bank_mask:0xf
	v_cndmask_b32_e64 v4, v4, v22, s[4:5]
	s_waitcnt lgkmcnt(0)
	v_min_u32_e32 v22, v7, v21
	v_max_u32_e32 v7, v7, v21
	s_nop 1
	v_mov_b32_dpp v21, v9 quad_perm:[1,0,3,2] row_mask:0xf bank_mask:0xf
	v_cndmask_b32_e64 v7, v7, v22, s[4:5]
	s_waitcnt lgkmcnt(0)
	v_min_u32_e32 v22, v5, v20
	v_max_u32_e32 v5, v5, v20
	s_nop 1
	v_mov_b32_dpp v20, v8 quad_perm:[1,0,3,2] row_mask:0xf bank_mask:0xf
	v_cndmask_b32_e64 v5, v5, v22, s[4:5]
	s_waitcnt lgkmcnt(0)
	v_min_u32_e32 v22, v9, v21
	v_max_u32_e32 v9, v9, v21
	s_nop 1
	v_mov_b32_dpp v21, v11 quad_perm:[1,0,3,2] row_mask:0xf bank_mask:0xf
	v_cndmask_b32_e64 v9, v9, v22, s[4:5]
	s_waitcnt lgkmcnt(0)
	v_min_u32_e32 v22, v8, v20
	v_max_u32_e32 v8, v8, v20
	s_nop 1
	v_mov_b32_dpp v20, v10 quad_perm:[1,0,3,2] row_mask:0xf bank_mask:0xf
	v_cndmask_b32_e64 v8, v8, v22, s[4:5]
	s_waitcnt lgkmcnt(0)
	v_min_u32_e32 v22, v11, v21
	v_max_u32_e32 v11, v11, v21
	s_nop 1
	v_mov_b32_dpp v21, v13 quad_perm:[1,0,3,2] row_mask:0xf bank_mask:0xf
	v_cndmask_b32_e64 v11, v11, v22, s[4:5]
	s_waitcnt lgkmcnt(0)
	v_min_u32_e32 v22, v10, v20
	v_max_u32_e32 v10, v10, v20
	s_nop 1
	v_mov_b32_dpp v20, v12 quad_perm:[1,0,3,2] row_mask:0xf bank_mask:0xf
	v_cndmask_b32_e64 v10, v10, v22, s[4:5]
	s_waitcnt lgkmcnt(0)
	v_min_u32_e32 v22, v13, v21
	v_max_u32_e32 v13, v13, v21
	s_nop 1
	v_mov_b32_dpp v21, v15 quad_perm:[1,0,3,2] row_mask:0xf bank_mask:0xf
	v_cndmask_b32_e64 v13, v13, v22, s[4:5]
	s_waitcnt lgkmcnt(0)
	v_min_u32_e32 v22, v12, v20
	v_max_u32_e32 v12, v12, v20
	s_nop 1
	v_mov_b32_dpp v20, v14 quad_perm:[1,0,3,2] row_mask:0xf bank_mask:0xf
	v_cndmask_b32_e64 v12, v12, v22, s[4:5]
	s_waitcnt lgkmcnt(0)
	v_min_u32_e32 v22, v15, v21
	v_max_u32_e32 v15, v15, v21
	s_nop 1
	v_mov_b32_dpp v21, v17 quad_perm:[1,0,3,2] row_mask:0xf bank_mask:0xf
	v_cndmask_b32_e64 v15, v15, v22, s[4:5]
	s_waitcnt lgkmcnt(0)
	v_min_u32_e32 v22, v14, v20
	v_max_u32_e32 v14, v14, v20
	s_nop 1
	v_mov_b32_dpp v20, v16 quad_perm:[1,0,3,2] row_mask:0xf bank_mask:0xf
	v_cndmask_b32_e64 v14, v14, v22, s[4:5]
	s_waitcnt lgkmcnt(0)
	v_min_u32_e32 v22, v17, v21
	v_max_u32_e32 v17, v17, v21
	v_cndmask_b32_e64 v17, v17, v22, s[4:5]
	s_waitcnt lgkmcnt(0)
	v_min_u32_e32 v22, v16, v20
	v_max_u32_e32 v16, v16, v20
	v_cndmask_b32_e64 v16, v16, v22, s[4:5]
	v_xor_b32_e32 v22, 8, v1
	s_nop 1
	v_mov_b32_dpp v21, v18 quad_perm:[1,0,3,2] row_mask:0xf bank_mask:0xf
	v_cmp_lt_i32_e64 s[6:7], v22, v2
	v_xor_b32_e32 v73, 0xfc, v0
	v_mov_b32_e32 v62, 0
	v_cndmask_b32_e64 v22, v1, v22, s[6:7]
	v_lshlrev_b32_e32 v82, 2, v22
	s_nop 1
	v_mov_b32_dpp v22, v3 row_ror:8 row_mask:0xf bank_mask:0xf
	s_waitcnt lgkmcnt(0)
	v_min_u32_e32 v20, v18, v21
	v_max_u32_e32 v18, v18, v21
	s_nop 1
	v_mov_b32_dpp v21, v6 row_ror:8 row_mask:0xf bank_mask:0xf
	v_cndmask_b32_e64 v18, v18, v20, s[4:5]
	v_and_b32_e32 v20, 16, v46
	v_cmp_eq_u32_e64 s[4:5], 0, v19
	v_cmp_ne_u32_e64 s[6:7], 0, v20
	s_waitcnt lgkmcnt(0)
	v_min_u32_e32 v19, v3, v22
	v_max_u32_e32 v3, v3, v22
	s_xor_b64 s[8:9], s[4:5], s[6:7]
	v_cndmask_b32_e64 v3, v3, v19, s[8:9]
	s_nop 1
	v_mov_b32_dpp v19, v4 row_ror:8 row_mask:0xf bank_mask:0xf
	s_waitcnt lgkmcnt(0)
	v_min_u32_e32 v22, v6, v21
	v_max_u32_e32 v6, v6, v21
	s_nop 1
	v_mov_b32_dpp v21, v7 row_ror:8 row_mask:0xf bank_mask:0xf
	v_cndmask_b32_e64 v6, v6, v22, s[8:9]
	s_waitcnt lgkmcnt(0)
	v_min_u32_e32 v22, v4, v19
	v_max_u32_e32 v4, v4, v19
	s_nop 1
	v_mov_b32_dpp v19, v5 row_ror:8 row_mask:0xf bank_mask:0xf
	v_cndmask_b32_e64 v4, v4, v22, s[8:9]
	s_waitcnt lgkmcnt(0)
	v_min_u32_e32 v22, v7, v21
	v_max_u32_e32 v7, v7, v21
	s_nop 1
	v_mov_b32_dpp v21, v9 row_ror:8 row_mask:0xf bank_mask:0xf
	v_cndmask_b32_e64 v7, v7, v22, s[8:9]
	s_waitcnt lgkmcnt(0)
	v_min_u32_e32 v22, v5, v19
	v_max_u32_e32 v5, v5, v19
	s_nop 1
	v_mov_b32_dpp v19, v8 row_ror:8 row_mask:0xf bank_mask:0xf
	v_cndmask_b32_e64 v5, v5, v22, s[8:9]
	s_waitcnt lgkmcnt(0)
	v_min_u32_e32 v22, v9, v21
	v_max_u32_e32 v9, v9, v21
	s_nop 1
	v_mov_b32_dpp v21, v11 row_ror:8 row_mask:0xf bank_mask:0xf
	v_cndmask_b32_e64 v9, v9, v22, s[8:9]
	s_waitcnt lgkmcnt(0)
	v_min_u32_e32 v22, v8, v19
	v_max_u32_e32 v8, v8, v19
	s_nop 1
	v_mov_b32_dpp v19, v10 row_ror:8 row_mask:0xf bank_mask:0xf
	v_cndmask_b32_e64 v8, v8, v22, s[8:9]
	s_waitcnt lgkmcnt(0)
	v_min_u32_e32 v22, v11, v21
	v_max_u32_e32 v11, v11, v21
	s_nop 1
	v_mov_b32_dpp v21, v13 row_ror:8 row_mask:0xf bank_mask:0xf
	v_cndmask_b32_e64 v11, v11, v22, s[8:9]
	s_waitcnt lgkmcnt(0)
	v_min_u32_e32 v22, v10, v19
	v_max_u32_e32 v10, v10, v19
	s_nop 1
	v_mov_b32_dpp v19, v12 row_ror:8 row_mask:0xf bank_mask:0xf
	v_cndmask_b32_e64 v10, v10, v22, s[8:9]
	s_waitcnt lgkmcnt(0)
	v_min_u32_e32 v22, v13, v21
	v_max_u32_e32 v13, v13, v21
	s_nop 1
	v_mov_b32_dpp v21, v15 row_ror:8 row_mask:0xf bank_mask:0xf
	v_cndmask_b32_e64 v13, v13, v22, s[8:9]
	s_waitcnt lgkmcnt(0)
	v_min_u32_e32 v22, v12, v19
	v_max_u32_e32 v12, v12, v19
	s_nop 1
	v_mov_b32_dpp v19, v14 row_ror:8 row_mask:0xf bank_mask:0xf
	v_cndmask_b32_e64 v12, v12, v22, s[8:9]
	s_waitcnt lgkmcnt(0)
	v_min_u32_e32 v22, v15, v21
	v_max_u32_e32 v15, v15, v21
	s_nop 1
	v_mov_b32_dpp v21, v17 row_ror:8 row_mask:0xf bank_mask:0xf
	v_cndmask_b32_e64 v15, v15, v22, s[8:9]
	s_waitcnt lgkmcnt(0)
	v_min_u32_e32 v22, v14, v19
	v_max_u32_e32 v14, v14, v19
	s_nop 1
	v_mov_b32_dpp v19, v16 row_ror:8 row_mask:0xf bank_mask:0xf
	v_cndmask_b32_e64 v14, v14, v22, s[8:9]
	s_waitcnt lgkmcnt(0)
	v_min_u32_e32 v22, v17, v21
	v_max_u32_e32 v17, v17, v21
	s_nop 1
	v_mov_b32_dpp v21, v18 row_ror:8 row_mask:0xf bank_mask:0xf
	v_cndmask_b32_e64 v17, v17, v22, s[8:9]
	s_waitcnt lgkmcnt(0)
	v_min_u32_e32 v22, v16, v19
	v_max_u32_e32 v16, v16, v19
	s_nop 1
	v_mov_b32_dpp v19, v3 row_shl:4 row_mask:0xf bank_mask:0x5
	v_mov_b32_dpp v19, v3 row_shr:4 row_mask:0xf bank_mask:0xa
	v_cndmask_b32_e64 v16, v16, v22, s[8:9]
	s_waitcnt lgkmcnt(0)
	v_min_u32_e32 v22, v18, v21
	v_max_u32_e32 v18, v18, v21
	v_cndmask_b32_e64 v18, v18, v22, s[8:9]
	s_nop 1
	v_mov_b32_dpp v22, v6 row_shl:4 row_mask:0xf bank_mask:0x5
	v_mov_b32_dpp v22, v6 row_shr:4 row_mask:0xf bank_mask:0xa
	s_waitcnt lgkmcnt(0)
	v_min_u32_e32 v21, v3, v19
	v_max_u32_e32 v3, v3, v19
	s_xor_b64 s[8:9], s[2:3], s[6:7]
	s_nop 1
	v_mov_b32_dpp v19, v4 row_shl:4 row_mask:0xf bank_mask:0x5
	v_mov_b32_dpp v19, v4 row_shr:4 row_mask:0xf bank_mask:0xa
	v_cndmask_b32_e64 v3, v3, v21, s[8:9]
	s_waitcnt lgkmcnt(0)
	v_min_u32_e32 v21, v6, v22
	v_max_u32_e32 v6, v6, v22
	v_cndmask_b32_e64 v6, v6, v21, s[8:9]
	s_nop 1
	v_mov_b32_dpp v21, v7 row_shl:4 row_mask:0xf bank_mask:0x5
	v_mov_b32_dpp v21, v7 row_shr:4 row_mask:0xf bank_mask:0xa
	s_waitcnt lgkmcnt(0)
	v_min_u32_e32 v22, v4, v19
	v_max_u32_e32 v4, v4, v19
	s_nop 1
	v_mov_b32_dpp v19, v5 row_shl:4 row_mask:0xf bank_mask:0x5
	v_mov_b32_dpp v19, v5 row_shr:4 row_mask:0xf bank_mask:0xa
	v_cndmask_b32_e64 v4, v4, v22, s[8:9]
	s_waitcnt lgkmcnt(0)
	v_min_u32_e32 v22, v7, v21
	v_max_u32_e32 v7, v7, v21
	s_nop 1
	v_mov_b32_dpp v21, v9 row_shl:4 row_mask:0xf bank_mask:0x5
	v_mov_b32_dpp v21, v9 row_shr:4 row_mask:0xf bank_mask:0xa
	v_cndmask_b32_e64 v7, v7, v22, s[8:9]
	s_waitcnt lgkmcnt(0)
	v_min_u32_e32 v22, v5, v19
	v_max_u32_e32 v5, v5, v19
	s_nop 1
	v_mov_b32_dpp v19, v8 row_shl:4 row_mask:0xf bank_mask:0x5
	v_mov_b32_dpp v19, v8 row_shr:4 row_mask:0xf bank_mask:0xa
	v_cndmask_b32_e64 v5, v5, v22, s[8:9]
	s_waitcnt lgkmcnt(0)
	v_min_u32_e32 v22, v9, v21
	v_max_u32_e32 v9, v9, v21
	s_nop 1
	v_mov_b32_dpp v21, v11 row_shl:4 row_mask:0xf bank_mask:0x5
	v_mov_b32_dpp v21, v11 row_shr:4 row_mask:0xf bank_mask:0xa
	v_cndmask_b32_e64 v9, v9, v22, s[8:9]
	s_waitcnt lgkmcnt(0)
	v_min_u32_e32 v22, v8, v19
	v_max_u32_e32 v8, v8, v19
	s_nop 1
	v_mov_b32_dpp v19, v10 row_shl:4 row_mask:0xf bank_mask:0x5
	v_mov_b32_dpp v19, v10 row_shr:4 row_mask:0xf bank_mask:0xa
	v_cndmask_b32_e64 v8, v8, v22, s[8:9]
	s_waitcnt lgkmcnt(0)
	v_min_u32_e32 v22, v11, v21
	v_max_u32_e32 v11, v11, v21
	s_nop 1
	v_mov_b32_dpp v21, v13 row_shl:4 row_mask:0xf bank_mask:0x5
	v_mov_b32_dpp v21, v13 row_shr:4 row_mask:0xf bank_mask:0xa
	v_cndmask_b32_e64 v11, v11, v22, s[8:9]
	s_waitcnt lgkmcnt(0)
	v_min_u32_e32 v22, v10, v19
	v_max_u32_e32 v10, v10, v19
	s_nop 1
	v_mov_b32_dpp v19, v12 row_shl:4 row_mask:0xf bank_mask:0x5
	v_mov_b32_dpp v19, v12 row_shr:4 row_mask:0xf bank_mask:0xa
	v_cndmask_b32_e64 v10, v10, v22, s[8:9]
	s_waitcnt lgkmcnt(0)
	v_min_u32_e32 v22, v13, v21
	v_max_u32_e32 v13, v13, v21
	s_nop 1
	v_mov_b32_dpp v21, v15 row_shl:4 row_mask:0xf bank_mask:0x5
	v_mov_b32_dpp v21, v15 row_shr:4 row_mask:0xf bank_mask:0xa
	v_cndmask_b32_e64 v13, v13, v22, s[8:9]
	s_waitcnt lgkmcnt(0)
	v_min_u32_e32 v22, v12, v19
	v_max_u32_e32 v12, v12, v19
	s_nop 1
	v_mov_b32_dpp v19, v14 row_shl:4 row_mask:0xf bank_mask:0x5
	v_mov_b32_dpp v19, v14 row_shr:4 row_mask:0xf bank_mask:0xa
	v_cndmask_b32_e64 v12, v12, v22, s[8:9]
	s_waitcnt lgkmcnt(0)
	v_min_u32_e32 v22, v15, v21
	v_max_u32_e32 v15, v15, v21
	s_nop 1
	v_mov_b32_dpp v21, v17 row_shl:4 row_mask:0xf bank_mask:0x5
	v_mov_b32_dpp v21, v17 row_shr:4 row_mask:0xf bank_mask:0xa
	v_cndmask_b32_e64 v15, v15, v22, s[8:9]
	s_waitcnt lgkmcnt(0)
	v_min_u32_e32 v22, v14, v19
	v_max_u32_e32 v14, v14, v19
	s_nop 1
	v_mov_b32_dpp v19, v16 row_shl:4 row_mask:0xf bank_mask:0x5
	v_mov_b32_dpp v19, v16 row_shr:4 row_mask:0xf bank_mask:0xa
	v_cndmask_b32_e64 v14, v14, v22, s[8:9]
	s_waitcnt lgkmcnt(0)
	v_min_u32_e32 v22, v17, v21
	v_max_u32_e32 v17, v17, v21
	s_nop 1
	v_mov_b32_dpp v21, v18 row_shl:4 row_mask:0xf bank_mask:0x5
	v_mov_b32_dpp v21, v18 row_shr:4 row_mask:0xf bank_mask:0xa
	v_cndmask_b32_e64 v17, v17, v22, s[8:9]
	s_waitcnt lgkmcnt(0)
	v_min_u32_e32 v22, v16, v19
	v_max_u32_e32 v16, v16, v19
	s_nop 1
	v_mov_b32_dpp v19, v3 quad_perm:[2,3,0,1] row_mask:0xf bank_mask:0xf
	v_cndmask_b32_e64 v16, v16, v22, s[8:9]
	s_waitcnt lgkmcnt(0)
	v_min_u32_e32 v22, v18, v21
	v_max_u32_e32 v18, v18, v21
	v_cndmask_b32_e64 v18, v18, v22, s[8:9]
	s_nop 1
	v_mov_b32_dpp v22, v6 quad_perm:[2,3,0,1] row_mask:0xf bank_mask:0xf
	s_waitcnt lgkmcnt(0)
	v_min_u32_e32 v21, v3, v19
	v_max_u32_e32 v3, v3, v19
	s_nop 1
	v_mov_b32_dpp v19, v4 quad_perm:[2,3,0,1] row_mask:0xf bank_mask:0xf
	s_xor_b64 s[8:9], s[0:1], s[6:7]
	v_cndmask_b32_e64 v3, v3, v21, s[8:9]
	s_waitcnt lgkmcnt(0)
	v_min_u32_e32 v21, v6, v22
	v_max_u32_e32 v6, v6, v22
	v_cndmask_b32_e64 v6, v6, v21, s[8:9]
	s_nop 1
	v_mov_b32_dpp v21, v7 quad_perm:[2,3,0,1] row_mask:0xf bank_mask:0xf
	s_waitcnt lgkmcnt(0)
	v_min_u32_e32 v22, v4, v19
	v_max_u32_e32 v4, v4, v19
	s_nop 1
	v_mov_b32_dpp v19, v5 quad_perm:[2,3,0,1] row_mask:0xf bank_mask:0xf
	v_cndmask_b32_e64 v4, v4, v22, s[8:9]
	s_waitcnt lgkmcnt(0)
	v_min_u32_e32 v22, v7, v21
	v_max_u32_e32 v7, v7, v21
	s_nop 1
	v_mov_b32_dpp v21, v9 quad_perm:[2,3,0,1] row_mask:0xf bank_mask:0xf
	v_cndmask_b32_e64 v7, v7, v22, s[8:9]
	s_waitcnt lgkmcnt(0)
	v_min_u32_e32 v22, v5, v19
	v_max_u32_e32 v5, v5, v19
	s_nop 1
	v_mov_b32_dpp v19, v8 quad_perm:[2,3,0,1] row_mask:0xf bank_mask:0xf
	v_cndmask_b32_e64 v5, v5, v22, s[8:9]
	s_waitcnt lgkmcnt(0)
	v_min_u32_e32 v22, v9, v21
	v_max_u32_e32 v9, v9, v21
	s_nop 1
	v_mov_b32_dpp v21, v11 quad_perm:[2,3,0,1] row_mask:0xf bank_mask:0xf
	v_cndmask_b32_e64 v9, v9, v22, s[8:9]
	s_waitcnt lgkmcnt(0)
	v_min_u32_e32 v22, v8, v19
	v_max_u32_e32 v8, v8, v19
	s_nop 1
	v_mov_b32_dpp v19, v10 quad_perm:[2,3,0,1] row_mask:0xf bank_mask:0xf
	v_cndmask_b32_e64 v8, v8, v22, s[8:9]
	s_waitcnt lgkmcnt(0)
	v_min_u32_e32 v22, v11, v21
	v_max_u32_e32 v11, v11, v21
	s_nop 1
	v_mov_b32_dpp v21, v13 quad_perm:[2,3,0,1] row_mask:0xf bank_mask:0xf
	v_cndmask_b32_e64 v11, v11, v22, s[8:9]
	s_waitcnt lgkmcnt(0)
	v_min_u32_e32 v22, v10, v19
	v_max_u32_e32 v10, v10, v19
	s_nop 1
	v_mov_b32_dpp v19, v12 quad_perm:[2,3,0,1] row_mask:0xf bank_mask:0xf
	v_cndmask_b32_e64 v10, v10, v22, s[8:9]
	s_waitcnt lgkmcnt(0)
	v_min_u32_e32 v22, v13, v21
	v_max_u32_e32 v13, v13, v21
	s_nop 1
	v_mov_b32_dpp v21, v15 quad_perm:[2,3,0,1] row_mask:0xf bank_mask:0xf
	v_cndmask_b32_e64 v13, v13, v22, s[8:9]
	s_waitcnt lgkmcnt(0)
	v_min_u32_e32 v22, v12, v19
	v_max_u32_e32 v12, v12, v19
	s_nop 1
	v_mov_b32_dpp v19, v14 quad_perm:[2,3,0,1] row_mask:0xf bank_mask:0xf
	v_cndmask_b32_e64 v12, v12, v22, s[8:9]
	s_waitcnt lgkmcnt(0)
	v_min_u32_e32 v22, v15, v21
	v_max_u32_e32 v15, v15, v21
	s_nop 1
	v_mov_b32_dpp v21, v17 quad_perm:[2,3,0,1] row_mask:0xf bank_mask:0xf
	v_cndmask_b32_e64 v15, v15, v22, s[8:9]
	s_waitcnt lgkmcnt(0)
	v_min_u32_e32 v22, v14, v19
	v_max_u32_e32 v14, v14, v19
	s_nop 1
	v_mov_b32_dpp v19, v16 quad_perm:[2,3,0,1] row_mask:0xf bank_mask:0xf
	v_cndmask_b32_e64 v14, v14, v22, s[8:9]
	s_waitcnt lgkmcnt(0)
	v_min_u32_e32 v22, v17, v21
	v_max_u32_e32 v17, v17, v21
	s_nop 1
	v_mov_b32_dpp v21, v18 quad_perm:[2,3,0,1] row_mask:0xf bank_mask:0xf
	v_cndmask_b32_e64 v17, v17, v22, s[8:9]
	s_waitcnt lgkmcnt(0)
	v_min_u32_e32 v22, v16, v19
	v_max_u32_e32 v16, v16, v19
	s_nop 1
	v_mov_b32_dpp v19, v3 quad_perm:[1,0,3,2] row_mask:0xf bank_mask:0xf
	v_cndmask_b32_e64 v16, v16, v22, s[8:9]
	s_waitcnt lgkmcnt(0)
	v_min_u32_e32 v22, v18, v21
	v_max_u32_e32 v18, v18, v21
	v_cndmask_b32_e64 v18, v18, v22, s[8:9]
	s_waitcnt lgkmcnt(0)
	v_min_u32_e32 v21, v3, v19
	s_nop 1
	v_mov_b32_dpp v22, v6 quad_perm:[1,0,3,2] row_mask:0xf bank_mask:0xf
	v_max_u32_e32 v3, v3, v19
	s_xor_b64 s[6:7], vcc, s[6:7]
	v_cndmask_b32_e64 v19, v3, v21, s[6:7]
	s_nop 1
	v_mov_b32_dpp v3, v4 quad_perm:[1,0,3,2] row_mask:0xf bank_mask:0xf
	s_waitcnt lgkmcnt(0)
	v_min_u32_e32 v21, v6, v22
	v_max_u32_e32 v6, v6, v22
	v_cndmask_b32_e64 v6, v6, v21, s[6:7]
	s_nop 1
	v_mov_b32_dpp v21, v7 quad_perm:[1,0,3,2] row_mask:0xf bank_mask:0xf
	s_waitcnt lgkmcnt(0)
	v_min_u32_e32 v22, v4, v3
	v_max_u32_e32 v3, v4, v3
	v_cndmask_b32_e64 v4, v3, v22, s[6:7]
	s_nop 1
	v_mov_b32_dpp v3, v5 quad_perm:[1,0,3,2] row_mask:0xf bank_mask:0xf
	s_waitcnt lgkmcnt(0)
	v_min_u32_e32 v22, v7, v21
	v_max_u32_e32 v7, v7, v21
	v_cndmask_b32_e64 v7, v7, v22, s[6:7]
	s_nop 1
	v_mov_b32_dpp v21, v9 quad_perm:[1,0,3,2] row_mask:0xf bank_mask:0xf
	s_waitcnt lgkmcnt(0)
	v_min_u32_e32 v22, v5, v3
	v_max_u32_e32 v3, v5, v3
	v_cndmask_b32_e64 v5, v3, v22, s[6:7]
	s_nop 1
	v_mov_b32_dpp v3, v8 quad_perm:[1,0,3,2] row_mask:0xf bank_mask:0xf
	s_waitcnt lgkmcnt(0)
	v_min_u32_e32 v22, v9, v21
	v_max_u32_e32 v9, v9, v21
	v_cndmask_b32_e64 v9, v9, v22, s[6:7]
	s_nop 1
	v_mov_b32_dpp v21, v11 quad_perm:[1,0,3,2] row_mask:0xf bank_mask:0xf
	s_waitcnt lgkmcnt(0)
	v_min_u32_e32 v22, v8, v3
	v_max_u32_e32 v3, v8, v3
	v_cndmask_b32_e64 v8, v3, v22, s[6:7]
	s_nop 1
	v_mov_b32_dpp v3, v10 quad_perm:[1,0,3,2] row_mask:0xf bank_mask:0xf
	s_waitcnt lgkmcnt(0)
	v_min_u32_e32 v22, v11, v21
	v_max_u32_e32 v11, v11, v21
	v_cndmask_b32_e64 v11, v11, v22, s[6:7]
	s_nop 1
	v_mov_b32_dpp v21, v13 quad_perm:[1,0,3,2] row_mask:0xf bank_mask:0xf
	s_waitcnt lgkmcnt(0)
	v_min_u32_e32 v22, v10, v3
	v_max_u32_e32 v3, v10, v3
	v_cndmask_b32_e64 v10, v3, v22, s[6:7]
	s_nop 1
	v_mov_b32_dpp v3, v12 quad_perm:[1,0,3,2] row_mask:0xf bank_mask:0xf
	s_waitcnt lgkmcnt(0)
	v_min_u32_e32 v22, v13, v21
	v_max_u32_e32 v13, v13, v21
	v_cndmask_b32_e64 v13, v13, v22, s[6:7]
	s_nop 1
	v_mov_b32_dpp v21, v15 quad_perm:[1,0,3,2] row_mask:0xf bank_mask:0xf
	s_waitcnt lgkmcnt(0)
	v_min_u32_e32 v22, v12, v3
	v_max_u32_e32 v3, v12, v3
	v_cndmask_b32_e64 v12, v3, v22, s[6:7]
	s_nop 1
	v_mov_b32_dpp v3, v14 quad_perm:[1,0,3,2] row_mask:0xf bank_mask:0xf
	s_waitcnt lgkmcnt(0)
	v_min_u32_e32 v22, v15, v21
	v_max_u32_e32 v15, v15, v21
	v_cndmask_b32_e64 v15, v15, v22, s[6:7]
	s_nop 1
	v_mov_b32_dpp v21, v17 quad_perm:[1,0,3,2] row_mask:0xf bank_mask:0xf
	s_waitcnt lgkmcnt(0)
	v_min_u32_e32 v22, v14, v3
	v_max_u32_e32 v3, v14, v3
	v_cndmask_b32_e64 v14, v3, v22, s[6:7]
	s_nop 1
	v_mov_b32_dpp v3, v16 quad_perm:[1,0,3,2] row_mask:0xf bank_mask:0xf
	s_waitcnt lgkmcnt(0)
	v_min_u32_e32 v22, v17, v21
	v_max_u32_e32 v17, v17, v21
	v_cndmask_b32_e64 v17, v17, v22, s[6:7]
	s_nop 1
	v_mov_b32_dpp v21, v18 quad_perm:[1,0,3,2] row_mask:0xf bank_mask:0xf
	s_waitcnt lgkmcnt(0)
	v_min_u32_e32 v22, v16, v3
	v_max_u32_e32 v3, v16, v3
	v_cndmask_b32_e64 v16, v3, v22, s[6:7]
	v_xor_b32_e32 v22, 16, v1
	v_cmp_lt_i32_e64 s[8:9], v22, v2
	s_waitcnt lgkmcnt(0)
	v_min_u32_e32 v3, v18, v21
	v_max_u32_e32 v18, v18, v21
	v_cndmask_b32_e64 v22, v1, v22, s[8:9]
	v_lshlrev_b32_e32 v83, 2, v22
	ds_bpermute_b32 v22, v83, v19
	ds_bpermute_b32 v21, v83, v6
	v_cndmask_b32_e64 v18, v18, v3, s[6:7]
	v_and_b32_e32 v3, 32, v46
	v_cmp_eq_u32_e64 s[6:7], 0, v20
	v_cmp_ne_u32_e64 s[8:9], 0, v3
	s_waitcnt lgkmcnt(0)
	v_min_u32_e32 v20, v19, v22
	v_max_u32_e32 v19, v19, v22
	s_xor_b64 s[10:11], s[6:7], s[8:9]
	v_cndmask_b32_e64 v19, v19, v20, s[10:11]
	ds_bpermute_b32 v20, v83, v4
	s_waitcnt lgkmcnt(0)
	v_min_u32_e32 v22, v6, v21
	v_max_u32_e32 v6, v6, v21
	ds_bpermute_b32 v21, v83, v7
	v_cndmask_b32_e64 v6, v6, v22, s[10:11]
	s_waitcnt lgkmcnt(0)
	v_min_u32_e32 v22, v4, v20
	v_max_u32_e32 v4, v4, v20
	ds_bpermute_b32 v20, v83, v5
	v_cndmask_b32_e64 v4, v4, v22, s[10:11]
	s_waitcnt lgkmcnt(0)
	v_min_u32_e32 v22, v7, v21
	v_max_u32_e32 v7, v7, v21
	ds_bpermute_b32 v21, v83, v9
	v_cndmask_b32_e64 v7, v7, v22, s[10:11]
	s_waitcnt lgkmcnt(0)
	v_min_u32_e32 v22, v5, v20
	v_max_u32_e32 v5, v5, v20
	ds_bpermute_b32 v20, v83, v8
	v_cndmask_b32_e64 v5, v5, v22, s[10:11]
	s_waitcnt lgkmcnt(0)
	v_min_u32_e32 v22, v9, v21
	v_max_u32_e32 v9, v9, v21
	ds_bpermute_b32 v21, v83, v11
	v_cndmask_b32_e64 v9, v9, v22, s[10:11]
	s_waitcnt lgkmcnt(0)
	v_min_u32_e32 v22, v8, v20
	v_max_u32_e32 v8, v8, v20
	ds_bpermute_b32 v20, v83, v10
	v_cndmask_b32_e64 v8, v8, v22, s[10:11]
	s_waitcnt lgkmcnt(0)
	v_min_u32_e32 v22, v11, v21
	v_max_u32_e32 v11, v11, v21
	ds_bpermute_b32 v21, v83, v13
	v_cndmask_b32_e64 v11, v11, v22, s[10:11]
	s_waitcnt lgkmcnt(0)
	v_min_u32_e32 v22, v10, v20
	v_max_u32_e32 v10, v10, v20
	ds_bpermute_b32 v20, v83, v12
	v_cndmask_b32_e64 v10, v10, v22, s[10:11]
	s_waitcnt lgkmcnt(0)
	v_min_u32_e32 v22, v13, v21
	v_max_u32_e32 v13, v13, v21
	ds_bpermute_b32 v21, v83, v15
	v_cndmask_b32_e64 v13, v13, v22, s[10:11]
	s_waitcnt lgkmcnt(0)
	v_min_u32_e32 v22, v12, v20
	v_max_u32_e32 v12, v12, v20
	ds_bpermute_b32 v20, v83, v14
	v_cndmask_b32_e64 v12, v12, v22, s[10:11]
	s_waitcnt lgkmcnt(0)
	v_min_u32_e32 v22, v15, v21
	v_max_u32_e32 v15, v15, v21
	ds_bpermute_b32 v21, v83, v17
	v_cndmask_b32_e64 v15, v15, v22, s[10:11]
	s_waitcnt lgkmcnt(0)
	v_min_u32_e32 v22, v14, v20
	v_max_u32_e32 v14, v14, v20
	ds_bpermute_b32 v20, v83, v16
	v_cndmask_b32_e64 v14, v14, v22, s[10:11]
	s_waitcnt lgkmcnt(0)
	v_min_u32_e32 v22, v17, v21
	v_max_u32_e32 v17, v17, v21
	ds_bpermute_b32 v21, v83, v18
	v_cndmask_b32_e64 v17, v17, v22, s[10:11]
	s_waitcnt lgkmcnt(0)
	v_min_u32_e32 v22, v16, v20
	v_max_u32_e32 v16, v16, v20
	s_nop 1
	v_mov_b32_dpp v20, v19 row_ror:8 row_mask:0xf bank_mask:0xf
	v_cndmask_b32_e64 v16, v16, v22, s[10:11]
	s_waitcnt lgkmcnt(0)
	v_min_u32_e32 v22, v18, v21
	v_max_u32_e32 v18, v18, v21
	v_cndmask_b32_e64 v18, v18, v22, s[10:11]
	s_nop 1
	v_mov_b32_dpp v22, v6 row_ror:8 row_mask:0xf bank_mask:0xf
	s_waitcnt lgkmcnt(0)
	v_min_u32_e32 v21, v19, v20
	v_max_u32_e32 v19, v19, v20
	s_xor_b64 s[10:11], s[4:5], s[8:9]
	v_cndmask_b32_e64 v19, v19, v21, s[10:11]
	s_nop 1
	v_mov_b32_dpp v20, v4 row_ror:8 row_mask:0xf bank_mask:0xf
	s_waitcnt lgkmcnt(0)
	v_min_u32_e32 v21, v6, v22
	v_max_u32_e32 v6, v6, v22
	v_cndmask_b32_e64 v6, v6, v21, s[10:11]
	s_nop 1
	v_mov_b32_dpp v21, v7 row_ror:8 row_mask:0xf bank_mask:0xf
	s_waitcnt lgkmcnt(0)
	v_min_u32_e32 v22, v4, v20
	v_max_u32_e32 v4, v4, v20
	s_nop 1
	v_mov_b32_dpp v20, v5 row_ror:8 row_mask:0xf bank_mask:0xf
	v_cndmask_b32_e64 v4, v4, v22, s[10:11]
	s_waitcnt lgkmcnt(0)
	v_min_u32_e32 v22, v7, v21
	v_max_u32_e32 v7, v7, v21
	s_nop 1
	v_mov_b32_dpp v21, v9 row_ror:8 row_mask:0xf bank_mask:0xf
	v_cndmask_b32_e64 v7, v7, v22, s[10:11]
	s_waitcnt lgkmcnt(0)
	v_min_u32_e32 v22, v5, v20
	v_max_u32_e32 v5, v5, v20
	s_nop 1
	v_mov_b32_dpp v20, v8 row_ror:8 row_mask:0xf bank_mask:0xf
	v_cndmask_b32_e64 v5, v5, v22, s[10:11]
	s_waitcnt lgkmcnt(0)
	v_min_u32_e32 v22, v9, v21
	v_max_u32_e32 v9, v9, v21
	s_nop 1
	v_mov_b32_dpp v21, v11 row_ror:8 row_mask:0xf bank_mask:0xf
	v_cndmask_b32_e64 v9, v9, v22, s[10:11]
	s_waitcnt lgkmcnt(0)
	v_min_u32_e32 v22, v8, v20
	v_max_u32_e32 v8, v8, v20
	s_nop 1
	v_mov_b32_dpp v20, v10 row_ror:8 row_mask:0xf bank_mask:0xf
	v_cndmask_b32_e64 v8, v8, v22, s[10:11]
	s_waitcnt lgkmcnt(0)
	v_min_u32_e32 v22, v11, v21
	v_max_u32_e32 v11, v11, v21
	s_nop 1
	v_mov_b32_dpp v21, v13 row_ror:8 row_mask:0xf bank_mask:0xf
	v_cndmask_b32_e64 v11, v11, v22, s[10:11]
	s_waitcnt lgkmcnt(0)
	v_min_u32_e32 v22, v10, v20
	v_max_u32_e32 v10, v10, v20
	s_nop 1
	v_mov_b32_dpp v20, v12 row_ror:8 row_mask:0xf bank_mask:0xf
	v_cndmask_b32_e64 v10, v10, v22, s[10:11]
	s_waitcnt lgkmcnt(0)
	v_min_u32_e32 v22, v13, v21
	v_max_u32_e32 v13, v13, v21
	s_nop 1
	v_mov_b32_dpp v21, v15 row_ror:8 row_mask:0xf bank_mask:0xf
	v_cndmask_b32_e64 v13, v13, v22, s[10:11]
	s_waitcnt lgkmcnt(0)
	v_min_u32_e32 v22, v12, v20
	v_max_u32_e32 v12, v12, v20
	s_nop 1
	v_mov_b32_dpp v20, v14 row_ror:8 row_mask:0xf bank_mask:0xf
	v_cndmask_b32_e64 v12, v12, v22, s[10:11]
	s_waitcnt lgkmcnt(0)
	v_min_u32_e32 v22, v15, v21
	v_max_u32_e32 v15, v15, v21
	s_nop 1
	v_mov_b32_dpp v21, v17 row_ror:8 row_mask:0xf bank_mask:0xf
	v_cndmask_b32_e64 v15, v15, v22, s[10:11]
	s_waitcnt lgkmcnt(0)
	v_min_u32_e32 v22, v14, v20
	v_max_u32_e32 v14, v14, v20
	s_nop 1
	v_mov_b32_dpp v20, v16 row_ror:8 row_mask:0xf bank_mask:0xf
	v_cndmask_b32_e64 v14, v14, v22, s[10:11]
	s_waitcnt lgkmcnt(0)
	v_min_u32_e32 v22, v17, v21
	v_max_u32_e32 v17, v17, v21
	s_nop 1
	v_mov_b32_dpp v21, v18 row_ror:8 row_mask:0xf bank_mask:0xf
	v_cndmask_b32_e64 v17, v17, v22, s[10:11]
	s_waitcnt lgkmcnt(0)
	v_min_u32_e32 v22, v16, v20
	v_max_u32_e32 v16, v16, v20
	s_nop 1
	v_mov_b32_dpp v20, v19 row_shl:4 row_mask:0xf bank_mask:0x5
	v_mov_b32_dpp v20, v19 row_shr:4 row_mask:0xf bank_mask:0xa
	v_cndmask_b32_e64 v16, v16, v22, s[10:11]
	s_waitcnt lgkmcnt(0)
	v_min_u32_e32 v22, v18, v21
	v_max_u32_e32 v18, v18, v21
	v_cndmask_b32_e64 v18, v18, v22, s[10:11]
	s_nop 1
	v_mov_b32_dpp v22, v6 row_shl:4 row_mask:0xf bank_mask:0x5
	v_mov_b32_dpp v22, v6 row_shr:4 row_mask:0xf bank_mask:0xa
	s_waitcnt lgkmcnt(0)
	v_min_u32_e32 v21, v19, v20
	v_max_u32_e32 v19, v19, v20
	s_xor_b64 s[10:11], s[2:3], s[8:9]
	v_cndmask_b32_e64 v19, v19, v21, s[10:11]
	s_nop 1
	v_mov_b32_dpp v20, v4 row_shl:4 row_mask:0xf bank_mask:0x5
	v_mov_b32_dpp v20, v4 row_shr:4 row_mask:0xf bank_mask:0xa
	s_waitcnt lgkmcnt(0)
	v_min_u32_e32 v21, v6, v22
	v_max_u32_e32 v6, v6, v22
	v_cndmask_b32_e64 v6, v6, v21, s[10:11]
	s_nop 1
	v_mov_b32_dpp v21, v7 row_shl:4 row_mask:0xf bank_mask:0x5
	v_mov_b32_dpp v21, v7 row_shr:4 row_mask:0xf bank_mask:0xa
	s_waitcnt lgkmcnt(0)
	v_min_u32_e32 v22, v4, v20
	v_max_u32_e32 v4, v4, v20
	s_nop 1
	v_mov_b32_dpp v20, v5 row_shl:4 row_mask:0xf bank_mask:0x5
	v_mov_b32_dpp v20, v5 row_shr:4 row_mask:0xf bank_mask:0xa
	v_cndmask_b32_e64 v4, v4, v22, s[10:11]
	s_waitcnt lgkmcnt(0)
	v_min_u32_e32 v22, v7, v21
	v_max_u32_e32 v7, v7, v21
	s_nop 1
	v_mov_b32_dpp v21, v9 row_shl:4 row_mask:0xf bank_mask:0x5
	v_mov_b32_dpp v21, v9 row_shr:4 row_mask:0xf bank_mask:0xa
	v_cndmask_b32_e64 v7, v7, v22, s[10:11]
	s_waitcnt lgkmcnt(0)
	v_min_u32_e32 v22, v5, v20
	v_max_u32_e32 v5, v5, v20
	s_nop 1
	v_mov_b32_dpp v20, v8 row_shl:4 row_mask:0xf bank_mask:0x5
	v_mov_b32_dpp v20, v8 row_shr:4 row_mask:0xf bank_mask:0xa
	v_cndmask_b32_e64 v5, v5, v22, s[10:11]
	s_waitcnt lgkmcnt(0)
	v_min_u32_e32 v22, v9, v21
	v_max_u32_e32 v9, v9, v21
	s_nop 1
	v_mov_b32_dpp v21, v11 row_shl:4 row_mask:0xf bank_mask:0x5
	v_mov_b32_dpp v21, v11 row_shr:4 row_mask:0xf bank_mask:0xa
	v_cndmask_b32_e64 v9, v9, v22, s[10:11]
	s_waitcnt lgkmcnt(0)
	v_min_u32_e32 v22, v8, v20
	v_max_u32_e32 v8, v8, v20
	s_nop 1
	v_mov_b32_dpp v20, v10 row_shl:4 row_mask:0xf bank_mask:0x5
	v_mov_b32_dpp v20, v10 row_shr:4 row_mask:0xf bank_mask:0xa
	v_cndmask_b32_e64 v8, v8, v22, s[10:11]
	s_waitcnt lgkmcnt(0)
	v_min_u32_e32 v22, v11, v21
	v_max_u32_e32 v11, v11, v21
	s_nop 1
	v_mov_b32_dpp v21, v13 row_shl:4 row_mask:0xf bank_mask:0x5
	v_mov_b32_dpp v21, v13 row_shr:4 row_mask:0xf bank_mask:0xa
	v_cndmask_b32_e64 v11, v11, v22, s[10:11]
	s_waitcnt lgkmcnt(0)
	v_min_u32_e32 v22, v10, v20
	v_max_u32_e32 v10, v10, v20
	s_nop 1
	v_mov_b32_dpp v20, v12 row_shl:4 row_mask:0xf bank_mask:0x5
	v_mov_b32_dpp v20, v12 row_shr:4 row_mask:0xf bank_mask:0xa
	v_cndmask_b32_e64 v10, v10, v22, s[10:11]
	s_waitcnt lgkmcnt(0)
	v_min_u32_e32 v22, v13, v21
	v_max_u32_e32 v13, v13, v21
	s_nop 1
	v_mov_b32_dpp v21, v15 row_shl:4 row_mask:0xf bank_mask:0x5
	v_mov_b32_dpp v21, v15 row_shr:4 row_mask:0xf bank_mask:0xa
	v_cndmask_b32_e64 v13, v13, v22, s[10:11]
	s_waitcnt lgkmcnt(0)
	v_min_u32_e32 v22, v12, v20
	v_max_u32_e32 v12, v12, v20
	s_nop 1
	v_mov_b32_dpp v20, v14 row_shl:4 row_mask:0xf bank_mask:0x5
	v_mov_b32_dpp v20, v14 row_shr:4 row_mask:0xf bank_mask:0xa
	v_cndmask_b32_e64 v12, v12, v22, s[10:11]
	s_waitcnt lgkmcnt(0)
	v_min_u32_e32 v22, v15, v21
	v_max_u32_e32 v15, v15, v21
	s_nop 1
	v_mov_b32_dpp v21, v17 row_shl:4 row_mask:0xf bank_mask:0x5
	v_mov_b32_dpp v21, v17 row_shr:4 row_mask:0xf bank_mask:0xa
	v_cndmask_b32_e64 v15, v15, v22, s[10:11]
	s_waitcnt lgkmcnt(0)
	v_min_u32_e32 v22, v14, v20
	v_max_u32_e32 v14, v14, v20
	s_nop 1
	v_mov_b32_dpp v20, v16 row_shl:4 row_mask:0xf bank_mask:0x5
	v_mov_b32_dpp v20, v16 row_shr:4 row_mask:0xf bank_mask:0xa
	v_cndmask_b32_e64 v14, v14, v22, s[10:11]
	s_waitcnt lgkmcnt(0)
	v_min_u32_e32 v22, v17, v21
	v_max_u32_e32 v17, v17, v21
	s_nop 1
	v_mov_b32_dpp v21, v18 row_shl:4 row_mask:0xf bank_mask:0x5
	v_mov_b32_dpp v21, v18 row_shr:4 row_mask:0xf bank_mask:0xa
	v_cndmask_b32_e64 v17, v17, v22, s[10:11]
	s_waitcnt lgkmcnt(0)
	v_min_u32_e32 v22, v16, v20
	v_max_u32_e32 v16, v16, v20
	s_nop 1
	v_mov_b32_dpp v20, v19 quad_perm:[2,3,0,1] row_mask:0xf bank_mask:0xf
	v_cndmask_b32_e64 v16, v16, v22, s[10:11]
	s_waitcnt lgkmcnt(0)
	v_min_u32_e32 v22, v18, v21
	v_max_u32_e32 v18, v18, v21
	v_cndmask_b32_e64 v18, v18, v22, s[10:11]
	s_nop 1
	v_mov_b32_dpp v22, v6 quad_perm:[2,3,0,1] row_mask:0xf bank_mask:0xf
	s_waitcnt lgkmcnt(0)
	v_min_u32_e32 v21, v19, v20
	v_max_u32_e32 v19, v19, v20
	s_xor_b64 s[10:11], s[0:1], s[8:9]
	s_nop 1
	v_mov_b32_dpp v20, v4 quad_perm:[2,3,0,1] row_mask:0xf bank_mask:0xf
	v_cndmask_b32_e64 v19, v19, v21, s[10:11]
	s_waitcnt lgkmcnt(0)
	v_min_u32_e32 v21, v6, v22
	v_max_u32_e32 v6, v6, v22
	v_cndmask_b32_e64 v6, v6, v21, s[10:11]
	s_nop 1
	v_mov_b32_dpp v21, v7 quad_perm:[2,3,0,1] row_mask:0xf bank_mask:0xf
	s_waitcnt lgkmcnt(0)
	v_min_u32_e32 v22, v4, v20
	v_max_u32_e32 v4, v4, v20
	s_nop 1
	v_mov_b32_dpp v20, v5 quad_perm:[2,3,0,1] row_mask:0xf bank_mask:0xf
	v_cndmask_b32_e64 v4, v4, v22, s[10:11]
	s_waitcnt lgkmcnt(0)
	v_min_u32_e32 v22, v7, v21
	v_max_u32_e32 v7, v7, v21
	s_nop 1
	v_mov_b32_dpp v21, v9 quad_perm:[2,3,0,1] row_mask:0xf bank_mask:0xf
	v_cndmask_b32_e64 v7, v7, v22, s[10:11]
	s_waitcnt lgkmcnt(0)
	v_min_u32_e32 v22, v5, v20
	v_max_u32_e32 v5, v5, v20
	s_nop 1
	v_mov_b32_dpp v20, v8 quad_perm:[2,3,0,1] row_mask:0xf bank_mask:0xf
	v_cndmask_b32_e64 v5, v5, v22, s[10:11]
	s_waitcnt lgkmcnt(0)
	v_min_u32_e32 v22, v9, v21
	v_max_u32_e32 v9, v9, v21
	s_nop 1
	v_mov_b32_dpp v21, v11 quad_perm:[2,3,0,1] row_mask:0xf bank_mask:0xf
	v_cndmask_b32_e64 v9, v9, v22, s[10:11]
	s_waitcnt lgkmcnt(0)
	v_min_u32_e32 v22, v8, v20
	v_max_u32_e32 v8, v8, v20
	s_nop 1
	v_mov_b32_dpp v20, v10 quad_perm:[2,3,0,1] row_mask:0xf bank_mask:0xf
	v_cndmask_b32_e64 v8, v8, v22, s[10:11]
	s_waitcnt lgkmcnt(0)
	v_min_u32_e32 v22, v11, v21
	v_max_u32_e32 v11, v11, v21
	s_nop 1
	v_mov_b32_dpp v21, v13 quad_perm:[2,3,0,1] row_mask:0xf bank_mask:0xf
	v_cndmask_b32_e64 v11, v11, v22, s[10:11]
	s_waitcnt lgkmcnt(0)
	v_min_u32_e32 v22, v10, v20
	v_max_u32_e32 v10, v10, v20
	s_nop 1
	v_mov_b32_dpp v20, v12 quad_perm:[2,3,0,1] row_mask:0xf bank_mask:0xf
	v_cndmask_b32_e64 v10, v10, v22, s[10:11]
	s_waitcnt lgkmcnt(0)
	v_min_u32_e32 v22, v13, v21
	v_max_u32_e32 v13, v13, v21
	s_nop 1
	v_mov_b32_dpp v21, v15 quad_perm:[2,3,0,1] row_mask:0xf bank_mask:0xf
	v_cndmask_b32_e64 v13, v13, v22, s[10:11]
	s_waitcnt lgkmcnt(0)
	v_min_u32_e32 v22, v12, v20
	v_max_u32_e32 v12, v12, v20
	s_nop 1
	v_mov_b32_dpp v20, v14 quad_perm:[2,3,0,1] row_mask:0xf bank_mask:0xf
	v_cndmask_b32_e64 v12, v12, v22, s[10:11]
	s_waitcnt lgkmcnt(0)
	v_min_u32_e32 v22, v15, v21
	v_max_u32_e32 v15, v15, v21
	s_nop 1
	v_mov_b32_dpp v21, v17 quad_perm:[2,3,0,1] row_mask:0xf bank_mask:0xf
	v_cndmask_b32_e64 v15, v15, v22, s[10:11]
	s_waitcnt lgkmcnt(0)
	v_min_u32_e32 v22, v14, v20
	v_max_u32_e32 v14, v14, v20
	s_nop 1
	v_mov_b32_dpp v20, v16 quad_perm:[2,3,0,1] row_mask:0xf bank_mask:0xf
	v_cndmask_b32_e64 v14, v14, v22, s[10:11]
	s_waitcnt lgkmcnt(0)
	v_min_u32_e32 v22, v17, v21
	v_max_u32_e32 v17, v17, v21
	s_nop 1
	v_mov_b32_dpp v21, v18 quad_perm:[2,3,0,1] row_mask:0xf bank_mask:0xf
	v_cndmask_b32_e64 v17, v17, v22, s[10:11]
	s_waitcnt lgkmcnt(0)
	v_min_u32_e32 v22, v16, v20
	v_max_u32_e32 v16, v16, v20
	s_nop 1
	v_mov_b32_dpp v20, v19 quad_perm:[1,0,3,2] row_mask:0xf bank_mask:0xf
	v_cndmask_b32_e64 v16, v16, v22, s[10:11]
	s_waitcnt lgkmcnt(0)
	v_min_u32_e32 v22, v18, v21
	v_max_u32_e32 v18, v18, v21
	v_cndmask_b32_e64 v18, v18, v22, s[10:11]
	s_nop 1
	v_mov_b32_dpp v22, v6 quad_perm:[1,0,3,2] row_mask:0xf bank_mask:0xf
	s_waitcnt lgkmcnt(0)
	v_min_u32_e32 v21, v19, v20
	v_max_u32_e32 v19, v19, v20
	s_nop 1
	v_mov_b32_dpp v20, v4 quad_perm:[1,0,3,2] row_mask:0xf bank_mask:0xf
	s_xor_b64 s[8:9], vcc, s[8:9]
	v_cndmask_b32_e64 v19, v19, v21, s[8:9]
	s_waitcnt lgkmcnt(0)
	v_min_u32_e32 v21, v6, v22
	v_max_u32_e32 v6, v6, v22
	v_cndmask_b32_e64 v6, v6, v21, s[8:9]
	s_nop 1
	v_mov_b32_dpp v21, v7 quad_perm:[1,0,3,2] row_mask:0xf bank_mask:0xf
	s_waitcnt lgkmcnt(0)
	v_min_u32_e32 v22, v4, v20
	v_max_u32_e32 v4, v4, v20
	s_nop 1
	v_mov_b32_dpp v20, v5 quad_perm:[1,0,3,2] row_mask:0xf bank_mask:0xf
	v_cndmask_b32_e64 v4, v4, v22, s[8:9]
	s_waitcnt lgkmcnt(0)
	v_min_u32_e32 v22, v7, v21
	v_max_u32_e32 v7, v7, v21
	s_nop 1
	v_mov_b32_dpp v21, v9 quad_perm:[1,0,3,2] row_mask:0xf bank_mask:0xf
	v_cndmask_b32_e64 v7, v7, v22, s[8:9]
	s_waitcnt lgkmcnt(0)
	v_min_u32_e32 v22, v5, v20
	v_max_u32_e32 v5, v5, v20
	s_nop 1
	v_mov_b32_dpp v20, v8 quad_perm:[1,0,3,2] row_mask:0xf bank_mask:0xf
	v_cndmask_b32_e64 v5, v5, v22, s[8:9]
	s_waitcnt lgkmcnt(0)
	v_min_u32_e32 v22, v9, v21
	v_max_u32_e32 v9, v9, v21
	s_nop 1
	v_mov_b32_dpp v21, v11 quad_perm:[1,0,3,2] row_mask:0xf bank_mask:0xf
	v_cndmask_b32_e64 v9, v9, v22, s[8:9]
	s_waitcnt lgkmcnt(0)
	v_min_u32_e32 v22, v8, v20
	v_max_u32_e32 v8, v8, v20
	s_nop 1
	v_mov_b32_dpp v20, v10 quad_perm:[1,0,3,2] row_mask:0xf bank_mask:0xf
	v_cndmask_b32_e64 v8, v8, v22, s[8:9]
	s_waitcnt lgkmcnt(0)
	v_min_u32_e32 v22, v11, v21
	v_max_u32_e32 v11, v11, v21
	s_nop 1
	v_mov_b32_dpp v21, v13 quad_perm:[1,0,3,2] row_mask:0xf bank_mask:0xf
	v_cndmask_b32_e64 v11, v11, v22, s[8:9]
	s_waitcnt lgkmcnt(0)
	v_min_u32_e32 v22, v10, v20
	v_max_u32_e32 v10, v10, v20
	s_nop 1
	v_mov_b32_dpp v20, v12 quad_perm:[1,0,3,2] row_mask:0xf bank_mask:0xf
	v_cndmask_b32_e64 v10, v10, v22, s[8:9]
	s_waitcnt lgkmcnt(0)
	v_min_u32_e32 v22, v13, v21
	v_max_u32_e32 v13, v13, v21
	s_nop 1
	v_mov_b32_dpp v21, v15 quad_perm:[1,0,3,2] row_mask:0xf bank_mask:0xf
	v_cndmask_b32_e64 v13, v13, v22, s[8:9]
	s_waitcnt lgkmcnt(0)
	v_min_u32_e32 v22, v12, v20
	v_max_u32_e32 v12, v12, v20
	s_nop 1
	v_mov_b32_dpp v20, v14 quad_perm:[1,0,3,2] row_mask:0xf bank_mask:0xf
	v_cndmask_b32_e64 v12, v12, v22, s[8:9]
	s_waitcnt lgkmcnt(0)
	v_min_u32_e32 v22, v15, v21
	v_max_u32_e32 v15, v15, v21
	s_nop 1
	v_mov_b32_dpp v21, v17 quad_perm:[1,0,3,2] row_mask:0xf bank_mask:0xf
	v_cndmask_b32_e64 v15, v15, v22, s[8:9]
	s_waitcnt lgkmcnt(0)
	v_min_u32_e32 v22, v14, v20
	v_max_u32_e32 v14, v14, v20
	s_nop 1
	v_mov_b32_dpp v20, v16 quad_perm:[1,0,3,2] row_mask:0xf bank_mask:0xf
	v_cndmask_b32_e64 v14, v14, v22, s[8:9]
	s_waitcnt lgkmcnt(0)
	v_min_u32_e32 v22, v17, v21
	v_max_u32_e32 v17, v17, v21
	v_cndmask_b32_e64 v17, v17, v22, s[8:9]
	s_waitcnt lgkmcnt(0)
	v_min_u32_e32 v21, v16, v20
	v_max_u32_e32 v16, v16, v20
	s_nop 1
	v_mov_b32_dpp v20, v18 quad_perm:[1,0,3,2] row_mask:0xf bank_mask:0xf
	v_xor_b32_e32 v22, 32, v1
	v_cmp_lt_i32_e64 s[10:11], v22, v2
	v_cndmask_b32_e64 v2, v16, v21, s[8:9]
	v_mov_b32_e32 v63, v91
	v_cndmask_b32_e64 v1, v1, v22, s[10:11]
	v_lshlrev_b32_e32 v84, 2, v1
	ds_bpermute_b32 v1, v84, v19
	s_waitcnt lgkmcnt(0)
	v_min_u32_e32 v16, v18, v20
	v_max_u32_e32 v18, v18, v20
	ds_bpermute_b32 v20, v84, v6
	v_cndmask_b32_e64 v16, v18, v16, s[8:9]
	s_waitcnt lgkmcnt(0)
	v_min_u32_e32 v18, v19, v1
	v_max_u32_e32 v1, v19, v1
	v_cmp_eq_u32_e64 s[8:9], 0, v3
	ds_bpermute_b32 v3, v84, v4
	s_mov_b32 s10, 0x1fffff80
	v_cndmask_b32_e64 v1, v1, v18, s[8:9]
	s_waitcnt lgkmcnt(0)
	v_min_u32_e32 v18, v6, v20
	v_max_u32_e32 v6, v6, v20
	v_cndmask_b32_e64 v6, v18, v6, s[8:9]
	ds_bpermute_b32 v18, v84, v7
	s_waitcnt lgkmcnt(0)
	v_min_u32_e32 v19, v4, v3
	v_max_u32_e32 v3, v4, v3
	ds_bpermute_b32 v4, v84, v5
	v_cndmask_b32_e64 v3, v3, v19, s[8:9]
	s_waitcnt lgkmcnt(0)
	v_min_u32_e32 v19, v7, v18
	v_max_u32_e32 v7, v7, v18
	ds_bpermute_b32 v18, v84, v9
	v_cndmask_b32_e64 v7, v19, v7, s[8:9]
	s_waitcnt lgkmcnt(0)
	v_min_u32_e32 v19, v5, v4
	v_max_u32_e32 v4, v5, v4
	ds_bpermute_b32 v5, v84, v8
	v_cndmask_b32_e64 v4, v4, v19, s[8:9]
	s_waitcnt lgkmcnt(0)
	v_min_u32_e32 v19, v9, v18
	v_max_u32_e32 v9, v9, v18
	ds_bpermute_b32 v18, v84, v11
	v_cndmask_b32_e64 v9, v19, v9, s[8:9]
	s_waitcnt lgkmcnt(0)
	v_min_u32_e32 v19, v8, v5
	v_max_u32_e32 v5, v8, v5
	ds_bpermute_b32 v8, v84, v10
	v_cndmask_b32_e64 v5, v5, v19, s[8:9]
	s_waitcnt lgkmcnt(0)
	v_min_u32_e32 v19, v11, v18
	v_max_u32_e32 v11, v11, v18
	ds_bpermute_b32 v18, v84, v13
	v_cndmask_b32_e64 v11, v19, v11, s[8:9]
	s_waitcnt lgkmcnt(0)
	v_min_u32_e32 v19, v10, v8
	v_max_u32_e32 v8, v10, v8
	ds_bpermute_b32 v10, v84, v12
	v_cndmask_b32_e64 v8, v8, v19, s[8:9]
	s_waitcnt lgkmcnt(0)
	v_min_u32_e32 v19, v13, v18
	v_max_u32_e32 v13, v13, v18
	ds_bpermute_b32 v18, v84, v15
	v_cndmask_b32_e64 v13, v19, v13, s[8:9]
	s_waitcnt lgkmcnt(0)
	v_min_u32_e32 v19, v12, v10
	v_max_u32_e32 v10, v12, v10
	ds_bpermute_b32 v12, v84, v14
	v_cndmask_b32_e64 v10, v10, v19, s[8:9]
	s_waitcnt lgkmcnt(0)
	v_min_u32_e32 v19, v15, v18
	v_max_u32_e32 v15, v15, v18
	ds_bpermute_b32 v18, v84, v17
	v_cndmask_b32_e64 v15, v19, v15, s[8:9]
	s_waitcnt lgkmcnt(0)
	v_min_u32_e32 v19, v14, v12
	v_max_u32_e32 v12, v14, v12
	ds_bpermute_b32 v14, v84, v2
	v_cndmask_b32_e64 v12, v12, v19, s[8:9]
	s_waitcnt lgkmcnt(0)
	v_min_u32_e32 v19, v17, v18
	v_max_u32_e32 v17, v17, v18
	ds_bpermute_b32 v18, v84, v16
	v_cndmask_b32_e64 v17, v19, v17, s[8:9]
	s_waitcnt lgkmcnt(0)
	v_min_u32_e32 v19, v2, v14
	v_max_u32_e32 v2, v2, v14
	ds_bpermute_b32 v14, v83, v1
	v_cndmask_b32_e64 v2, v2, v19, s[8:9]
	s_waitcnt lgkmcnt(0)
	v_min_u32_e32 v19, v16, v18
	v_max_u32_e32 v16, v16, v18
	ds_bpermute_b32 v18, v83, v6
	v_cndmask_b32_e64 v16, v19, v16, s[8:9]
	s_waitcnt lgkmcnt(0)
	v_min_u32_e32 v19, v1, v14
	v_max_u32_e32 v1, v1, v14
	ds_bpermute_b32 v14, v83, v3
	v_cndmask_b32_e64 v1, v1, v19, s[6:7]
	s_waitcnt lgkmcnt(0)
	v_min_u32_e32 v19, v6, v18
	v_max_u32_e32 v6, v6, v18
	ds_bpermute_b32 v18, v83, v7
	v_cndmask_b32_e64 v6, v19, v6, s[6:7]
	s_waitcnt lgkmcnt(0)
	v_min_u32_e32 v19, v3, v14
	v_max_u32_e32 v3, v3, v14
	ds_bpermute_b32 v14, v83, v4
	v_cndmask_b32_e64 v3, v3, v19, s[6:7]
	s_waitcnt lgkmcnt(0)
	v_min_u32_e32 v19, v7, v18
	v_max_u32_e32 v7, v7, v18
	ds_bpermute_b32 v18, v83, v9
	v_cndmask_b32_e64 v7, v19, v7, s[6:7]
	s_waitcnt lgkmcnt(0)
	v_min_u32_e32 v19, v4, v14
	v_max_u32_e32 v4, v4, v14
	ds_bpermute_b32 v14, v83, v5
	v_cndmask_b32_e64 v4, v4, v19, s[6:7]
	s_waitcnt lgkmcnt(0)
	v_min_u32_e32 v19, v9, v18
	v_max_u32_e32 v9, v9, v18
	ds_bpermute_b32 v18, v83, v11
	v_cndmask_b32_e64 v9, v19, v9, s[6:7]
	s_waitcnt lgkmcnt(0)
	v_min_u32_e32 v19, v5, v14
	v_max_u32_e32 v5, v5, v14
	ds_bpermute_b32 v14, v83, v8
	v_cndmask_b32_e64 v5, v5, v19, s[6:7]
	s_waitcnt lgkmcnt(0)
	v_min_u32_e32 v19, v11, v18
	v_max_u32_e32 v11, v11, v18
	ds_bpermute_b32 v18, v83, v13
	v_cndmask_b32_e64 v11, v19, v11, s[6:7]
	s_waitcnt lgkmcnt(0)
	v_min_u32_e32 v19, v8, v14
	v_max_u32_e32 v8, v8, v14
	ds_bpermute_b32 v14, v83, v10
	v_cndmask_b32_e64 v8, v8, v19, s[6:7]
	s_waitcnt lgkmcnt(0)
	v_min_u32_e32 v19, v13, v18
	v_max_u32_e32 v13, v13, v18
	ds_bpermute_b32 v18, v83, v15
	v_cndmask_b32_e64 v13, v19, v13, s[6:7]
	s_waitcnt lgkmcnt(0)
	v_min_u32_e32 v19, v10, v14
	v_max_u32_e32 v10, v10, v14
	ds_bpermute_b32 v14, v83, v12
	v_cndmask_b32_e64 v10, v10, v19, s[6:7]
	s_waitcnt lgkmcnt(0)
	v_min_u32_e32 v19, v15, v18
	v_max_u32_e32 v15, v15, v18
	ds_bpermute_b32 v18, v83, v17
	v_cndmask_b32_e64 v15, v19, v15, s[6:7]
	s_waitcnt lgkmcnt(0)
	v_min_u32_e32 v19, v12, v14
	v_max_u32_e32 v12, v12, v14
	ds_bpermute_b32 v14, v83, v2
	v_cndmask_b32_e64 v12, v12, v19, s[6:7]
	s_waitcnt lgkmcnt(0)
	v_min_u32_e32 v19, v17, v18
	v_max_u32_e32 v17, v17, v18
	ds_bpermute_b32 v18, v83, v16
	v_cndmask_b32_e64 v17, v19, v17, s[6:7]
	s_waitcnt lgkmcnt(0)
	v_min_u32_e32 v19, v2, v14
	v_max_u32_e32 v2, v2, v14
	s_nop 1
	v_mov_b32_dpp v14, v1 row_ror:8 row_mask:0xf bank_mask:0xf
	v_cndmask_b32_e64 v2, v2, v19, s[6:7]
	s_waitcnt lgkmcnt(0)
	v_min_u32_e32 v19, v16, v18
	v_max_u32_e32 v16, v16, v18
	s_nop 1
	v_mov_b32_dpp v18, v6 row_ror:8 row_mask:0xf bank_mask:0xf
	v_cndmask_b32_e64 v16, v19, v16, s[6:7]
	s_waitcnt lgkmcnt(0)
	v_min_u32_e32 v19, v1, v14
	v_max_u32_e32 v1, v1, v14
	s_nop 1
	v_mov_b32_dpp v14, v3 row_ror:8 row_mask:0xf bank_mask:0xf
	v_cndmask_b32_e64 v1, v1, v19, s[4:5]
	s_waitcnt lgkmcnt(0)
	v_min_u32_e32 v19, v6, v18
	v_max_u32_e32 v6, v6, v18
	s_nop 1
	v_mov_b32_dpp v18, v7 row_ror:8 row_mask:0xf bank_mask:0xf
	v_cndmask_b32_e64 v6, v19, v6, s[4:5]
	s_waitcnt lgkmcnt(0)
	v_min_u32_e32 v19, v3, v14
	v_max_u32_e32 v3, v3, v14
	s_nop 1
	v_mov_b32_dpp v14, v4 row_ror:8 row_mask:0xf bank_mask:0xf
	v_cndmask_b32_e64 v3, v3, v19, s[4:5]
	s_waitcnt lgkmcnt(0)
	v_min_u32_e32 v19, v7, v18
	v_max_u32_e32 v7, v7, v18
	s_nop 1
	v_mov_b32_dpp v18, v9 row_ror:8 row_mask:0xf bank_mask:0xf
	v_cndmask_b32_e64 v7, v19, v7, s[4:5]
	s_waitcnt lgkmcnt(0)
	v_min_u32_e32 v19, v4, v14
	v_max_u32_e32 v4, v4, v14
	s_nop 1
	v_mov_b32_dpp v14, v5 row_ror:8 row_mask:0xf bank_mask:0xf
	v_cndmask_b32_e64 v4, v4, v19, s[4:5]
	s_waitcnt lgkmcnt(0)
	v_min_u32_e32 v19, v9, v18
	v_max_u32_e32 v9, v9, v18
	s_nop 1
	v_mov_b32_dpp v18, v11 row_ror:8 row_mask:0xf bank_mask:0xf
	v_cndmask_b32_e64 v9, v19, v9, s[4:5]
	s_waitcnt lgkmcnt(0)
	v_min_u32_e32 v19, v5, v14
	v_max_u32_e32 v5, v5, v14
	s_nop 1
	v_mov_b32_dpp v14, v8 row_ror:8 row_mask:0xf bank_mask:0xf
	v_cndmask_b32_e64 v5, v5, v19, s[4:5]
	s_waitcnt lgkmcnt(0)
	v_min_u32_e32 v19, v11, v18
	v_max_u32_e32 v11, v11, v18
	s_nop 1
	v_mov_b32_dpp v18, v13 row_ror:8 row_mask:0xf bank_mask:0xf
	v_cndmask_b32_e64 v11, v19, v11, s[4:5]
	s_waitcnt lgkmcnt(0)
	v_min_u32_e32 v19, v8, v14
	v_max_u32_e32 v8, v8, v14
	s_nop 1
	v_mov_b32_dpp v14, v10 row_ror:8 row_mask:0xf bank_mask:0xf
	v_cndmask_b32_e64 v8, v8, v19, s[4:5]
	s_waitcnt lgkmcnt(0)
	v_min_u32_e32 v19, v13, v18
	v_max_u32_e32 v13, v13, v18
	s_nop 1
	v_mov_b32_dpp v18, v15 row_ror:8 row_mask:0xf bank_mask:0xf
	v_cndmask_b32_e64 v13, v19, v13, s[4:5]
	s_waitcnt lgkmcnt(0)
	v_min_u32_e32 v19, v10, v14
	v_max_u32_e32 v10, v10, v14
	s_nop 1
	v_mov_b32_dpp v14, v12 row_ror:8 row_mask:0xf bank_mask:0xf
	v_cndmask_b32_e64 v10, v10, v19, s[4:5]
	s_waitcnt lgkmcnt(0)
	v_min_u32_e32 v19, v15, v18
	v_max_u32_e32 v15, v15, v18
	s_nop 1
	v_mov_b32_dpp v18, v17 row_ror:8 row_mask:0xf bank_mask:0xf
	v_cndmask_b32_e64 v15, v19, v15, s[4:5]
	s_waitcnt lgkmcnt(0)
	v_min_u32_e32 v19, v12, v14
	v_max_u32_e32 v12, v12, v14
	s_nop 1
	v_mov_b32_dpp v14, v2 row_ror:8 row_mask:0xf bank_mask:0xf
	v_cndmask_b32_e64 v12, v12, v19, s[4:5]
	s_waitcnt lgkmcnt(0)
	v_min_u32_e32 v19, v17, v18
	v_max_u32_e32 v17, v17, v18
	s_nop 1
	v_mov_b32_dpp v18, v16 row_ror:8 row_mask:0xf bank_mask:0xf
	v_cndmask_b32_e64 v17, v19, v17, s[4:5]
	s_waitcnt lgkmcnt(0)
	v_min_u32_e32 v19, v2, v14
	v_max_u32_e32 v2, v2, v14
	s_nop 1
	v_mov_b32_dpp v14, v1 row_shl:4 row_mask:0xf bank_mask:0x5
	v_mov_b32_dpp v14, v1 row_shr:4 row_mask:0xf bank_mask:0xa
	v_cndmask_b32_e64 v2, v2, v19, s[4:5]
	s_waitcnt lgkmcnt(0)
	v_min_u32_e32 v19, v16, v18
	v_max_u32_e32 v16, v16, v18
	s_nop 1
	v_mov_b32_dpp v18, v6 row_shl:4 row_mask:0xf bank_mask:0x5
	v_mov_b32_dpp v18, v6 row_shr:4 row_mask:0xf bank_mask:0xa
	v_cndmask_b32_e64 v16, v19, v16, s[4:5]
	s_waitcnt lgkmcnt(0)
	v_min_u32_e32 v19, v1, v14
	v_max_u32_e32 v1, v1, v14
	s_nop 1
	v_mov_b32_dpp v14, v3 row_shl:4 row_mask:0xf bank_mask:0x5
	v_mov_b32_dpp v14, v3 row_shr:4 row_mask:0xf bank_mask:0xa
	v_cndmask_b32_e64 v1, v1, v19, s[2:3]
	s_waitcnt lgkmcnt(0)
	v_min_u32_e32 v19, v6, v18
	v_max_u32_e32 v6, v6, v18
	s_nop 1
	v_mov_b32_dpp v18, v7 row_shl:4 row_mask:0xf bank_mask:0x5
	v_mov_b32_dpp v18, v7 row_shr:4 row_mask:0xf bank_mask:0xa
	v_cndmask_b32_e64 v6, v19, v6, s[2:3]
	s_waitcnt lgkmcnt(0)
	v_min_u32_e32 v19, v3, v14
	v_max_u32_e32 v3, v3, v14
	s_nop 1
	v_mov_b32_dpp v14, v4 row_shl:4 row_mask:0xf bank_mask:0x5
	v_mov_b32_dpp v14, v4 row_shr:4 row_mask:0xf bank_mask:0xa
	v_cndmask_b32_e64 v3, v3, v19, s[2:3]
	s_waitcnt lgkmcnt(0)
	v_min_u32_e32 v19, v7, v18
	v_max_u32_e32 v7, v7, v18
	s_nop 1
	v_mov_b32_dpp v18, v9 row_shl:4 row_mask:0xf bank_mask:0x5
	v_mov_b32_dpp v18, v9 row_shr:4 row_mask:0xf bank_mask:0xa
	v_cndmask_b32_e64 v7, v19, v7, s[2:3]
	s_waitcnt lgkmcnt(0)
	v_min_u32_e32 v19, v4, v14
	v_max_u32_e32 v4, v4, v14
	s_nop 1
	v_mov_b32_dpp v14, v5 row_shl:4 row_mask:0xf bank_mask:0x5
	v_mov_b32_dpp v14, v5 row_shr:4 row_mask:0xf bank_mask:0xa
	v_cndmask_b32_e64 v4, v4, v19, s[2:3]
	s_waitcnt lgkmcnt(0)
	v_min_u32_e32 v19, v9, v18
	v_max_u32_e32 v9, v9, v18
	s_nop 1
	v_mov_b32_dpp v18, v11 row_shl:4 row_mask:0xf bank_mask:0x5
	v_mov_b32_dpp v18, v11 row_shr:4 row_mask:0xf bank_mask:0xa
	v_cndmask_b32_e64 v9, v19, v9, s[2:3]
	s_waitcnt lgkmcnt(0)
	v_min_u32_e32 v19, v5, v14
	v_max_u32_e32 v5, v5, v14
	s_nop 1
	v_mov_b32_dpp v14, v8 row_shl:4 row_mask:0xf bank_mask:0x5
	v_mov_b32_dpp v14, v8 row_shr:4 row_mask:0xf bank_mask:0xa
	v_cndmask_b32_e64 v5, v5, v19, s[2:3]
	s_waitcnt lgkmcnt(0)
	v_min_u32_e32 v19, v11, v18
	v_max_u32_e32 v11, v11, v18
	s_nop 1
	v_mov_b32_dpp v18, v13 row_shl:4 row_mask:0xf bank_mask:0x5
	v_mov_b32_dpp v18, v13 row_shr:4 row_mask:0xf bank_mask:0xa
	v_cndmask_b32_e64 v11, v19, v11, s[2:3]
	s_waitcnt lgkmcnt(0)
	v_min_u32_e32 v19, v8, v14
	v_max_u32_e32 v8, v8, v14
	s_nop 1
	v_mov_b32_dpp v14, v10 row_shl:4 row_mask:0xf bank_mask:0x5
	v_mov_b32_dpp v14, v10 row_shr:4 row_mask:0xf bank_mask:0xa
	v_cndmask_b32_e64 v8, v8, v19, s[2:3]
	s_waitcnt lgkmcnt(0)
	v_min_u32_e32 v19, v13, v18
	v_max_u32_e32 v13, v13, v18
	s_nop 1
	v_mov_b32_dpp v18, v15 row_shl:4 row_mask:0xf bank_mask:0x5
	v_mov_b32_dpp v18, v15 row_shr:4 row_mask:0xf bank_mask:0xa
	v_cndmask_b32_e64 v13, v19, v13, s[2:3]
	s_waitcnt lgkmcnt(0)
	v_min_u32_e32 v19, v10, v14
	v_max_u32_e32 v10, v10, v14
	s_nop 1
	v_mov_b32_dpp v14, v12 row_shl:4 row_mask:0xf bank_mask:0x5
	v_mov_b32_dpp v14, v12 row_shr:4 row_mask:0xf bank_mask:0xa
	v_cndmask_b32_e64 v10, v10, v19, s[2:3]
	s_waitcnt lgkmcnt(0)
	v_min_u32_e32 v19, v15, v18
	v_max_u32_e32 v15, v15, v18
	s_nop 1
	v_mov_b32_dpp v18, v17 row_shl:4 row_mask:0xf bank_mask:0x5
	v_mov_b32_dpp v18, v17 row_shr:4 row_mask:0xf bank_mask:0xa
	v_cndmask_b32_e64 v15, v19, v15, s[2:3]
	s_waitcnt lgkmcnt(0)
	v_min_u32_e32 v19, v12, v14
	v_max_u32_e32 v12, v12, v14
	s_nop 1
	v_mov_b32_dpp v14, v2 row_shl:4 row_mask:0xf bank_mask:0x5
	v_mov_b32_dpp v14, v2 row_shr:4 row_mask:0xf bank_mask:0xa
	v_cndmask_b32_e64 v12, v12, v19, s[2:3]
	s_waitcnt lgkmcnt(0)
	v_min_u32_e32 v19, v17, v18
	v_max_u32_e32 v17, v17, v18
	s_nop 1
	v_mov_b32_dpp v18, v16 row_shl:4 row_mask:0xf bank_mask:0x5
	v_mov_b32_dpp v18, v16 row_shr:4 row_mask:0xf bank_mask:0xa
	v_cndmask_b32_e64 v17, v19, v17, s[2:3]
	s_waitcnt lgkmcnt(0)
	v_min_u32_e32 v19, v2, v14
	v_max_u32_e32 v2, v2, v14
	s_nop 1
	v_mov_b32_dpp v14, v1 quad_perm:[2,3,0,1] row_mask:0xf bank_mask:0xf
	v_cndmask_b32_e64 v2, v2, v19, s[2:3]
	s_waitcnt lgkmcnt(0)
	v_min_u32_e32 v19, v16, v18
	v_max_u32_e32 v16, v16, v18
	s_nop 1
	v_mov_b32_dpp v18, v6 quad_perm:[2,3,0,1] row_mask:0xf bank_mask:0xf
	v_cndmask_b32_e64 v16, v19, v16, s[2:3]
	s_waitcnt lgkmcnt(0)
	v_min_u32_e32 v19, v1, v14
	v_max_u32_e32 v1, v1, v14
	s_nop 1
	v_mov_b32_dpp v14, v3 quad_perm:[2,3,0,1] row_mask:0xf bank_mask:0xf
	v_cndmask_b32_e64 v1, v1, v19, s[0:1]
	s_waitcnt lgkmcnt(0)
	v_min_u32_e32 v19, v6, v18
	v_max_u32_e32 v6, v6, v18
	s_nop 1
	v_mov_b32_dpp v18, v7 quad_perm:[2,3,0,1] row_mask:0xf bank_mask:0xf
	v_cndmask_b32_e64 v6, v19, v6, s[0:1]
	s_waitcnt lgkmcnt(0)
	v_min_u32_e32 v19, v3, v14
	v_max_u32_e32 v3, v3, v14
	s_nop 1
	v_mov_b32_dpp v14, v4 quad_perm:[2,3,0,1] row_mask:0xf bank_mask:0xf
	v_cndmask_b32_e64 v3, v3, v19, s[0:1]
	s_waitcnt lgkmcnt(0)
	v_min_u32_e32 v19, v7, v18
	v_max_u32_e32 v7, v7, v18
	s_nop 1
	v_mov_b32_dpp v18, v9 quad_perm:[2,3,0,1] row_mask:0xf bank_mask:0xf
	v_cndmask_b32_e64 v7, v19, v7, s[0:1]
	s_waitcnt lgkmcnt(0)
	v_min_u32_e32 v19, v4, v14
	v_max_u32_e32 v4, v4, v14
	s_nop 1
	v_mov_b32_dpp v14, v5 quad_perm:[2,3,0,1] row_mask:0xf bank_mask:0xf
	v_cndmask_b32_e64 v4, v4, v19, s[0:1]
	s_waitcnt lgkmcnt(0)
	v_min_u32_e32 v19, v9, v18
	v_max_u32_e32 v9, v9, v18
	s_nop 1
	v_mov_b32_dpp v18, v11 quad_perm:[2,3,0,1] row_mask:0xf bank_mask:0xf
	v_cndmask_b32_e64 v9, v19, v9, s[0:1]
	s_waitcnt lgkmcnt(0)
	v_min_u32_e32 v19, v5, v14
	v_max_u32_e32 v5, v5, v14
	s_nop 1
	v_mov_b32_dpp v14, v8 quad_perm:[2,3,0,1] row_mask:0xf bank_mask:0xf
	v_cndmask_b32_e64 v5, v5, v19, s[0:1]
	s_waitcnt lgkmcnt(0)
	v_min_u32_e32 v19, v11, v18
	v_max_u32_e32 v11, v11, v18
	s_nop 1
	v_mov_b32_dpp v18, v13 quad_perm:[2,3,0,1] row_mask:0xf bank_mask:0xf
	v_cndmask_b32_e64 v11, v19, v11, s[0:1]
	s_waitcnt lgkmcnt(0)
	v_min_u32_e32 v19, v8, v14
	v_max_u32_e32 v8, v8, v14
	s_nop 1
	v_mov_b32_dpp v14, v10 quad_perm:[2,3,0,1] row_mask:0xf bank_mask:0xf
	v_cndmask_b32_e64 v8, v8, v19, s[0:1]
	s_waitcnt lgkmcnt(0)
	v_min_u32_e32 v19, v13, v18
	v_max_u32_e32 v13, v13, v18
	s_nop 1
	v_mov_b32_dpp v18, v15 quad_perm:[2,3,0,1] row_mask:0xf bank_mask:0xf
	v_cndmask_b32_e64 v13, v19, v13, s[0:1]
	s_waitcnt lgkmcnt(0)
	v_min_u32_e32 v19, v10, v14
	v_max_u32_e32 v10, v10, v14
	s_nop 1
	v_mov_b32_dpp v14, v12 quad_perm:[2,3,0,1] row_mask:0xf bank_mask:0xf
	v_cndmask_b32_e64 v10, v10, v19, s[0:1]
	s_waitcnt lgkmcnt(0)
	v_min_u32_e32 v19, v15, v18
	v_max_u32_e32 v15, v15, v18
	s_nop 1
	v_mov_b32_dpp v18, v17 quad_perm:[2,3,0,1] row_mask:0xf bank_mask:0xf
	v_cndmask_b32_e64 v15, v19, v15, s[0:1]
	s_waitcnt lgkmcnt(0)
	v_min_u32_e32 v19, v12, v14
	v_max_u32_e32 v12, v12, v14
	s_nop 1
	v_mov_b32_dpp v14, v2 quad_perm:[2,3,0,1] row_mask:0xf bank_mask:0xf
	v_cndmask_b32_e64 v12, v12, v19, s[0:1]
	s_waitcnt lgkmcnt(0)
	v_min_u32_e32 v19, v17, v18
	v_max_u32_e32 v17, v17, v18
	s_nop 1
	v_mov_b32_dpp v18, v16 quad_perm:[2,3,0,1] row_mask:0xf bank_mask:0xf
	v_cndmask_b32_e64 v17, v19, v17, s[0:1]
	s_waitcnt lgkmcnt(0)
	v_min_u32_e32 v19, v2, v14
	v_max_u32_e32 v2, v2, v14
	s_nop 1
	v_mov_b32_dpp v14, v1 quad_perm:[1,0,3,2] row_mask:0xf bank_mask:0xf
	v_cndmask_b32_e64 v2, v2, v19, s[0:1]
	s_waitcnt lgkmcnt(0)
	v_min_u32_e32 v19, v16, v18
	v_max_u32_e32 v16, v16, v18
	s_nop 1
	v_mov_b32_dpp v18, v6 quad_perm:[1,0,3,2] row_mask:0xf bank_mask:0xf
	v_cndmask_b32_e64 v16, v19, v16, s[0:1]
	s_waitcnt lgkmcnt(0)
	v_min_u32_e32 v19, v1, v14
	v_max_u32_e32 v1, v1, v14
	s_nop 1
	v_mov_b32_dpp v14, v3 quad_perm:[1,0,3,2] row_mask:0xf bank_mask:0xf
	v_cndmask_b32_e32 v1, v1, v19, vcc
	s_waitcnt lgkmcnt(0)
	v_min_u32_e32 v19, v6, v18
	v_max_u32_e32 v6, v6, v18
	s_nop 1
	v_mov_b32_dpp v18, v7 quad_perm:[1,0,3,2] row_mask:0xf bank_mask:0xf
	v_cndmask_b32_e32 v6, v19, v6, vcc
	s_waitcnt lgkmcnt(0)
	v_min_u32_e32 v19, v3, v14
	v_max_u32_e32 v3, v3, v14
	s_nop 1
	v_mov_b32_dpp v14, v4 quad_perm:[1,0,3,2] row_mask:0xf bank_mask:0xf
	v_cndmask_b32_e32 v3, v3, v19, vcc
	s_waitcnt lgkmcnt(0)
	v_min_u32_e32 v19, v7, v18
	v_max_u32_e32 v7, v7, v18
	s_nop 1
	v_mov_b32_dpp v18, v9 quad_perm:[1,0,3,2] row_mask:0xf bank_mask:0xf
	v_cndmask_b32_e32 v7, v19, v7, vcc
	s_waitcnt lgkmcnt(0)
	v_min_u32_e32 v19, v4, v14
	v_max_u32_e32 v4, v4, v14
	s_nop 1
	v_mov_b32_dpp v14, v5 quad_perm:[1,0,3,2] row_mask:0xf bank_mask:0xf
	v_cndmask_b32_e32 v4, v4, v19, vcc
	s_waitcnt lgkmcnt(0)
	v_min_u32_e32 v19, v9, v18
	v_max_u32_e32 v9, v9, v18
	s_nop 1
	v_mov_b32_dpp v18, v11 quad_perm:[1,0,3,2] row_mask:0xf bank_mask:0xf
	v_cndmask_b32_e32 v9, v19, v9, vcc
	s_waitcnt lgkmcnt(0)
	v_min_u32_e32 v19, v5, v14
	v_max_u32_e32 v5, v5, v14
	s_nop 1
	v_mov_b32_dpp v14, v8 quad_perm:[1,0,3,2] row_mask:0xf bank_mask:0xf
	v_cndmask_b32_e32 v5, v5, v19, vcc
	s_waitcnt lgkmcnt(0)
	v_min_u32_e32 v19, v11, v18
	v_max_u32_e32 v11, v11, v18
	s_nop 1
	v_mov_b32_dpp v18, v13 quad_perm:[1,0,3,2] row_mask:0xf bank_mask:0xf
	v_cndmask_b32_e32 v11, v19, v11, vcc
	s_waitcnt lgkmcnt(0)
	v_min_u32_e32 v19, v8, v14
	v_max_u32_e32 v8, v8, v14
	s_nop 1
	v_mov_b32_dpp v14, v10 quad_perm:[1,0,3,2] row_mask:0xf bank_mask:0xf
	v_cndmask_b32_e32 v8, v8, v19, vcc
	s_waitcnt lgkmcnt(0)
	v_min_u32_e32 v19, v13, v18
	v_max_u32_e32 v13, v13, v18
	s_nop 1
	v_mov_b32_dpp v18, v15 quad_perm:[1,0,3,2] row_mask:0xf bank_mask:0xf
	v_cndmask_b32_e32 v13, v19, v13, vcc
	s_waitcnt lgkmcnt(0)
	v_min_u32_e32 v19, v10, v14
	v_max_u32_e32 v10, v10, v14
	s_nop 1
	v_mov_b32_dpp v14, v12 quad_perm:[1,0,3,2] row_mask:0xf bank_mask:0xf
	v_cndmask_b32_e32 v10, v10, v19, vcc
	s_waitcnt lgkmcnt(0)
	v_min_u32_e32 v19, v15, v18
	v_max_u32_e32 v15, v15, v18
	s_nop 1
	v_mov_b32_dpp v18, v17 quad_perm:[1,0,3,2] row_mask:0xf bank_mask:0xf
	v_cndmask_b32_e32 v15, v19, v15, vcc
	s_waitcnt lgkmcnt(0)
	v_min_u32_e32 v19, v12, v14
	v_max_u32_e32 v12, v12, v14
	v_cndmask_b32_e32 v12, v12, v19, vcc
	s_nop 1
	v_mov_b32_dpp v14, v2 quad_perm:[1,0,3,2] row_mask:0xf bank_mask:0xf
	s_waitcnt lgkmcnt(0)
	v_min_u32_e32 v19, v17, v18
	v_max_u32_e32 v17, v17, v18
	s_nop 1
	v_mov_b32_dpp v18, v16 quad_perm:[1,0,3,2] row_mask:0xf bank_mask:0xf
	v_cndmask_b32_e32 v17, v19, v17, vcc
	s_waitcnt lgkmcnt(0)
	v_min_u32_e32 v19, v2, v14
	v_max_u32_e32 v2, v2, v14
	v_cndmask_b32_e32 v2, v2, v19, vcc
	s_waitcnt lgkmcnt(0)
	v_min_u32_e32 v14, v16, v18
	v_max_u32_e32 v16, v16, v18
	v_cndmask_b32_e32 v14, v14, v16, vcc
	v_min_u32_e32 v16, v1, v6
	ds_bpermute_b32 v18, v84, v16
	v_max_u32_e32 v1, v1, v6
	v_min_u32_e32 v6, v3, v7
	v_max_u32_e32 v3, v3, v7
	v_min_u32_e32 v7, v4, v9
	v_max_u32_e32 v4, v4, v9
	v_min_u32_e32 v9, v5, v11
	v_max_u32_e32 v5, v5, v11
	v_min_u32_e32 v11, v8, v13
	v_max_u32_e32 v8, v8, v13
	v_min_u32_e32 v13, v10, v15
	v_max_u32_e32 v10, v10, v15
	v_min_u32_e32 v15, v12, v17
	v_max_u32_e32 v12, v12, v17
	v_min_u32_e32 v17, v2, v14
	v_max_u32_e32 v2, v2, v14
	ds_bpermute_b32 v14, v84, v1
	s_waitcnt lgkmcnt(0)
	v_min_u32_e32 v19, v16, v18
	v_max_u32_e32 v16, v16, v18
	ds_bpermute_b32 v18, v84, v3
	v_cndmask_b32_e64 v16, v16, v19, s[8:9]
	s_waitcnt lgkmcnt(0)
	v_min_u32_e32 v19, v1, v14
	v_max_u32_e32 v1, v1, v14
	ds_bpermute_b32 v14, v84, v6
	v_cndmask_b32_e64 v1, v1, v19, s[8:9]
	s_waitcnt lgkmcnt(0)
	v_min_u32_e32 v19, v3, v18
	v_max_u32_e32 v3, v3, v18
	ds_bpermute_b32 v18, v84, v7
	v_cndmask_b32_e64 v3, v19, v3, s[8:9]
	s_waitcnt lgkmcnt(0)
	v_min_u32_e32 v19, v6, v14
	v_max_u32_e32 v6, v6, v14
	ds_bpermute_b32 v14, v84, v4
	v_cndmask_b32_e64 v6, v19, v6, s[8:9]
	s_waitcnt lgkmcnt(0)
	v_min_u32_e32 v19, v7, v18
	v_max_u32_e32 v7, v7, v18
	ds_bpermute_b32 v18, v84, v5
	v_cndmask_b32_e64 v7, v7, v19, s[8:9]
	s_waitcnt lgkmcnt(0)
	v_min_u32_e32 v19, v4, v14
	v_max_u32_e32 v4, v4, v14
	ds_bpermute_b32 v14, v84, v9
	v_cndmask_b32_e64 v4, v4, v19, s[8:9]
	s_waitcnt lgkmcnt(0)
	v_min_u32_e32 v19, v5, v18
	v_max_u32_e32 v5, v5, v18
	ds_bpermute_b32 v18, v84, v11
	v_cndmask_b32_e64 v5, v19, v5, s[8:9]
	s_waitcnt lgkmcnt(0)
	v_min_u32_e32 v19, v9, v14
	v_max_u32_e32 v9, v9, v14
	ds_bpermute_b32 v14, v84, v8
	v_cndmask_b32_e64 v9, v19, v9, s[8:9]
	s_waitcnt lgkmcnt(0)
	v_min_u32_e32 v19, v11, v18
	v_max_u32_e32 v11, v11, v18
	ds_bpermute_b32 v18, v84, v10
	v_cndmask_b32_e64 v11, v11, v19, s[8:9]
	s_waitcnt lgkmcnt(0)
	v_min_u32_e32 v19, v8, v14
	v_max_u32_e32 v8, v8, v14
	ds_bpermute_b32 v14, v84, v13
	v_cndmask_b32_e64 v8, v8, v19, s[8:9]
	s_waitcnt lgkmcnt(0)
	v_min_u32_e32 v19, v10, v18
	v_max_u32_e32 v10, v10, v18
	ds_bpermute_b32 v18, v84, v15
	v_cndmask_b32_e64 v10, v19, v10, s[8:9]
	s_waitcnt lgkmcnt(0)
	v_min_u32_e32 v19, v13, v14
	v_max_u32_e32 v13, v13, v14
	ds_bpermute_b32 v14, v84, v12
	v_cndmask_b32_e64 v13, v19, v13, s[8:9]
	s_waitcnt lgkmcnt(0)
	v_min_u32_e32 v19, v15, v18
	v_max_u32_e32 v15, v15, v18
	ds_bpermute_b32 v18, v84, v2
	v_cndmask_b32_e64 v15, v15, v19, s[8:9]
	s_waitcnt lgkmcnt(0)
	v_min_u32_e32 v19, v12, v14
	v_max_u32_e32 v12, v12, v14
	ds_bpermute_b32 v14, v84, v17
	v_cndmask_b32_e64 v12, v12, v19, s[8:9]
	s_waitcnt lgkmcnt(0)
	v_min_u32_e32 v19, v2, v18
	v_max_u32_e32 v2, v2, v18
	ds_bpermute_b32 v18, v83, v16
	v_cndmask_b32_e64 v2, v19, v2, s[8:9]
	s_waitcnt lgkmcnt(0)
	v_min_u32_e32 v19, v17, v14
	v_max_u32_e32 v14, v17, v14
	ds_bpermute_b32 v17, v83, v1
	v_cndmask_b32_e64 v14, v19, v14, s[8:9]
	s_waitcnt lgkmcnt(0)
	v_min_u32_e32 v19, v16, v18
	v_max_u32_e32 v16, v16, v18
	ds_bpermute_b32 v18, v83, v3
	v_cndmask_b32_e64 v16, v16, v19, s[6:7]
	s_waitcnt lgkmcnt(0)
	v_min_u32_e32 v19, v1, v17
	v_max_u32_e32 v1, v1, v17
	ds_bpermute_b32 v17, v83, v6
	v_cndmask_b32_e64 v1, v1, v19, s[6:7]
	s_waitcnt lgkmcnt(0)
	v_min_u32_e32 v19, v3, v18
	v_max_u32_e32 v3, v3, v18
	ds_bpermute_b32 v18, v83, v7
	v_cndmask_b32_e64 v3, v19, v3, s[6:7]
	s_waitcnt lgkmcnt(0)
	v_min_u32_e32 v19, v6, v17
	v_max_u32_e32 v6, v6, v17
	ds_bpermute_b32 v17, v83, v4
	v_cndmask_b32_e64 v6, v19, v6, s[6:7]
	s_waitcnt lgkmcnt(0)
	v_min_u32_e32 v19, v7, v18
	v_max_u32_e32 v7, v7, v18
	ds_bpermute_b32 v18, v83, v5
	v_cndmask_b32_e64 v7, v7, v19, s[6:7]
	s_waitcnt lgkmcnt(0)
	v_min_u32_e32 v19, v4, v17
	v_max_u32_e32 v4, v4, v17
	ds_bpermute_b32 v17, v83, v9
	v_cndmask_b32_e64 v4, v4, v19, s[6:7]
	s_waitcnt lgkmcnt(0)
	v_min_u32_e32 v19, v5, v18
	v_max_u32_e32 v5, v5, v18
	ds_bpermute_b32 v18, v83, v11
	v_cndmask_b32_e64 v5, v19, v5, s[6:7]
	s_waitcnt lgkmcnt(0)
	v_min_u32_e32 v19, v9, v17
	v_max_u32_e32 v9, v9, v17
	ds_bpermute_b32 v17, v83, v8
	v_cndmask_b32_e64 v9, v19, v9, s[6:7]
	s_waitcnt lgkmcnt(0)
	v_min_u32_e32 v19, v11, v18
	v_max_u32_e32 v11, v11, v18
	ds_bpermute_b32 v18, v83, v10
	v_cndmask_b32_e64 v11, v11, v19, s[6:7]
	s_waitcnt lgkmcnt(0)
	v_min_u32_e32 v19, v8, v17
	v_max_u32_e32 v8, v8, v17
	ds_bpermute_b32 v17, v83, v13
	v_cndmask_b32_e64 v8, v8, v19, s[6:7]
	s_waitcnt lgkmcnt(0)
	v_min_u32_e32 v19, v10, v18
	v_max_u32_e32 v10, v10, v18
	ds_bpermute_b32 v18, v83, v15
	v_cndmask_b32_e64 v10, v19, v10, s[6:7]
	s_waitcnt lgkmcnt(0)
	v_min_u32_e32 v19, v13, v17
	v_max_u32_e32 v13, v13, v17
	ds_bpermute_b32 v17, v83, v12
	v_cndmask_b32_e64 v13, v19, v13, s[6:7]
	s_waitcnt lgkmcnt(0)
	v_min_u32_e32 v19, v15, v18
	v_max_u32_e32 v15, v15, v18
	ds_bpermute_b32 v18, v83, v2
	v_cndmask_b32_e64 v15, v15, v19, s[6:7]
	s_waitcnt lgkmcnt(0)
	v_min_u32_e32 v19, v12, v17
	v_max_u32_e32 v12, v12, v17
	ds_bpermute_b32 v17, v83, v14
	v_cndmask_b32_e64 v12, v12, v19, s[6:7]
	s_waitcnt lgkmcnt(0)
	v_min_u32_e32 v19, v2, v18
	v_max_u32_e32 v2, v2, v18
	s_nop 1
	v_mov_b32_dpp v18, v16 row_ror:8 row_mask:0xf bank_mask:0xf
	v_cndmask_b32_e64 v2, v19, v2, s[6:7]
	s_waitcnt lgkmcnt(0)
	v_min_u32_e32 v19, v14, v17
	v_max_u32_e32 v14, v14, v17
	s_nop 1
	v_mov_b32_dpp v17, v1 row_ror:8 row_mask:0xf bank_mask:0xf
	v_cndmask_b32_e64 v14, v19, v14, s[6:7]
	s_waitcnt lgkmcnt(0)
	v_min_u32_e32 v19, v16, v18
	v_max_u32_e32 v16, v16, v18
	s_nop 1
	v_mov_b32_dpp v18, v3 row_ror:8 row_mask:0xf bank_mask:0xf
	v_cndmask_b32_e64 v16, v16, v19, s[4:5]
	s_waitcnt lgkmcnt(0)
	v_min_u32_e32 v19, v1, v17
	v_max_u32_e32 v1, v1, v17
	s_nop 1
	v_mov_b32_dpp v17, v6 row_ror:8 row_mask:0xf bank_mask:0xf
	v_cndmask_b32_e64 v1, v1, v19, s[4:5]
	s_waitcnt lgkmcnt(0)
	v_min_u32_e32 v19, v3, v18
	v_max_u32_e32 v3, v3, v18
	s_nop 1
	v_mov_b32_dpp v18, v7 row_ror:8 row_mask:0xf bank_mask:0xf
	v_cndmask_b32_e64 v3, v19, v3, s[4:5]
	s_waitcnt lgkmcnt(0)
	v_min_u32_e32 v19, v6, v17
	v_max_u32_e32 v6, v6, v17
	s_nop 1
	v_mov_b32_dpp v17, v4 row_ror:8 row_mask:0xf bank_mask:0xf
	v_cndmask_b32_e64 v6, v19, v6, s[4:5]
	s_waitcnt lgkmcnt(0)
	v_min_u32_e32 v19, v7, v18
	v_max_u32_e32 v7, v7, v18
	s_nop 1
	v_mov_b32_dpp v18, v5 row_ror:8 row_mask:0xf bank_mask:0xf
	v_cndmask_b32_e64 v7, v7, v19, s[4:5]
	s_waitcnt lgkmcnt(0)
	v_min_u32_e32 v19, v4, v17
	v_max_u32_e32 v4, v4, v17
	s_nop 1
	v_mov_b32_dpp v17, v9 row_ror:8 row_mask:0xf bank_mask:0xf
	v_cndmask_b32_e64 v4, v4, v19, s[4:5]
	s_waitcnt lgkmcnt(0)
	v_min_u32_e32 v19, v5, v18
	v_max_u32_e32 v5, v5, v18
	s_nop 1
	v_mov_b32_dpp v18, v11 row_ror:8 row_mask:0xf bank_mask:0xf
	v_cndmask_b32_e64 v5, v19, v5, s[4:5]
	s_waitcnt lgkmcnt(0)
	v_min_u32_e32 v19, v9, v17
	v_max_u32_e32 v9, v9, v17
	s_nop 1
	v_mov_b32_dpp v17, v8 row_ror:8 row_mask:0xf bank_mask:0xf
	v_cndmask_b32_e64 v9, v19, v9, s[4:5]
	s_waitcnt lgkmcnt(0)
	v_min_u32_e32 v19, v11, v18
	v_max_u32_e32 v11, v11, v18
	s_nop 1
	v_mov_b32_dpp v18, v10 row_ror:8 row_mask:0xf bank_mask:0xf
	v_cndmask_b32_e64 v11, v11, v19, s[4:5]
	s_waitcnt lgkmcnt(0)
	v_min_u32_e32 v19, v8, v17
	v_max_u32_e32 v8, v8, v17
	s_nop 1
	v_mov_b32_dpp v17, v13 row_ror:8 row_mask:0xf bank_mask:0xf
	v_cndmask_b32_e64 v8, v8, v19, s[4:5]
	s_waitcnt lgkmcnt(0)
	v_min_u32_e32 v19, v10, v18
	v_max_u32_e32 v10, v10, v18
	s_nop 1
	v_mov_b32_dpp v18, v15 row_ror:8 row_mask:0xf bank_mask:0xf
	v_cndmask_b32_e64 v10, v19, v10, s[4:5]
	s_waitcnt lgkmcnt(0)
	v_min_u32_e32 v19, v13, v17
	v_max_u32_e32 v13, v13, v17
	s_nop 1
	v_mov_b32_dpp v17, v12 row_ror:8 row_mask:0xf bank_mask:0xf
	v_cndmask_b32_e64 v13, v19, v13, s[4:5]
	s_waitcnt lgkmcnt(0)
	v_min_u32_e32 v19, v15, v18
	v_max_u32_e32 v15, v15, v18
	s_nop 1
	v_mov_b32_dpp v18, v2 row_ror:8 row_mask:0xf bank_mask:0xf
	v_cndmask_b32_e64 v15, v15, v19, s[4:5]
	s_waitcnt lgkmcnt(0)
	v_min_u32_e32 v19, v12, v17
	v_max_u32_e32 v12, v12, v17
	s_nop 1
	v_mov_b32_dpp v17, v14 row_ror:8 row_mask:0xf bank_mask:0xf
	v_cndmask_b32_e64 v12, v12, v19, s[4:5]
	s_waitcnt lgkmcnt(0)
	v_min_u32_e32 v19, v2, v18
	v_max_u32_e32 v2, v2, v18
	s_nop 1
	v_mov_b32_dpp v18, v16 row_shl:4 row_mask:0xf bank_mask:0x5
	v_mov_b32_dpp v18, v16 row_shr:4 row_mask:0xf bank_mask:0xa
	v_cndmask_b32_e64 v2, v19, v2, s[4:5]
	s_waitcnt lgkmcnt(0)
	v_min_u32_e32 v19, v14, v17
	v_max_u32_e32 v14, v14, v17
	s_nop 1
	v_mov_b32_dpp v17, v1 row_shl:4 row_mask:0xf bank_mask:0x5
	v_mov_b32_dpp v17, v1 row_shr:4 row_mask:0xf bank_mask:0xa
	v_cndmask_b32_e64 v14, v19, v14, s[4:5]
	s_waitcnt lgkmcnt(0)
	v_min_u32_e32 v19, v16, v18
	v_max_u32_e32 v16, v16, v18
	s_nop 1
	v_mov_b32_dpp v18, v3 row_shl:4 row_mask:0xf bank_mask:0x5
	v_mov_b32_dpp v18, v3 row_shr:4 row_mask:0xf bank_mask:0xa
	v_cndmask_b32_e64 v16, v16, v19, s[2:3]
	s_waitcnt lgkmcnt(0)
	v_min_u32_e32 v19, v1, v17
	v_max_u32_e32 v1, v1, v17
	s_nop 1
	v_mov_b32_dpp v17, v6 row_shl:4 row_mask:0xf bank_mask:0x5
	v_mov_b32_dpp v17, v6 row_shr:4 row_mask:0xf bank_mask:0xa
	v_cndmask_b32_e64 v1, v1, v19, s[2:3]
	s_waitcnt lgkmcnt(0)
	v_min_u32_e32 v19, v3, v18
	v_max_u32_e32 v3, v3, v18
	s_nop 1
	v_mov_b32_dpp v18, v7 row_shl:4 row_mask:0xf bank_mask:0x5
	v_mov_b32_dpp v18, v7 row_shr:4 row_mask:0xf bank_mask:0xa
	v_cndmask_b32_e64 v3, v19, v3, s[2:3]
	s_waitcnt lgkmcnt(0)
	v_min_u32_e32 v19, v6, v17
	v_max_u32_e32 v6, v6, v17
	s_nop 1
	v_mov_b32_dpp v17, v4 row_shl:4 row_mask:0xf bank_mask:0x5
	v_mov_b32_dpp v17, v4 row_shr:4 row_mask:0xf bank_mask:0xa
	v_cndmask_b32_e64 v6, v19, v6, s[2:3]
	s_waitcnt lgkmcnt(0)
	v_min_u32_e32 v19, v7, v18
	v_max_u32_e32 v7, v7, v18
	s_nop 1
	v_mov_b32_dpp v18, v5 row_shl:4 row_mask:0xf bank_mask:0x5
	v_mov_b32_dpp v18, v5 row_shr:4 row_mask:0xf bank_mask:0xa
	v_cndmask_b32_e64 v7, v7, v19, s[2:3]
	s_waitcnt lgkmcnt(0)
	v_min_u32_e32 v19, v4, v17
	v_max_u32_e32 v4, v4, v17
	s_nop 1
	v_mov_b32_dpp v17, v9 row_shl:4 row_mask:0xf bank_mask:0x5
	v_mov_b32_dpp v17, v9 row_shr:4 row_mask:0xf bank_mask:0xa
	v_cndmask_b32_e64 v4, v4, v19, s[2:3]
	s_waitcnt lgkmcnt(0)
	v_min_u32_e32 v19, v5, v18
	v_max_u32_e32 v5, v5, v18
	s_nop 1
	v_mov_b32_dpp v18, v11 row_shl:4 row_mask:0xf bank_mask:0x5
	v_mov_b32_dpp v18, v11 row_shr:4 row_mask:0xf bank_mask:0xa
	v_cndmask_b32_e64 v5, v19, v5, s[2:3]
	s_waitcnt lgkmcnt(0)
	v_min_u32_e32 v19, v9, v17
	v_max_u32_e32 v9, v9, v17
	s_nop 1
	v_mov_b32_dpp v17, v8 row_shl:4 row_mask:0xf bank_mask:0x5
	v_mov_b32_dpp v17, v8 row_shr:4 row_mask:0xf bank_mask:0xa
	v_cndmask_b32_e64 v9, v19, v9, s[2:3]
	s_waitcnt lgkmcnt(0)
	v_min_u32_e32 v19, v11, v18
	v_max_u32_e32 v11, v11, v18
	s_nop 1
	v_mov_b32_dpp v18, v10 row_shl:4 row_mask:0xf bank_mask:0x5
	v_mov_b32_dpp v18, v10 row_shr:4 row_mask:0xf bank_mask:0xa
	v_cndmask_b32_e64 v11, v11, v19, s[2:3]
	s_waitcnt lgkmcnt(0)
	v_min_u32_e32 v19, v8, v17
	v_max_u32_e32 v8, v8, v17
	s_nop 1
	v_mov_b32_dpp v17, v13 row_shl:4 row_mask:0xf bank_mask:0x5
	v_mov_b32_dpp v17, v13 row_shr:4 row_mask:0xf bank_mask:0xa
	v_cndmask_b32_e64 v8, v8, v19, s[2:3]
	s_waitcnt lgkmcnt(0)
	v_min_u32_e32 v19, v10, v18
	v_max_u32_e32 v10, v10, v18
	s_nop 1
	v_mov_b32_dpp v18, v15 row_shl:4 row_mask:0xf bank_mask:0x5
	v_mov_b32_dpp v18, v15 row_shr:4 row_mask:0xf bank_mask:0xa
	v_cndmask_b32_e64 v10, v19, v10, s[2:3]
	s_waitcnt lgkmcnt(0)
	v_min_u32_e32 v19, v13, v17
	v_max_u32_e32 v13, v13, v17
	s_nop 1
	v_mov_b32_dpp v17, v12 row_shl:4 row_mask:0xf bank_mask:0x5
	v_mov_b32_dpp v17, v12 row_shr:4 row_mask:0xf bank_mask:0xa
	v_cndmask_b32_e64 v13, v19, v13, s[2:3]
	s_waitcnt lgkmcnt(0)
	v_min_u32_e32 v19, v15, v18
	v_max_u32_e32 v15, v15, v18
	s_nop 1
	v_mov_b32_dpp v18, v2 row_shl:4 row_mask:0xf bank_mask:0x5
	v_mov_b32_dpp v18, v2 row_shr:4 row_mask:0xf bank_mask:0xa
	v_cndmask_b32_e64 v15, v15, v19, s[2:3]
	s_waitcnt lgkmcnt(0)
	v_min_u32_e32 v19, v12, v17
	v_max_u32_e32 v12, v12, v17
	s_nop 1
	v_mov_b32_dpp v17, v14 row_shl:4 row_mask:0xf bank_mask:0x5
	v_mov_b32_dpp v17, v14 row_shr:4 row_mask:0xf bank_mask:0xa
	v_cndmask_b32_e64 v12, v12, v19, s[2:3]
	s_waitcnt lgkmcnt(0)
	v_min_u32_e32 v19, v2, v18
	v_max_u32_e32 v2, v2, v18
	s_nop 1
	v_mov_b32_dpp v18, v16 quad_perm:[2,3,0,1] row_mask:0xf bank_mask:0xf
	v_cndmask_b32_e64 v2, v19, v2, s[2:3]
	s_waitcnt lgkmcnt(0)
	v_min_u32_e32 v19, v14, v17
	v_max_u32_e32 v14, v14, v17
	s_nop 1
	v_mov_b32_dpp v17, v1 quad_perm:[2,3,0,1] row_mask:0xf bank_mask:0xf
	v_cndmask_b32_e64 v14, v19, v14, s[2:3]
	s_waitcnt lgkmcnt(0)
	v_min_u32_e32 v19, v16, v18
	v_max_u32_e32 v16, v16, v18
	s_nop 1
	v_mov_b32_dpp v18, v3 quad_perm:[2,3,0,1] row_mask:0xf bank_mask:0xf
	v_cndmask_b32_e64 v16, v16, v19, s[0:1]
	s_waitcnt lgkmcnt(0)
	v_min_u32_e32 v19, v1, v17
	v_max_u32_e32 v1, v1, v17
	s_nop 1
	v_mov_b32_dpp v17, v6 quad_perm:[2,3,0,1] row_mask:0xf bank_mask:0xf
	v_cndmask_b32_e64 v1, v1, v19, s[0:1]
	s_waitcnt lgkmcnt(0)
	v_min_u32_e32 v19, v3, v18
	v_max_u32_e32 v3, v3, v18
	s_nop 1
	v_mov_b32_dpp v18, v7 quad_perm:[2,3,0,1] row_mask:0xf bank_mask:0xf
	v_cndmask_b32_e64 v3, v19, v3, s[0:1]
	s_waitcnt lgkmcnt(0)
	v_min_u32_e32 v19, v6, v17
	v_max_u32_e32 v6, v6, v17
	s_nop 1
	v_mov_b32_dpp v17, v4 quad_perm:[2,3,0,1] row_mask:0xf bank_mask:0xf
	v_cndmask_b32_e64 v6, v19, v6, s[0:1]
	s_waitcnt lgkmcnt(0)
	v_min_u32_e32 v19, v7, v18
	v_max_u32_e32 v7, v7, v18
	s_nop 1
	v_mov_b32_dpp v18, v5 quad_perm:[2,3,0,1] row_mask:0xf bank_mask:0xf
	v_cndmask_b32_e64 v7, v7, v19, s[0:1]
	s_waitcnt lgkmcnt(0)
	v_min_u32_e32 v19, v4, v17
	v_max_u32_e32 v4, v4, v17
	s_nop 1
	v_mov_b32_dpp v17, v9 quad_perm:[2,3,0,1] row_mask:0xf bank_mask:0xf
	v_cndmask_b32_e64 v4, v4, v19, s[0:1]
	s_waitcnt lgkmcnt(0)
	v_min_u32_e32 v19, v5, v18
	v_max_u32_e32 v5, v5, v18
	s_nop 1
	v_mov_b32_dpp v18, v11 quad_perm:[2,3,0,1] row_mask:0xf bank_mask:0xf
	v_cndmask_b32_e64 v5, v19, v5, s[0:1]
	s_waitcnt lgkmcnt(0)
	v_min_u32_e32 v19, v9, v17
	v_max_u32_e32 v9, v9, v17
	s_nop 1
	v_mov_b32_dpp v17, v8 quad_perm:[2,3,0,1] row_mask:0xf bank_mask:0xf
	v_cndmask_b32_e64 v9, v19, v9, s[0:1]
	s_waitcnt lgkmcnt(0)
	v_min_u32_e32 v19, v11, v18
	v_max_u32_e32 v11, v11, v18
	s_nop 1
	v_mov_b32_dpp v18, v10 quad_perm:[2,3,0,1] row_mask:0xf bank_mask:0xf
	v_cndmask_b32_e64 v11, v11, v19, s[0:1]
	s_waitcnt lgkmcnt(0)
	v_min_u32_e32 v19, v8, v17
	v_max_u32_e32 v8, v8, v17
	s_nop 1
	v_mov_b32_dpp v17, v13 quad_perm:[2,3,0,1] row_mask:0xf bank_mask:0xf
	v_cndmask_b32_e64 v8, v8, v19, s[0:1]
	s_waitcnt lgkmcnt(0)
	v_min_u32_e32 v19, v10, v18
	v_max_u32_e32 v10, v10, v18
	s_nop 1
	v_mov_b32_dpp v18, v15 quad_perm:[2,3,0,1] row_mask:0xf bank_mask:0xf
	v_cndmask_b32_e64 v10, v19, v10, s[0:1]
	s_waitcnt lgkmcnt(0)
	v_min_u32_e32 v19, v13, v17
	v_max_u32_e32 v13, v13, v17
	s_nop 1
	v_mov_b32_dpp v17, v12 quad_perm:[2,3,0,1] row_mask:0xf bank_mask:0xf
	v_cndmask_b32_e64 v13, v19, v13, s[0:1]
	s_waitcnt lgkmcnt(0)
	v_min_u32_e32 v19, v15, v18
	v_max_u32_e32 v15, v15, v18
	s_nop 1
	v_mov_b32_dpp v18, v2 quad_perm:[2,3,0,1] row_mask:0xf bank_mask:0xf
	v_cndmask_b32_e64 v15, v15, v19, s[0:1]
	s_waitcnt lgkmcnt(0)
	v_min_u32_e32 v19, v12, v17
	v_max_u32_e32 v12, v12, v17
	s_nop 1
	v_mov_b32_dpp v17, v14 quad_perm:[2,3,0,1] row_mask:0xf bank_mask:0xf
	v_cndmask_b32_e64 v12, v12, v19, s[0:1]
	s_waitcnt lgkmcnt(0)
	v_min_u32_e32 v19, v2, v18
	v_max_u32_e32 v2, v2, v18
	s_nop 1
	v_mov_b32_dpp v18, v16 quad_perm:[1,0,3,2] row_mask:0xf bank_mask:0xf
	v_cndmask_b32_e64 v2, v19, v2, s[0:1]
	s_waitcnt lgkmcnt(0)
	v_min_u32_e32 v19, v14, v17
	v_max_u32_e32 v14, v14, v17
	v_cndmask_b32_e64 v14, v19, v14, s[0:1]
	s_nop 1
	v_mov_b32_dpp v17, v1 quad_perm:[1,0,3,2] row_mask:0xf bank_mask:0xf
	s_waitcnt lgkmcnt(0)
	v_min_u32_e32 v19, v16, v18
	v_max_u32_e32 v16, v16, v18
	v_cndmask_b32_e32 v65, v16, v19, vcc
	s_nop 1
	v_mov_b32_dpp v16, v3 quad_perm:[1,0,3,2] row_mask:0xf bank_mask:0xf
	s_waitcnt lgkmcnt(0)
	v_min_u32_e32 v18, v1, v17
	v_max_u32_e32 v1, v1, v17
	v_cndmask_b32_e32 v66, v1, v18, vcc
	s_nop 1
	v_mov_b32_dpp v1, v6 quad_perm:[1,0,3,2] row_mask:0xf bank_mask:0xf
	s_waitcnt lgkmcnt(0)
	v_min_u32_e32 v17, v3, v16
	v_max_u32_e32 v3, v3, v16
	v_cndmask_b32_e32 v74, v17, v3, vcc
	s_nop 1
	v_mov_b32_dpp v3, v7 quad_perm:[1,0,3,2] row_mask:0xf bank_mask:0xf
	s_waitcnt lgkmcnt(0)
	v_min_u32_e32 v16, v6, v1
	v_max_u32_e32 v1, v6, v1
	v_cndmask_b32_e32 v1, v16, v1, vcc
	s_nop 1
	v_mov_b32_dpp v6, v4 quad_perm:[1,0,3,2] row_mask:0xf bank_mask:0xf
	s_waitcnt lgkmcnt(0)
	v_min_u32_e32 v16, v7, v3
	v_max_u32_e32 v3, v7, v3
	v_cndmask_b32_e32 v68, v3, v16, vcc
	s_nop 1
	v_mov_b32_dpp v3, v5 quad_perm:[1,0,3,2] row_mask:0xf bank_mask:0xf
	s_waitcnt lgkmcnt(0)
	v_min_u32_e32 v7, v4, v6
	v_max_u32_e32 v4, v4, v6
	v_cndmask_b32_e32 v67, v4, v7, vcc
	s_nop 1
	v_mov_b32_dpp v4, v9 quad_perm:[1,0,3,2] row_mask:0xf bank_mask:0xf
	s_waitcnt lgkmcnt(0)
	v_min_u32_e32 v6, v5, v3
	v_max_u32_e32 v3, v5, v3
	v_cndmask_b32_e32 v75, v6, v3, vcc
	s_nop 1
	v_mov_b32_dpp v3, v11 quad_perm:[1,0,3,2] row_mask:0xf bank_mask:0xf
	s_waitcnt lgkmcnt(0)
	v_min_u32_e32 v5, v9, v4
	v_max_u32_e32 v4, v9, v4
	v_cndmask_b32_e32 v4, v5, v4, vcc
	s_nop 1
	v_mov_b32_dpp v5, v8 quad_perm:[1,0,3,2] row_mask:0xf bank_mask:0xf
	s_waitcnt lgkmcnt(0)
	v_min_u32_e32 v6, v11, v3
	v_max_u32_e32 v3, v11, v3
	v_cndmask_b32_e32 v70, v3, v6, vcc
	s_nop 1
	v_mov_b32_dpp v3, v10 quad_perm:[1,0,3,2] row_mask:0xf bank_mask:0xf
	s_waitcnt lgkmcnt(0)
	v_min_u32_e32 v6, v8, v5
	v_max_u32_e32 v5, v8, v5
	v_cndmask_b32_e32 v69, v5, v6, vcc
	s_nop 1
	v_mov_b32_dpp v5, v13 quad_perm:[1,0,3,2] row_mask:0xf bank_mask:0xf
	s_waitcnt lgkmcnt(0)
	v_min_u32_e32 v6, v10, v3
	v_max_u32_e32 v3, v10, v3
	v_cndmask_b32_e32 v76, v6, v3, vcc
	s_nop 1
	v_mov_b32_dpp v3, v15 quad_perm:[1,0,3,2] row_mask:0xf bank_mask:0xf
	s_waitcnt lgkmcnt(0)
	v_min_u32_e32 v6, v13, v5
	v_max_u32_e32 v5, v13, v5
	v_cndmask_b32_e32 v5, v6, v5, vcc
	s_nop 1
	v_mov_b32_dpp v6, v12 quad_perm:[1,0,3,2] row_mask:0xf bank_mask:0xf
	s_waitcnt lgkmcnt(0)
	v_min_u32_e32 v7, v15, v3
	v_max_u32_e32 v3, v15, v3
	v_cndmask_b32_e32 v71, v3, v7, vcc
	s_nop 1
	v_mov_b32_dpp v3, v2 quad_perm:[1,0,3,2] row_mask:0xf bank_mask:0xf
	s_nop 1
	v_mov_b32_dpp v8, v14 quad_perm:[1,0,3,2] row_mask:0xf bank_mask:0xf
	s_waitcnt lgkmcnt(0)
	v_min_u32_e32 v7, v12, v6
	v_max_u32_e32 v6, v12, v6
	v_cndmask_b32_e32 v72, v6, v7, vcc
	s_waitcnt lgkmcnt(0)
	v_min_u32_e32 v6, v2, v3
	v_max_u32_e32 v2, v2, v3
	v_cndmask_b32_e32 v2, v6, v2, vcc
	s_waitcnt lgkmcnt(0)
	v_min_u32_e32 v3, v14, v8
	v_max_u32_e32 v6, v14, v8
	v_cndmask_b32_e32 v77, v3, v6, vcc
	v_lshrrev_b32_e32 v0, 3, v1
	v_and_b32_e32 v3, 0x7f, v1
	v_and_or_b32 v0, v0, s10, v3
	ds_bpermute_b32 v85, v73, v0
	v_lshrrev_b32_e32 v0, 3, v4
	v_and_b32_e32 v3, 0x7f, v4
	v_and_or_b32 v0, v0, s10, v3
	ds_bpermute_b32 v86, v73, v0
	v_lshrrev_b32_e32 v0, 3, v5
	v_and_b32_e32 v3, 0x7f, v5
	v_and_or_b32 v0, v0, s10, v3
	ds_bpermute_b32 v87, v73, v0
	v_lshrrev_b32_e32 v0, 3, v2
	v_and_b32_e32 v3, 0x7f, v2
	v_and_or_b32 v0, v0, s10, v3
	ds_bpermute_b32 v88, v73, v0
	v_min_u32_e32 v0, v65, v74
	v_min_u32_e32 v6, v66, v1
	v_min_u32_e32 v16, v0, v6
	v_max_u32_e32 v3, v65, v74
	v_max_u32_e32 v1, v66, v1
	v_min_u32_e32 v7, v68, v75
	v_max_u32_e32 v8, v68, v75
	v_min_u32_e32 v9, v67, v4
	v_max_u32_e32 v4, v67, v4
	v_min_u32_e32 v10, v70, v76
	v_max_u32_e32 v11, v70, v76
	v_min_u32_e32 v12, v69, v5
	v_max_u32_e32 v5, v69, v5
	v_min_u32_e32 v13, v71, v2
	v_max_u32_e32 v2, v71, v2
	v_min_u32_e32 v14, v72, v77
	v_max_u32_e32 v15, v72, v77
	v_max_u32_e32 v0, v0, v6
	ds_bpermute_b32 v17, v84, v16
	v_min_u32_e32 v6, v3, v1
	v_max_u32_e32 v1, v3, v1
	v_min_u32_e32 v3, v8, v4
	v_max_u32_e32 v4, v8, v4
	v_min_u32_e32 v8, v7, v9
	v_max_u32_e32 v7, v7, v9
	v_min_u32_e32 v9, v10, v12
	v_max_u32_e32 v10, v10, v12
	v_min_u32_e32 v12, v11, v5
	v_max_u32_e32 v5, v11, v5
	v_min_u32_e32 v11, v2, v15
	v_max_u32_e32 v2, v2, v15
	v_min_u32_e32 v15, v13, v14
	v_max_u32_e32 v13, v13, v14
	ds_bpermute_b32 v14, v84, v0
	s_waitcnt lgkmcnt(0)
	v_min_u32_e32 v18, v16, v17
	v_max_u32_e32 v16, v16, v17
	ds_bpermute_b32 v17, v84, v6
	v_cndmask_b32_e64 v16, v16, v18, s[8:9]
	s_waitcnt lgkmcnt(0)
	v_min_u32_e32 v18, v0, v14
	v_max_u32_e32 v0, v0, v14
	ds_bpermute_b32 v14, v84, v1
	v_cndmask_b32_e64 v0, v0, v18, s[8:9]
	s_waitcnt lgkmcnt(0)
	v_min_u32_e32 v18, v6, v17
	v_max_u32_e32 v6, v6, v17
	ds_bpermute_b32 v17, v84, v4
	v_cndmask_b32_e64 v6, v6, v18, s[8:9]
	s_waitcnt lgkmcnt(0)
	v_min_u32_e32 v18, v1, v14
	v_max_u32_e32 v1, v1, v14
	ds_bpermute_b32 v14, v84, v3
	v_cndmask_b32_e64 v1, v1, v18, s[8:9]
	s_waitcnt lgkmcnt(0)
	v_min_u32_e32 v18, v4, v17
	v_max_u32_e32 v4, v4, v17
	ds_bpermute_b32 v17, v84, v7
	v_cndmask_b32_e64 v4, v18, v4, s[8:9]
	s_waitcnt lgkmcnt(0)
	v_min_u32_e32 v18, v3, v14
	v_max_u32_e32 v3, v3, v14
	ds_bpermute_b32 v14, v84, v8
	v_cndmask_b32_e64 v3, v18, v3, s[8:9]
	s_waitcnt lgkmcnt(0)
	v_min_u32_e32 v18, v7, v17
	v_max_u32_e32 v7, v7, v17
	ds_bpermute_b32 v17, v84, v9
	v_cndmask_b32_e64 v7, v18, v7, s[8:9]
	s_waitcnt lgkmcnt(0)
	v_min_u32_e32 v18, v8, v14
	v_max_u32_e32 v8, v8, v14
	ds_bpermute_b32 v14, v84, v10
	v_cndmask_b32_e64 v8, v18, v8, s[8:9]
	s_waitcnt lgkmcnt(0)
	v_min_u32_e32 v18, v9, v17
	v_max_u32_e32 v9, v9, v17
	ds_bpermute_b32 v17, v84, v12
	v_cndmask_b32_e64 v9, v9, v18, s[8:9]
	s_waitcnt lgkmcnt(0)
	v_min_u32_e32 v18, v10, v14
	v_max_u32_e32 v10, v10, v14
	ds_bpermute_b32 v14, v84, v5
	v_cndmask_b32_e64 v10, v10, v18, s[8:9]
	s_waitcnt lgkmcnt(0)
	v_min_u32_e32 v18, v12, v17
	v_max_u32_e32 v12, v12, v17
	ds_bpermute_b32 v17, v84, v2
	v_cndmask_b32_e64 v12, v12, v18, s[8:9]
	s_waitcnt lgkmcnt(0)
	v_min_u32_e32 v18, v5, v14
	v_max_u32_e32 v5, v5, v14
	ds_bpermute_b32 v14, v84, v11
	v_cndmask_b32_e64 v5, v5, v18, s[8:9]
	s_waitcnt lgkmcnt(0)
	v_min_u32_e32 v18, v2, v17
	v_max_u32_e32 v2, v2, v17
	ds_bpermute_b32 v17, v84, v13
	v_cndmask_b32_e64 v2, v18, v2, s[8:9]
	s_waitcnt lgkmcnt(0)
	v_min_u32_e32 v18, v11, v14
	v_max_u32_e32 v11, v11, v14
	ds_bpermute_b32 v14, v84, v15
	v_cndmask_b32_e64 v11, v18, v11, s[8:9]
	s_waitcnt lgkmcnt(0)
	v_min_u32_e32 v18, v13, v17
	v_max_u32_e32 v13, v13, v17
	ds_bpermute_b32 v17, v83, v16
	v_cndmask_b32_e64 v13, v18, v13, s[8:9]
	s_waitcnt lgkmcnt(0)
	v_min_u32_e32 v18, v15, v14
	v_max_u32_e32 v14, v15, v14
	ds_bpermute_b32 v15, v83, v0
	v_cndmask_b32_e64 v14, v18, v14, s[8:9]
	s_waitcnt lgkmcnt(0)
	v_min_u32_e32 v18, v16, v17
	v_max_u32_e32 v16, v16, v17
	ds_bpermute_b32 v17, v83, v6
	v_cndmask_b32_e64 v16, v16, v18, s[6:7]
	s_waitcnt lgkmcnt(0)
	v_min_u32_e32 v18, v0, v15
	v_max_u32_e32 v0, v0, v15
	ds_bpermute_b32 v15, v83, v1
	v_cndmask_b32_e64 v0, v0, v18, s[6:7]
	s_waitcnt lgkmcnt(0)
	v_min_u32_e32 v18, v6, v17
	v_max_u32_e32 v6, v6, v17
	ds_bpermute_b32 v17, v83, v4
	v_cndmask_b32_e64 v6, v6, v18, s[6:7]
	s_waitcnt lgkmcnt(0)
	v_min_u32_e32 v18, v1, v15
	v_max_u32_e32 v1, v1, v15
	ds_bpermute_b32 v15, v83, v3
	v_cndmask_b32_e64 v1, v1, v18, s[6:7]
	s_waitcnt lgkmcnt(0)
	v_min_u32_e32 v18, v4, v17
	v_max_u32_e32 v4, v4, v17
	ds_bpermute_b32 v17, v83, v7
	v_cndmask_b32_e64 v4, v18, v4, s[6:7]
	s_waitcnt lgkmcnt(0)
	v_min_u32_e32 v18, v3, v15
	v_max_u32_e32 v3, v3, v15
	ds_bpermute_b32 v15, v83, v8
	v_cndmask_b32_e64 v3, v18, v3, s[6:7]
	s_waitcnt lgkmcnt(0)
	v_min_u32_e32 v18, v7, v17
	v_max_u32_e32 v7, v7, v17
	ds_bpermute_b32 v17, v83, v9
	v_cndmask_b32_e64 v7, v18, v7, s[6:7]
	s_waitcnt lgkmcnt(0)
	v_min_u32_e32 v18, v8, v15
	v_max_u32_e32 v8, v8, v15
	ds_bpermute_b32 v15, v83, v10
	v_cndmask_b32_e64 v8, v18, v8, s[6:7]
	s_waitcnt lgkmcnt(0)
	v_min_u32_e32 v18, v9, v17
	v_max_u32_e32 v9, v9, v17
	ds_bpermute_b32 v17, v83, v12
	v_cndmask_b32_e64 v9, v9, v18, s[6:7]
	s_waitcnt lgkmcnt(0)
	v_min_u32_e32 v18, v10, v15
	v_max_u32_e32 v10, v10, v15
	ds_bpermute_b32 v15, v83, v5
	v_cndmask_b32_e64 v10, v10, v18, s[6:7]
	s_waitcnt lgkmcnt(0)
	v_min_u32_e32 v18, v12, v17
	v_max_u32_e32 v12, v12, v17
	ds_bpermute_b32 v17, v83, v2
	v_cndmask_b32_e64 v12, v12, v18, s[6:7]
	s_waitcnt lgkmcnt(0)
	v_min_u32_e32 v18, v5, v15
	v_max_u32_e32 v5, v5, v15
	ds_bpermute_b32 v15, v83, v11
	v_cndmask_b32_e64 v5, v5, v18, s[6:7]
	s_waitcnt lgkmcnt(0)
	v_min_u32_e32 v18, v2, v17
	v_max_u32_e32 v2, v2, v17
	ds_bpermute_b32 v17, v83, v13
	v_cndmask_b32_e64 v2, v18, v2, s[6:7]
	s_waitcnt lgkmcnt(0)
	v_min_u32_e32 v18, v11, v15
	v_max_u32_e32 v11, v11, v15
	ds_bpermute_b32 v15, v83, v14
	v_cndmask_b32_e64 v11, v18, v11, s[6:7]
	s_waitcnt lgkmcnt(0)
	v_min_u32_e32 v18, v13, v17
	v_max_u32_e32 v13, v13, v17
	s_nop 1
	v_mov_b32_dpp v17, v16 row_ror:8 row_mask:0xf bank_mask:0xf
	v_cndmask_b32_e64 v13, v18, v13, s[6:7]
	s_waitcnt lgkmcnt(0)
	v_min_u32_e32 v18, v14, v15
	v_max_u32_e32 v14, v14, v15
	s_nop 1
	v_mov_b32_dpp v15, v0 row_ror:8 row_mask:0xf bank_mask:0xf
	v_cndmask_b32_e64 v14, v18, v14, s[6:7]
	s_waitcnt lgkmcnt(0)
	v_min_u32_e32 v18, v16, v17
	v_max_u32_e32 v16, v16, v17
	s_nop 1
	v_mov_b32_dpp v17, v6 row_ror:8 row_mask:0xf bank_mask:0xf
	v_cndmask_b32_e64 v16, v16, v18, s[4:5]
	s_waitcnt lgkmcnt(0)
	v_min_u32_e32 v18, v0, v15
	v_max_u32_e32 v0, v0, v15
	s_nop 1
	v_mov_b32_dpp v15, v1 row_ror:8 row_mask:0xf bank_mask:0xf
	v_cndmask_b32_e64 v0, v0, v18, s[4:5]
	s_waitcnt lgkmcnt(0)
	v_min_u32_e32 v18, v6, v17
	v_max_u32_e32 v6, v6, v17
	s_nop 1
	v_mov_b32_dpp v17, v4 row_ror:8 row_mask:0xf bank_mask:0xf
	v_cndmask_b32_e64 v6, v6, v18, s[4:5]
	s_waitcnt lgkmcnt(0)
	v_min_u32_e32 v18, v1, v15
	v_max_u32_e32 v1, v1, v15
	s_nop 1
	v_mov_b32_dpp v15, v3 row_ror:8 row_mask:0xf bank_mask:0xf
	v_cndmask_b32_e64 v1, v1, v18, s[4:5]
	s_waitcnt lgkmcnt(0)
	v_min_u32_e32 v18, v4, v17
	v_max_u32_e32 v4, v4, v17
	s_nop 1
	v_mov_b32_dpp v17, v7 row_ror:8 row_mask:0xf bank_mask:0xf
	v_cndmask_b32_e64 v4, v18, v4, s[4:5]
	s_waitcnt lgkmcnt(0)
	v_min_u32_e32 v18, v3, v15
	v_max_u32_e32 v3, v3, v15
	s_nop 1
	v_mov_b32_dpp v15, v8 row_ror:8 row_mask:0xf bank_mask:0xf
	v_cndmask_b32_e64 v3, v18, v3, s[4:5]
	s_waitcnt lgkmcnt(0)
	v_min_u32_e32 v18, v7, v17
	v_max_u32_e32 v7, v7, v17
	s_nop 1
	v_mov_b32_dpp v17, v9 row_ror:8 row_mask:0xf bank_mask:0xf
	v_cndmask_b32_e64 v7, v18, v7, s[4:5]
	s_waitcnt lgkmcnt(0)
	v_min_u32_e32 v18, v8, v15
	v_max_u32_e32 v8, v8, v15
	s_nop 1
	v_mov_b32_dpp v15, v10 row_ror:8 row_mask:0xf bank_mask:0xf
	v_cndmask_b32_e64 v8, v18, v8, s[4:5]
	s_waitcnt lgkmcnt(0)
	v_min_u32_e32 v18, v9, v17
	v_max_u32_e32 v9, v9, v17
	s_nop 1
	v_mov_b32_dpp v17, v12 row_ror:8 row_mask:0xf bank_mask:0xf
	v_cndmask_b32_e64 v9, v9, v18, s[4:5]
	s_waitcnt lgkmcnt(0)
	v_min_u32_e32 v18, v10, v15
	v_max_u32_e32 v10, v10, v15
	s_nop 1
	v_mov_b32_dpp v15, v5 row_ror:8 row_mask:0xf bank_mask:0xf
	v_cndmask_b32_e64 v10, v10, v18, s[4:5]
	s_waitcnt lgkmcnt(0)
	v_min_u32_e32 v18, v12, v17
	v_max_u32_e32 v12, v12, v17
	s_nop 1
	v_mov_b32_dpp v17, v2 row_ror:8 row_mask:0xf bank_mask:0xf
	v_cndmask_b32_e64 v12, v12, v18, s[4:5]
	s_waitcnt lgkmcnt(0)
	v_min_u32_e32 v18, v5, v15
	v_max_u32_e32 v5, v5, v15
	s_nop 1
	v_mov_b32_dpp v15, v11 row_ror:8 row_mask:0xf bank_mask:0xf
	v_cndmask_b32_e64 v5, v5, v18, s[4:5]
	s_waitcnt lgkmcnt(0)
	v_min_u32_e32 v18, v2, v17
	v_max_u32_e32 v2, v2, v17
	s_nop 1
	v_mov_b32_dpp v17, v13 row_ror:8 row_mask:0xf bank_mask:0xf
	v_cndmask_b32_e64 v2, v18, v2, s[4:5]
	s_waitcnt lgkmcnt(0)
	v_min_u32_e32 v18, v11, v15
	v_max_u32_e32 v11, v11, v15
	s_nop 1
	v_mov_b32_dpp v15, v14 row_ror:8 row_mask:0xf bank_mask:0xf
	v_cndmask_b32_e64 v11, v18, v11, s[4:5]
	s_waitcnt lgkmcnt(0)
	v_min_u32_e32 v18, v13, v17
	v_max_u32_e32 v13, v13, v17
	s_nop 1
	v_mov_b32_dpp v17, v16 row_shl:4 row_mask:0xf bank_mask:0x5
	v_mov_b32_dpp v17, v16 row_shr:4 row_mask:0xf bank_mask:0xa
	v_cndmask_b32_e64 v13, v18, v13, s[4:5]
	s_waitcnt lgkmcnt(0)
	v_min_u32_e32 v18, v14, v15
	v_max_u32_e32 v14, v14, v15
	s_nop 1
	v_mov_b32_dpp v15, v0 row_shl:4 row_mask:0xf bank_mask:0x5
	v_mov_b32_dpp v15, v0 row_shr:4 row_mask:0xf bank_mask:0xa
	v_cndmask_b32_e64 v14, v18, v14, s[4:5]
	s_waitcnt lgkmcnt(0)
	v_min_u32_e32 v18, v16, v17
	v_max_u32_e32 v16, v16, v17
	s_nop 1
	v_mov_b32_dpp v17, v6 row_shl:4 row_mask:0xf bank_mask:0x5
	v_mov_b32_dpp v17, v6 row_shr:4 row_mask:0xf bank_mask:0xa
	v_cndmask_b32_e64 v16, v16, v18, s[2:3]
	s_waitcnt lgkmcnt(0)
	v_min_u32_e32 v18, v0, v15
	v_max_u32_e32 v0, v0, v15
	s_nop 1
	v_mov_b32_dpp v15, v1 row_shl:4 row_mask:0xf bank_mask:0x5
	v_mov_b32_dpp v15, v1 row_shr:4 row_mask:0xf bank_mask:0xa
	v_cndmask_b32_e64 v0, v0, v18, s[2:3]
	s_waitcnt lgkmcnt(0)
	v_min_u32_e32 v18, v6, v17
	v_max_u32_e32 v6, v6, v17
	s_nop 1
	v_mov_b32_dpp v17, v4 row_shl:4 row_mask:0xf bank_mask:0x5
	v_mov_b32_dpp v17, v4 row_shr:4 row_mask:0xf bank_mask:0xa
	v_cndmask_b32_e64 v6, v6, v18, s[2:3]
	s_waitcnt lgkmcnt(0)
	v_min_u32_e32 v18, v1, v15
	v_max_u32_e32 v1, v1, v15
	s_nop 1
	v_mov_b32_dpp v15, v3 row_shl:4 row_mask:0xf bank_mask:0x5
	v_mov_b32_dpp v15, v3 row_shr:4 row_mask:0xf bank_mask:0xa
	v_cndmask_b32_e64 v1, v1, v18, s[2:3]
	s_waitcnt lgkmcnt(0)
	v_min_u32_e32 v18, v4, v17
	v_max_u32_e32 v4, v4, v17
	s_nop 1
	v_mov_b32_dpp v17, v7 row_shl:4 row_mask:0xf bank_mask:0x5
	v_mov_b32_dpp v17, v7 row_shr:4 row_mask:0xf bank_mask:0xa
	v_cndmask_b32_e64 v4, v18, v4, s[2:3]
	s_waitcnt lgkmcnt(0)
	v_min_u32_e32 v18, v3, v15
	v_max_u32_e32 v3, v3, v15
	s_nop 1
	v_mov_b32_dpp v15, v8 row_shl:4 row_mask:0xf bank_mask:0x5
	v_mov_b32_dpp v15, v8 row_shr:4 row_mask:0xf bank_mask:0xa
	v_cndmask_b32_e64 v3, v18, v3, s[2:3]
	s_waitcnt lgkmcnt(0)
	v_min_u32_e32 v18, v7, v17
	v_max_u32_e32 v7, v7, v17
	s_nop 1
	v_mov_b32_dpp v17, v9 row_shl:4 row_mask:0xf bank_mask:0x5
	v_mov_b32_dpp v17, v9 row_shr:4 row_mask:0xf bank_mask:0xa
	v_cndmask_b32_e64 v7, v18, v7, s[2:3]
	s_waitcnt lgkmcnt(0)
	v_min_u32_e32 v18, v8, v15
	v_max_u32_e32 v8, v8, v15
	s_nop 1
	v_mov_b32_dpp v15, v10 row_shl:4 row_mask:0xf bank_mask:0x5
	v_mov_b32_dpp v15, v10 row_shr:4 row_mask:0xf bank_mask:0xa
	v_cndmask_b32_e64 v8, v18, v8, s[2:3]
	s_waitcnt lgkmcnt(0)
	v_min_u32_e32 v18, v9, v17
	v_max_u32_e32 v9, v9, v17
	s_nop 1
	v_mov_b32_dpp v17, v12 row_shl:4 row_mask:0xf bank_mask:0x5
	v_mov_b32_dpp v17, v12 row_shr:4 row_mask:0xf bank_mask:0xa
	v_cndmask_b32_e64 v9, v9, v18, s[2:3]
	s_waitcnt lgkmcnt(0)
	v_min_u32_e32 v18, v10, v15
	v_max_u32_e32 v10, v10, v15
	s_nop 1
	v_mov_b32_dpp v15, v5 row_shl:4 row_mask:0xf bank_mask:0x5
	v_mov_b32_dpp v15, v5 row_shr:4 row_mask:0xf bank_mask:0xa
	v_cndmask_b32_e64 v10, v10, v18, s[2:3]
	s_waitcnt lgkmcnt(0)
	v_min_u32_e32 v18, v12, v17
	v_max_u32_e32 v12, v12, v17
	s_nop 1
	v_mov_b32_dpp v17, v2 row_shl:4 row_mask:0xf bank_mask:0x5
	v_mov_b32_dpp v17, v2 row_shr:4 row_mask:0xf bank_mask:0xa
	v_cndmask_b32_e64 v12, v12, v18, s[2:3]
	s_waitcnt lgkmcnt(0)
	v_min_u32_e32 v18, v5, v15
	v_max_u32_e32 v5, v5, v15
	s_nop 1
	v_mov_b32_dpp v15, v11 row_shl:4 row_mask:0xf bank_mask:0x5
	v_mov_b32_dpp v15, v11 row_shr:4 row_mask:0xf bank_mask:0xa
	v_cndmask_b32_e64 v5, v5, v18, s[2:3]
	s_waitcnt lgkmcnt(0)
	v_min_u32_e32 v18, v2, v17
	v_max_u32_e32 v2, v2, v17
	s_nop 1
	v_mov_b32_dpp v17, v13 row_shl:4 row_mask:0xf bank_mask:0x5
	v_mov_b32_dpp v17, v13 row_shr:4 row_mask:0xf bank_mask:0xa
	v_cndmask_b32_e64 v2, v18, v2, s[2:3]
	s_waitcnt lgkmcnt(0)
	v_min_u32_e32 v18, v11, v15
	v_max_u32_e32 v11, v11, v15
	s_nop 1
	v_mov_b32_dpp v15, v14 row_shl:4 row_mask:0xf bank_mask:0x5
	v_mov_b32_dpp v15, v14 row_shr:4 row_mask:0xf bank_mask:0xa
	v_cndmask_b32_e64 v11, v18, v11, s[2:3]
	s_waitcnt lgkmcnt(0)
	v_min_u32_e32 v18, v13, v17
	v_max_u32_e32 v13, v13, v17
	s_nop 1
	v_mov_b32_dpp v17, v16 quad_perm:[2,3,0,1] row_mask:0xf bank_mask:0xf
	v_cndmask_b32_e64 v13, v18, v13, s[2:3]
	s_waitcnt lgkmcnt(0)
	v_min_u32_e32 v18, v14, v15
	v_max_u32_e32 v14, v14, v15
	s_nop 1
	v_mov_b32_dpp v15, v0 quad_perm:[2,3,0,1] row_mask:0xf bank_mask:0xf
	v_cndmask_b32_e64 v14, v18, v14, s[2:3]
	s_waitcnt lgkmcnt(0)
	v_min_u32_e32 v18, v16, v17
	v_max_u32_e32 v16, v16, v17
	s_nop 1
	v_mov_b32_dpp v17, v6 quad_perm:[2,3,0,1] row_mask:0xf bank_mask:0xf
	v_cndmask_b32_e64 v16, v16, v18, s[0:1]
	s_waitcnt lgkmcnt(0)
	v_min_u32_e32 v18, v0, v15
	v_max_u32_e32 v0, v0, v15
	s_nop 1
	v_mov_b32_dpp v15, v1 quad_perm:[2,3,0,1] row_mask:0xf bank_mask:0xf
	v_cndmask_b32_e64 v0, v0, v18, s[0:1]
	s_waitcnt lgkmcnt(0)
	v_min_u32_e32 v18, v6, v17
	v_max_u32_e32 v6, v6, v17
	s_nop 1
	v_mov_b32_dpp v17, v4 quad_perm:[2,3,0,1] row_mask:0xf bank_mask:0xf
	v_cndmask_b32_e64 v6, v6, v18, s[0:1]
	s_waitcnt lgkmcnt(0)
	v_min_u32_e32 v18, v1, v15
	v_max_u32_e32 v1, v1, v15
	s_nop 1
	v_mov_b32_dpp v15, v3 quad_perm:[2,3,0,1] row_mask:0xf bank_mask:0xf
	v_cndmask_b32_e64 v1, v1, v18, s[0:1]
	s_waitcnt lgkmcnt(0)
	v_min_u32_e32 v18, v4, v17
	v_max_u32_e32 v4, v4, v17
	s_nop 1
	v_mov_b32_dpp v17, v7 quad_perm:[2,3,0,1] row_mask:0xf bank_mask:0xf
	v_cndmask_b32_e64 v4, v18, v4, s[0:1]
	s_waitcnt lgkmcnt(0)
	v_min_u32_e32 v18, v3, v15
	v_max_u32_e32 v3, v3, v15
	s_nop 1
	v_mov_b32_dpp v15, v8 quad_perm:[2,3,0,1] row_mask:0xf bank_mask:0xf
	v_cndmask_b32_e64 v3, v18, v3, s[0:1]
	s_waitcnt lgkmcnt(0)
	v_min_u32_e32 v18, v7, v17
	v_max_u32_e32 v7, v7, v17
	s_nop 1
	v_mov_b32_dpp v17, v9 quad_perm:[2,3,0,1] row_mask:0xf bank_mask:0xf
	v_cndmask_b32_e64 v7, v18, v7, s[0:1]
	s_waitcnt lgkmcnt(0)
	v_min_u32_e32 v18, v8, v15
	v_max_u32_e32 v8, v8, v15
	s_nop 1
	v_mov_b32_dpp v15, v10 quad_perm:[2,3,0,1] row_mask:0xf bank_mask:0xf
	v_cndmask_b32_e64 v8, v18, v8, s[0:1]
	s_waitcnt lgkmcnt(0)
	v_min_u32_e32 v18, v9, v17
	v_max_u32_e32 v9, v9, v17
	s_nop 1
	v_mov_b32_dpp v17, v12 quad_perm:[2,3,0,1] row_mask:0xf bank_mask:0xf
	v_cndmask_b32_e64 v9, v9, v18, s[0:1]
	s_waitcnt lgkmcnt(0)
	v_min_u32_e32 v18, v10, v15
	v_max_u32_e32 v10, v10, v15
	s_nop 1
	v_mov_b32_dpp v15, v5 quad_perm:[2,3,0,1] row_mask:0xf bank_mask:0xf
	v_cndmask_b32_e64 v10, v10, v18, s[0:1]
	s_waitcnt lgkmcnt(0)
	v_min_u32_e32 v18, v12, v17
	v_max_u32_e32 v12, v12, v17
	s_nop 1
	v_mov_b32_dpp v17, v2 quad_perm:[2,3,0,1] row_mask:0xf bank_mask:0xf
	v_cndmask_b32_e64 v12, v12, v18, s[0:1]
	s_waitcnt lgkmcnt(0)
	v_min_u32_e32 v18, v5, v15
	v_max_u32_e32 v5, v5, v15
	s_nop 1
	v_mov_b32_dpp v15, v11 quad_perm:[2,3,0,1] row_mask:0xf bank_mask:0xf
	v_cndmask_b32_e64 v5, v5, v18, s[0:1]
	s_waitcnt lgkmcnt(0)
	v_min_u32_e32 v18, v2, v17
	v_max_u32_e32 v2, v2, v17
	s_nop 1
	v_mov_b32_dpp v17, v13 quad_perm:[2,3,0,1] row_mask:0xf bank_mask:0xf
	v_cndmask_b32_e64 v2, v18, v2, s[0:1]
	s_waitcnt lgkmcnt(0)
	v_min_u32_e32 v18, v11, v15
	v_max_u32_e32 v11, v11, v15
	s_nop 1
	v_mov_b32_dpp v15, v14 quad_perm:[2,3,0,1] row_mask:0xf bank_mask:0xf
	v_cndmask_b32_e64 v11, v18, v11, s[0:1]
	s_waitcnt lgkmcnt(0)
	v_min_u32_e32 v18, v13, v17
	v_max_u32_e32 v13, v13, v17
	s_nop 1
	v_mov_b32_dpp v17, v16 quad_perm:[1,0,3,2] row_mask:0xf bank_mask:0xf
	v_cndmask_b32_e64 v13, v18, v13, s[0:1]
	s_waitcnt lgkmcnt(0)
	v_min_u32_e32 v18, v14, v15
	v_max_u32_e32 v14, v14, v15
	s_nop 1
	v_mov_b32_dpp v15, v0 quad_perm:[1,0,3,2] row_mask:0xf bank_mask:0xf
	v_cndmask_b32_e64 v14, v18, v14, s[0:1]
	s_waitcnt lgkmcnt(0)
	v_min_u32_e32 v18, v16, v17
	v_max_u32_e32 v16, v16, v17
	s_nop 1
	v_mov_b32_dpp v17, v6 quad_perm:[1,0,3,2] row_mask:0xf bank_mask:0xf
	v_cndmask_b32_e32 v16, v16, v18, vcc
	s_waitcnt lgkmcnt(0)
	v_min_u32_e32 v18, v0, v15
	v_max_u32_e32 v0, v0, v15
	s_nop 1
	v_mov_b32_dpp v15, v1 quad_perm:[1,0,3,2] row_mask:0xf bank_mask:0xf
	v_cndmask_b32_e32 v0, v0, v18, vcc
	s_waitcnt lgkmcnt(0)
	v_min_u32_e32 v18, v6, v17
	v_max_u32_e32 v6, v6, v17
	s_nop 1
	v_mov_b32_dpp v17, v4 quad_perm:[1,0,3,2] row_mask:0xf bank_mask:0xf
	v_cndmask_b32_e32 v6, v6, v18, vcc
	s_waitcnt lgkmcnt(0)
	v_min_u32_e32 v18, v1, v15
	v_max_u32_e32 v1, v1, v15
	s_nop 1
	v_mov_b32_dpp v15, v3 quad_perm:[1,0,3,2] row_mask:0xf bank_mask:0xf
	v_cndmask_b32_e32 v1, v1, v18, vcc
	s_waitcnt lgkmcnt(0)
	v_min_u32_e32 v18, v4, v17
	v_max_u32_e32 v4, v4, v17
	s_nop 1
	v_mov_b32_dpp v17, v7 quad_perm:[1,0,3,2] row_mask:0xf bank_mask:0xf
	v_cndmask_b32_e32 v4, v18, v4, vcc
	s_waitcnt lgkmcnt(0)
	v_min_u32_e32 v18, v3, v15
	v_max_u32_e32 v3, v3, v15
	s_nop 1
	v_mov_b32_dpp v15, v8 quad_perm:[1,0,3,2] row_mask:0xf bank_mask:0xf
	v_cndmask_b32_e32 v3, v18, v3, vcc
	s_waitcnt lgkmcnt(0)
	v_min_u32_e32 v18, v7, v17
	v_max_u32_e32 v7, v7, v17
	s_nop 1
	v_mov_b32_dpp v17, v9 quad_perm:[1,0,3,2] row_mask:0xf bank_mask:0xf
	v_cndmask_b32_e32 v7, v18, v7, vcc
	s_waitcnt lgkmcnt(0)
	v_min_u32_e32 v18, v8, v15
	v_max_u32_e32 v8, v8, v15
	s_nop 1
	v_mov_b32_dpp v15, v10 quad_perm:[1,0,3,2] row_mask:0xf bank_mask:0xf
	v_cndmask_b32_e32 v8, v18, v8, vcc
	s_waitcnt lgkmcnt(0)
	v_min_u32_e32 v18, v9, v17
	v_max_u32_e32 v9, v9, v17
	s_nop 1
	v_mov_b32_dpp v17, v12 quad_perm:[1,0,3,2] row_mask:0xf bank_mask:0xf
	v_cndmask_b32_e32 v9, v9, v18, vcc
	s_waitcnt lgkmcnt(0)
	v_min_u32_e32 v18, v10, v15
	v_max_u32_e32 v10, v10, v15
	s_nop 1
	v_mov_b32_dpp v15, v5 quad_perm:[1,0,3,2] row_mask:0xf bank_mask:0xf
	v_cndmask_b32_e32 v10, v10, v18, vcc
	s_waitcnt lgkmcnt(0)
	v_min_u32_e32 v18, v12, v17
	v_max_u32_e32 v12, v12, v17
	s_nop 1
	v_mov_b32_dpp v17, v2 quad_perm:[1,0,3,2] row_mask:0xf bank_mask:0xf
	v_cndmask_b32_e32 v12, v12, v18, vcc
	s_waitcnt lgkmcnt(0)
	v_min_u32_e32 v18, v5, v15
	v_max_u32_e32 v5, v5, v15
	s_nop 1
	v_mov_b32_dpp v15, v11 quad_perm:[1,0,3,2] row_mask:0xf bank_mask:0xf
	v_cndmask_b32_e32 v5, v5, v18, vcc
	s_waitcnt lgkmcnt(0)
	v_min_u32_e32 v18, v2, v17
	v_max_u32_e32 v2, v2, v17
	v_cndmask_b32_e32 v2, v18, v2, vcc
	s_nop 1
	v_mov_b32_dpp v17, v13 quad_perm:[1,0,3,2] row_mask:0xf bank_mask:0xf
	s_waitcnt lgkmcnt(0)
	v_min_u32_e32 v18, v11, v15
	v_max_u32_e32 v11, v11, v15
	s_nop 1
	v_mov_b32_dpp v15, v14 quad_perm:[1,0,3,2] row_mask:0xf bank_mask:0xf
	v_cndmask_b32_e32 v11, v18, v11, vcc
	s_waitcnt lgkmcnt(0)
	v_min_u32_e32 v18, v13, v17
	v_max_u32_e32 v13, v13, v17
	v_cndmask_b32_e32 v13, v18, v13, vcc
	s_waitcnt lgkmcnt(0)
	v_min_u32_e32 v17, v14, v15
	v_max_u32_e32 v14, v14, v15
	v_cndmask_b32_e32 v14, v17, v14, vcc
	v_min_u32_e32 v15, v16, v4
	v_max_u32_e32 v4, v16, v4
	v_min_u32_e32 v16, v0, v3
	v_max_u32_e32 v0, v0, v3
	v_min_u32_e32 v3, v6, v7
	v_max_u32_e32 v6, v6, v7
	v_min_u32_e32 v7, v1, v8
	v_max_u32_e32 v1, v1, v8
	v_min_u32_e32 v8, v9, v2
	v_max_u32_e32 v2, v9, v2
	v_min_u32_e32 v9, v10, v11
	v_max_u32_e32 v10, v10, v11
	v_min_u32_e32 v11, v12, v13
	v_max_u32_e32 v12, v12, v13
	v_min_u32_e32 v13, v5, v14
	v_max_u32_e32 v5, v5, v14
	v_min_u32_e32 v14, v15, v3
	v_max_u32_e32 v3, v15, v3
	v_min_u32_e32 v15, v16, v7
	v_max_u32_e32 v7, v16, v7
	v_min_u32_e32 v16, v4, v6
	v_max_u32_e32 v4, v4, v6
	v_min_u32_e32 v6, v0, v1
	v_max_u32_e32 v0, v0, v1
	v_min_u32_e32 v1, v2, v12
	v_max_u32_e32 v2, v2, v12
	v_min_u32_e32 v12, v10, v5
	v_max_u32_e32 v5, v10, v5
	v_min_u32_e32 v10, v8, v11
	v_max_u32_e32 v8, v8, v11
	v_min_u32_e32 v11, v9, v13
	v_max_u32_e32 v9, v9, v13
	v_min_u32_e32 v13, v14, v15
	v_max_u32_e32 v14, v14, v15
	ds_bpermute_b32 v17, v84, v13
	v_min_u32_e32 v15, v3, v7
	v_max_u32_e32 v3, v3, v7
	v_min_u32_e32 v7, v16, v6
	v_max_u32_e32 v6, v16, v6
	v_min_u32_e32 v16, v4, v0
	v_max_u32_e32 v0, v4, v0
	v_min_u32_e32 v4, v2, v5
	v_max_u32_e32 v2, v2, v5
	v_min_u32_e32 v5, v1, v12
	v_max_u32_e32 v1, v1, v12
	v_min_u32_e32 v12, v8, v9
	v_max_u32_e32 v8, v8, v9
	v_min_u32_e32 v9, v10, v11
	v_max_u32_e32 v10, v10, v11
	ds_bpermute_b32 v11, v84, v14
	s_waitcnt lgkmcnt(0)
	v_min_u32_e32 v18, v13, v17
	v_max_u32_e32 v13, v13, v17
	ds_bpermute_b32 v17, v84, v15
	v_cndmask_b32_e64 v13, v13, v18, s[8:9]
	s_waitcnt lgkmcnt(0)
	v_min_u32_e32 v18, v14, v11
	v_max_u32_e32 v11, v14, v11
	ds_bpermute_b32 v14, v84, v3
	v_cndmask_b32_e64 v11, v11, v18, s[8:9]
	s_waitcnt lgkmcnt(0)
	v_min_u32_e32 v18, v15, v17
	v_max_u32_e32 v15, v15, v17
	ds_bpermute_b32 v17, v84, v7
	v_cndmask_b32_e64 v15, v15, v18, s[8:9]
	s_waitcnt lgkmcnt(0)
	v_min_u32_e32 v18, v3, v14
	v_max_u32_e32 v3, v3, v14
	ds_bpermute_b32 v14, v84, v6
	v_cndmask_b32_e64 v3, v3, v18, s[8:9]
	s_waitcnt lgkmcnt(0)
	v_min_u32_e32 v18, v7, v17
	v_max_u32_e32 v7, v7, v17
	ds_bpermute_b32 v17, v84, v16
	v_cndmask_b32_e64 v7, v7, v18, s[8:9]
	s_waitcnt lgkmcnt(0)
	v_min_u32_e32 v18, v6, v14
	v_max_u32_e32 v6, v6, v14
	ds_bpermute_b32 v14, v84, v0
	v_cndmask_b32_e64 v6, v6, v18, s[8:9]
	s_waitcnt lgkmcnt(0)
	v_min_u32_e32 v18, v16, v17
	v_max_u32_e32 v16, v16, v17
	ds_bpermute_b32 v17, v84, v2
	v_cndmask_b32_e64 v16, v16, v18, s[8:9]
	s_waitcnt lgkmcnt(0)
	v_min_u32_e32 v18, v0, v14
	v_max_u32_e32 v0, v0, v14
	ds_bpermute_b32 v14, v84, v4
	v_cndmask_b32_e64 v0, v0, v18, s[8:9]
	s_waitcnt lgkmcnt(0)
	v_min_u32_e32 v18, v2, v17
	v_max_u32_e32 v2, v2, v17
	ds_bpermute_b32 v17, v84, v1
	v_cndmask_b32_e64 v2, v18, v2, s[8:9]
	s_waitcnt lgkmcnt(0)
	v_min_u32_e32 v18, v4, v14
	v_max_u32_e32 v4, v4, v14
	ds_bpermute_b32 v14, v84, v5
	v_cndmask_b32_e64 v4, v18, v4, s[8:9]
	s_waitcnt lgkmcnt(0)
	v_min_u32_e32 v18, v1, v17
	v_max_u32_e32 v1, v1, v17
	ds_bpermute_b32 v17, v84, v8
	v_cndmask_b32_e64 v1, v18, v1, s[8:9]
	s_waitcnt lgkmcnt(0)
	v_min_u32_e32 v18, v5, v14
	v_max_u32_e32 v5, v5, v14
	ds_bpermute_b32 v14, v84, v12
	v_cndmask_b32_e64 v5, v18, v5, s[8:9]
	s_waitcnt lgkmcnt(0)
	v_min_u32_e32 v18, v8, v17
	v_max_u32_e32 v8, v8, v17
	ds_bpermute_b32 v17, v84, v10
	v_cndmask_b32_e64 v8, v18, v8, s[8:9]
	s_waitcnt lgkmcnt(0)
	v_min_u32_e32 v18, v12, v14
	v_max_u32_e32 v12, v12, v14
	ds_bpermute_b32 v14, v84, v9
	v_cndmask_b32_e64 v12, v18, v12, s[8:9]
	s_waitcnt lgkmcnt(0)
	v_min_u32_e32 v18, v10, v17
	v_max_u32_e32 v10, v10, v17
	ds_bpermute_b32 v17, v83, v13
	v_cndmask_b32_e64 v10, v18, v10, s[8:9]
	s_waitcnt lgkmcnt(0)
	v_min_u32_e32 v18, v9, v14
	v_max_u32_e32 v9, v9, v14
	ds_bpermute_b32 v14, v83, v11
	v_cndmask_b32_e64 v9, v18, v9, s[8:9]
	s_waitcnt lgkmcnt(0)
	v_min_u32_e32 v18, v13, v17
	v_max_u32_e32 v13, v13, v17
	ds_bpermute_b32 v17, v83, v15
	v_cndmask_b32_e64 v13, v13, v18, s[6:7]
	s_waitcnt lgkmcnt(0)
	v_min_u32_e32 v18, v11, v14
	v_max_u32_e32 v11, v11, v14
	ds_bpermute_b32 v14, v83, v3
	v_cndmask_b32_e64 v11, v11, v18, s[6:7]
	s_waitcnt lgkmcnt(0)
	v_min_u32_e32 v18, v15, v17
	v_max_u32_e32 v15, v15, v17
	ds_bpermute_b32 v17, v83, v7
	v_cndmask_b32_e64 v15, v15, v18, s[6:7]
	s_waitcnt lgkmcnt(0)
	v_min_u32_e32 v18, v3, v14
	v_max_u32_e32 v3, v3, v14
	ds_bpermute_b32 v14, v83, v6
	v_cndmask_b32_e64 v3, v3, v18, s[6:7]
	s_waitcnt lgkmcnt(0)
	v_min_u32_e32 v18, v7, v17
	v_max_u32_e32 v7, v7, v17
	ds_bpermute_b32 v17, v83, v16
	v_cndmask_b32_e64 v7, v7, v18, s[6:7]
	s_waitcnt lgkmcnt(0)
	v_min_u32_e32 v18, v6, v14
	v_max_u32_e32 v6, v6, v14
	ds_bpermute_b32 v14, v83, v0
	v_cndmask_b32_e64 v6, v6, v18, s[6:7]
	s_waitcnt lgkmcnt(0)
	v_min_u32_e32 v18, v16, v17
	v_max_u32_e32 v16, v16, v17
	ds_bpermute_b32 v17, v83, v2
	v_cndmask_b32_e64 v16, v16, v18, s[6:7]
	s_waitcnt lgkmcnt(0)
	v_min_u32_e32 v18, v0, v14
	v_max_u32_e32 v0, v0, v14
	ds_bpermute_b32 v14, v83, v4
	v_cndmask_b32_e64 v0, v0, v18, s[6:7]
	s_waitcnt lgkmcnt(0)
	v_min_u32_e32 v18, v2, v17
	v_max_u32_e32 v2, v2, v17
	ds_bpermute_b32 v17, v83, v1
	v_cndmask_b32_e64 v2, v18, v2, s[6:7]
	s_waitcnt lgkmcnt(0)
	v_min_u32_e32 v18, v4, v14
	v_max_u32_e32 v4, v4, v14
	ds_bpermute_b32 v14, v83, v5
	v_cndmask_b32_e64 v4, v18, v4, s[6:7]
	s_waitcnt lgkmcnt(0)
	v_min_u32_e32 v18, v1, v17
	v_max_u32_e32 v1, v1, v17
	ds_bpermute_b32 v17, v83, v8
	v_cndmask_b32_e64 v1, v18, v1, s[6:7]
	s_waitcnt lgkmcnt(0)
	v_min_u32_e32 v18, v5, v14
	v_max_u32_e32 v5, v5, v14
	ds_bpermute_b32 v14, v83, v12
	v_cndmask_b32_e64 v5, v18, v5, s[6:7]
	s_waitcnt lgkmcnt(0)
	v_min_u32_e32 v18, v8, v17
	v_max_u32_e32 v8, v8, v17
	ds_bpermute_b32 v17, v83, v10
	v_cndmask_b32_e64 v8, v18, v8, s[6:7]
	s_waitcnt lgkmcnt(0)
	v_min_u32_e32 v18, v12, v14
	v_max_u32_e32 v12, v12, v14
	ds_bpermute_b32 v14, v83, v9
	v_cndmask_b32_e64 v12, v18, v12, s[6:7]
	s_waitcnt lgkmcnt(0)
	v_min_u32_e32 v18, v10, v17
	v_max_u32_e32 v10, v10, v17
	s_nop 1
	v_mov_b32_dpp v17, v13 row_ror:8 row_mask:0xf bank_mask:0xf
	v_cndmask_b32_e64 v10, v18, v10, s[6:7]
	s_waitcnt lgkmcnt(0)
	v_min_u32_e32 v18, v9, v14
	v_max_u32_e32 v9, v9, v14
	s_nop 1
	v_mov_b32_dpp v14, v11 row_ror:8 row_mask:0xf bank_mask:0xf
	v_cndmask_b32_e64 v9, v18, v9, s[6:7]
	s_waitcnt lgkmcnt(0)
	v_min_u32_e32 v18, v13, v17
	v_max_u32_e32 v13, v13, v17
	s_nop 1
	v_mov_b32_dpp v17, v15 row_ror:8 row_mask:0xf bank_mask:0xf
	v_cndmask_b32_e64 v13, v13, v18, s[4:5]
	s_waitcnt lgkmcnt(0)
	v_min_u32_e32 v18, v11, v14
	v_max_u32_e32 v11, v11, v14
	s_nop 1
	v_mov_b32_dpp v14, v3 row_ror:8 row_mask:0xf bank_mask:0xf
	v_cndmask_b32_e64 v11, v11, v18, s[4:5]
	s_waitcnt lgkmcnt(0)
	v_min_u32_e32 v18, v15, v17
	v_max_u32_e32 v15, v15, v17
	s_nop 1
	v_mov_b32_dpp v17, v7 row_ror:8 row_mask:0xf bank_mask:0xf
	v_cndmask_b32_e64 v15, v15, v18, s[4:5]
	s_waitcnt lgkmcnt(0)
	v_min_u32_e32 v18, v3, v14
	v_max_u32_e32 v3, v3, v14
	s_nop 1
	v_mov_b32_dpp v14, v6 row_ror:8 row_mask:0xf bank_mask:0xf
	v_cndmask_b32_e64 v3, v3, v18, s[4:5]
	s_waitcnt lgkmcnt(0)
	v_min_u32_e32 v18, v7, v17
	v_max_u32_e32 v7, v7, v17
	s_nop 1
	v_mov_b32_dpp v17, v16 row_ror:8 row_mask:0xf bank_mask:0xf
	v_cndmask_b32_e64 v7, v7, v18, s[4:5]
	s_waitcnt lgkmcnt(0)
	v_min_u32_e32 v18, v6, v14
	v_max_u32_e32 v6, v6, v14
	s_nop 1
	v_mov_b32_dpp v14, v0 row_ror:8 row_mask:0xf bank_mask:0xf
	v_cndmask_b32_e64 v6, v6, v18, s[4:5]
	s_waitcnt lgkmcnt(0)
	v_min_u32_e32 v18, v16, v17
	v_max_u32_e32 v16, v16, v17
	s_nop 1
	v_mov_b32_dpp v17, v2 row_ror:8 row_mask:0xf bank_mask:0xf
	v_cndmask_b32_e64 v16, v16, v18, s[4:5]
	s_waitcnt lgkmcnt(0)
	v_min_u32_e32 v18, v0, v14
	v_max_u32_e32 v0, v0, v14
	s_nop 1
	v_mov_b32_dpp v14, v4 row_ror:8 row_mask:0xf bank_mask:0xf
	v_cndmask_b32_e64 v0, v0, v18, s[4:5]
	s_waitcnt lgkmcnt(0)
	v_min_u32_e32 v18, v2, v17
	v_max_u32_e32 v2, v2, v17
	s_nop 1
	v_mov_b32_dpp v17, v1 row_ror:8 row_mask:0xf bank_mask:0xf
	v_cndmask_b32_e64 v2, v18, v2, s[4:5]
	s_waitcnt lgkmcnt(0)
	v_min_u32_e32 v18, v4, v14
	v_max_u32_e32 v4, v4, v14
	s_nop 1
	v_mov_b32_dpp v14, v5 row_ror:8 row_mask:0xf bank_mask:0xf
	v_cndmask_b32_e64 v4, v18, v4, s[4:5]
	s_waitcnt lgkmcnt(0)
	v_min_u32_e32 v18, v1, v17
	v_max_u32_e32 v1, v1, v17
	s_nop 1
	v_mov_b32_dpp v17, v8 row_ror:8 row_mask:0xf bank_mask:0xf
	v_cndmask_b32_e64 v1, v18, v1, s[4:5]
	s_waitcnt lgkmcnt(0)
	v_min_u32_e32 v18, v5, v14
	v_max_u32_e32 v5, v5, v14
	s_nop 1
	v_mov_b32_dpp v14, v12 row_ror:8 row_mask:0xf bank_mask:0xf
	v_cndmask_b32_e64 v5, v18, v5, s[4:5]
	s_waitcnt lgkmcnt(0)
	v_min_u32_e32 v18, v8, v17
	v_max_u32_e32 v8, v8, v17
	s_nop 1
	v_mov_b32_dpp v17, v10 row_ror:8 row_mask:0xf bank_mask:0xf
	v_cndmask_b32_e64 v8, v18, v8, s[4:5]
	s_waitcnt lgkmcnt(0)
	v_min_u32_e32 v18, v12, v14
	v_max_u32_e32 v12, v12, v14
	s_nop 1
	v_mov_b32_dpp v14, v9 row_ror:8 row_mask:0xf bank_mask:0xf
	v_cndmask_b32_e64 v12, v18, v12, s[4:5]
	s_waitcnt lgkmcnt(0)
	v_min_u32_e32 v18, v10, v17
	v_max_u32_e32 v10, v10, v17
	s_nop 1
	v_mov_b32_dpp v17, v13 row_shl:4 row_mask:0xf bank_mask:0x5
	v_mov_b32_dpp v17, v13 row_shr:4 row_mask:0xf bank_mask:0xa
	v_cndmask_b32_e64 v10, v18, v10, s[4:5]
	s_waitcnt lgkmcnt(0)
	v_min_u32_e32 v18, v9, v14
	v_max_u32_e32 v9, v9, v14
	s_nop 1
	v_mov_b32_dpp v14, v11 row_shl:4 row_mask:0xf bank_mask:0x5
	v_mov_b32_dpp v14, v11 row_shr:4 row_mask:0xf bank_mask:0xa
	v_cndmask_b32_e64 v9, v18, v9, s[4:5]
	s_waitcnt lgkmcnt(0)
	v_min_u32_e32 v18, v13, v17
	v_max_u32_e32 v13, v13, v17
	s_nop 1
	v_mov_b32_dpp v17, v15 row_shl:4 row_mask:0xf bank_mask:0x5
	v_mov_b32_dpp v17, v15 row_shr:4 row_mask:0xf bank_mask:0xa
	v_cndmask_b32_e64 v13, v13, v18, s[2:3]
	s_waitcnt lgkmcnt(0)
	v_min_u32_e32 v18, v11, v14
	v_max_u32_e32 v11, v11, v14
	s_nop 1
	v_mov_b32_dpp v14, v3 row_shl:4 row_mask:0xf bank_mask:0x5
	v_mov_b32_dpp v14, v3 row_shr:4 row_mask:0xf bank_mask:0xa
	v_cndmask_b32_e64 v11, v11, v18, s[2:3]
	s_waitcnt lgkmcnt(0)
	v_min_u32_e32 v18, v15, v17
	v_max_u32_e32 v15, v15, v17
	s_nop 1
	v_mov_b32_dpp v17, v7 row_shl:4 row_mask:0xf bank_mask:0x5
	v_mov_b32_dpp v17, v7 row_shr:4 row_mask:0xf bank_mask:0xa
	v_cndmask_b32_e64 v15, v15, v18, s[2:3]
	s_waitcnt lgkmcnt(0)
	v_min_u32_e32 v18, v3, v14
	v_max_u32_e32 v3, v3, v14
	s_nop 1
	v_mov_b32_dpp v14, v6 row_shl:4 row_mask:0xf bank_mask:0x5
	v_mov_b32_dpp v14, v6 row_shr:4 row_mask:0xf bank_mask:0xa
	v_cndmask_b32_e64 v3, v3, v18, s[2:3]
	s_waitcnt lgkmcnt(0)
	v_min_u32_e32 v18, v7, v17
	v_max_u32_e32 v7, v7, v17
	s_nop 1
	v_mov_b32_dpp v17, v16 row_shl:4 row_mask:0xf bank_mask:0x5
	v_mov_b32_dpp v17, v16 row_shr:4 row_mask:0xf bank_mask:0xa
	v_cndmask_b32_e64 v7, v7, v18, s[2:3]
	s_waitcnt lgkmcnt(0)
	v_min_u32_e32 v18, v6, v14
	v_max_u32_e32 v6, v6, v14
	s_nop 1
	v_mov_b32_dpp v14, v0 row_shl:4 row_mask:0xf bank_mask:0x5
	v_mov_b32_dpp v14, v0 row_shr:4 row_mask:0xf bank_mask:0xa
	v_cndmask_b32_e64 v6, v6, v18, s[2:3]
	s_waitcnt lgkmcnt(0)
	v_min_u32_e32 v18, v16, v17
	v_max_u32_e32 v16, v16, v17
	s_nop 1
	v_mov_b32_dpp v17, v2 row_shl:4 row_mask:0xf bank_mask:0x5
	v_mov_b32_dpp v17, v2 row_shr:4 row_mask:0xf bank_mask:0xa
	v_cndmask_b32_e64 v16, v16, v18, s[2:3]
	s_waitcnt lgkmcnt(0)
	v_min_u32_e32 v18, v0, v14
	v_max_u32_e32 v0, v0, v14
	s_nop 1
	v_mov_b32_dpp v14, v4 row_shl:4 row_mask:0xf bank_mask:0x5
	v_mov_b32_dpp v14, v4 row_shr:4 row_mask:0xf bank_mask:0xa
	v_cndmask_b32_e64 v0, v0, v18, s[2:3]
	s_waitcnt lgkmcnt(0)
	v_min_u32_e32 v18, v2, v17
	v_max_u32_e32 v2, v2, v17
	s_nop 1
	v_mov_b32_dpp v17, v1 row_shl:4 row_mask:0xf bank_mask:0x5
	v_mov_b32_dpp v17, v1 row_shr:4 row_mask:0xf bank_mask:0xa
	v_cndmask_b32_e64 v2, v18, v2, s[2:3]
	s_waitcnt lgkmcnt(0)
	v_min_u32_e32 v18, v4, v14
	v_max_u32_e32 v4, v4, v14
	s_nop 1
	v_mov_b32_dpp v14, v5 row_shl:4 row_mask:0xf bank_mask:0x5
	v_mov_b32_dpp v14, v5 row_shr:4 row_mask:0xf bank_mask:0xa
	v_cndmask_b32_e64 v4, v18, v4, s[2:3]
	s_waitcnt lgkmcnt(0)
	v_min_u32_e32 v18, v1, v17
	v_max_u32_e32 v1, v1, v17
	s_nop 1
	v_mov_b32_dpp v17, v8 row_shl:4 row_mask:0xf bank_mask:0x5
	v_mov_b32_dpp v17, v8 row_shr:4 row_mask:0xf bank_mask:0xa
	v_cndmask_b32_e64 v1, v18, v1, s[2:3]
	s_waitcnt lgkmcnt(0)
	v_min_u32_e32 v18, v5, v14
	v_max_u32_e32 v5, v5, v14
	s_nop 1
	v_mov_b32_dpp v14, v12 row_shl:4 row_mask:0xf bank_mask:0x5
	v_mov_b32_dpp v14, v12 row_shr:4 row_mask:0xf bank_mask:0xa
	v_cndmask_b32_e64 v5, v18, v5, s[2:3]
	s_waitcnt lgkmcnt(0)
	v_min_u32_e32 v18, v8, v17
	v_max_u32_e32 v8, v8, v17
	s_nop 1
	v_mov_b32_dpp v17, v10 row_shl:4 row_mask:0xf bank_mask:0x5
	v_mov_b32_dpp v17, v10 row_shr:4 row_mask:0xf bank_mask:0xa
	v_cndmask_b32_e64 v8, v18, v8, s[2:3]
	s_waitcnt lgkmcnt(0)
	v_min_u32_e32 v18, v12, v14
	v_max_u32_e32 v12, v12, v14
	s_nop 1
	v_mov_b32_dpp v14, v9 row_shl:4 row_mask:0xf bank_mask:0x5
	v_mov_b32_dpp v14, v9 row_shr:4 row_mask:0xf bank_mask:0xa
	v_cndmask_b32_e64 v12, v18, v12, s[2:3]
	s_waitcnt lgkmcnt(0)
	v_min_u32_e32 v18, v10, v17
	v_max_u32_e32 v10, v10, v17
	s_nop 1
	v_mov_b32_dpp v17, v13 quad_perm:[2,3,0,1] row_mask:0xf bank_mask:0xf
	v_cndmask_b32_e64 v10, v18, v10, s[2:3]
	s_waitcnt lgkmcnt(0)
	v_min_u32_e32 v18, v9, v14
	v_max_u32_e32 v9, v9, v14
	s_nop 1
	v_mov_b32_dpp v14, v11 quad_perm:[2,3,0,1] row_mask:0xf bank_mask:0xf
	v_cndmask_b32_e64 v9, v18, v9, s[2:3]
	s_waitcnt lgkmcnt(0)
	v_min_u32_e32 v18, v13, v17
	v_max_u32_e32 v13, v13, v17
	s_nop 1
	v_mov_b32_dpp v17, v15 quad_perm:[2,3,0,1] row_mask:0xf bank_mask:0xf
	v_cndmask_b32_e64 v13, v13, v18, s[0:1]
	s_waitcnt lgkmcnt(0)
	v_min_u32_e32 v18, v11, v14
	v_max_u32_e32 v11, v11, v14
	s_nop 1
	v_mov_b32_dpp v14, v3 quad_perm:[2,3,0,1] row_mask:0xf bank_mask:0xf
	v_cndmask_b32_e64 v11, v11, v18, s[0:1]
	s_waitcnt lgkmcnt(0)
	v_min_u32_e32 v18, v15, v17
	v_max_u32_e32 v15, v15, v17
	s_nop 1
	v_mov_b32_dpp v17, v7 quad_perm:[2,3,0,1] row_mask:0xf bank_mask:0xf
	v_cndmask_b32_e64 v15, v15, v18, s[0:1]
	s_waitcnt lgkmcnt(0)
	v_min_u32_e32 v18, v3, v14
	v_max_u32_e32 v3, v3, v14
	s_nop 1
	v_mov_b32_dpp v14, v6 quad_perm:[2,3,0,1] row_mask:0xf bank_mask:0xf
	v_cndmask_b32_e64 v3, v3, v18, s[0:1]
	s_waitcnt lgkmcnt(0)
	v_min_u32_e32 v18, v7, v17
	v_max_u32_e32 v7, v7, v17
	s_nop 1
	v_mov_b32_dpp v17, v16 quad_perm:[2,3,0,1] row_mask:0xf bank_mask:0xf
	v_cndmask_b32_e64 v7, v7, v18, s[0:1]
	s_waitcnt lgkmcnt(0)
	v_min_u32_e32 v18, v6, v14
	v_max_u32_e32 v6, v6, v14
	s_nop 1
	v_mov_b32_dpp v14, v0 quad_perm:[2,3,0,1] row_mask:0xf bank_mask:0xf
	v_cndmask_b32_e64 v6, v6, v18, s[0:1]
	s_waitcnt lgkmcnt(0)
	v_min_u32_e32 v18, v16, v17
	v_max_u32_e32 v16, v16, v17
	s_nop 1
	v_mov_b32_dpp v17, v2 quad_perm:[2,3,0,1] row_mask:0xf bank_mask:0xf
	v_cndmask_b32_e64 v16, v16, v18, s[0:1]
	s_waitcnt lgkmcnt(0)
	v_min_u32_e32 v18, v0, v14
	v_max_u32_e32 v0, v0, v14
	s_nop 1
	v_mov_b32_dpp v14, v4 quad_perm:[2,3,0,1] row_mask:0xf bank_mask:0xf
	v_cndmask_b32_e64 v0, v0, v18, s[0:1]
	s_waitcnt lgkmcnt(0)
	v_min_u32_e32 v18, v2, v17
	v_max_u32_e32 v2, v2, v17
	s_nop 1
	v_mov_b32_dpp v17, v1 quad_perm:[2,3,0,1] row_mask:0xf bank_mask:0xf
	v_cndmask_b32_e64 v2, v18, v2, s[0:1]
	s_waitcnt lgkmcnt(0)
	v_min_u32_e32 v18, v4, v14
	v_max_u32_e32 v4, v4, v14
	s_nop 1
	v_mov_b32_dpp v14, v5 quad_perm:[2,3,0,1] row_mask:0xf bank_mask:0xf
	v_cndmask_b32_e64 v4, v18, v4, s[0:1]
	s_waitcnt lgkmcnt(0)
	v_min_u32_e32 v18, v1, v17
	v_max_u32_e32 v1, v1, v17
	s_nop 1
	v_mov_b32_dpp v17, v8 quad_perm:[2,3,0,1] row_mask:0xf bank_mask:0xf
	v_cndmask_b32_e64 v1, v18, v1, s[0:1]
	s_waitcnt lgkmcnt(0)
	v_min_u32_e32 v18, v5, v14
	v_max_u32_e32 v5, v5, v14
	s_nop 1
	v_mov_b32_dpp v14, v12 quad_perm:[2,3,0,1] row_mask:0xf bank_mask:0xf
	v_cndmask_b32_e64 v5, v18, v5, s[0:1]
	s_waitcnt lgkmcnt(0)
	v_min_u32_e32 v18, v8, v17
	v_max_u32_e32 v8, v8, v17
	s_nop 1
	v_mov_b32_dpp v17, v10 quad_perm:[2,3,0,1] row_mask:0xf bank_mask:0xf
	v_cndmask_b32_e64 v8, v18, v8, s[0:1]
	s_waitcnt lgkmcnt(0)
	v_min_u32_e32 v18, v12, v14
	v_max_u32_e32 v12, v12, v14
	s_nop 1
	v_mov_b32_dpp v14, v9 quad_perm:[2,3,0,1] row_mask:0xf bank_mask:0xf
	v_cndmask_b32_e64 v12, v18, v12, s[0:1]
	s_waitcnt lgkmcnt(0)
	v_min_u32_e32 v18, v10, v17
	v_max_u32_e32 v10, v10, v17
	s_nop 1
	v_mov_b32_dpp v17, v13 quad_perm:[1,0,3,2] row_mask:0xf bank_mask:0xf
	v_cndmask_b32_e64 v10, v18, v10, s[0:1]
	s_waitcnt lgkmcnt(0)
	v_min_u32_e32 v18, v9, v14
	v_max_u32_e32 v9, v9, v14
	s_nop 1
	v_mov_b32_dpp v14, v11 quad_perm:[1,0,3,2] row_mask:0xf bank_mask:0xf
	v_cndmask_b32_e64 v9, v18, v9, s[0:1]
	s_waitcnt lgkmcnt(0)
	v_min_u32_e32 v18, v13, v17
	v_max_u32_e32 v13, v13, v17
	s_nop 1
	v_mov_b32_dpp v17, v15 quad_perm:[1,0,3,2] row_mask:0xf bank_mask:0xf
	v_cndmask_b32_e32 v13, v13, v18, vcc
	s_waitcnt lgkmcnt(0)
	v_min_u32_e32 v18, v11, v14
	v_max_u32_e32 v11, v11, v14
	s_nop 1
	v_mov_b32_dpp v14, v3 quad_perm:[1,0,3,2] row_mask:0xf bank_mask:0xf
	v_cndmask_b32_e32 v11, v11, v18, vcc
	s_waitcnt lgkmcnt(0)
	v_min_u32_e32 v18, v15, v17
	v_max_u32_e32 v15, v15, v17
	s_nop 1
	v_mov_b32_dpp v17, v7 quad_perm:[1,0,3,2] row_mask:0xf bank_mask:0xf
	v_cndmask_b32_e32 v15, v15, v18, vcc
	s_waitcnt lgkmcnt(0)
	v_min_u32_e32 v18, v3, v14
	v_max_u32_e32 v3, v3, v14
	s_nop 1
	v_mov_b32_dpp v14, v6 quad_perm:[1,0,3,2] row_mask:0xf bank_mask:0xf
	v_cndmask_b32_e32 v3, v3, v18, vcc
	s_waitcnt lgkmcnt(0)
	v_min_u32_e32 v18, v7, v17
	v_max_u32_e32 v7, v7, v17
	s_nop 1
	v_mov_b32_dpp v17, v16 quad_perm:[1,0,3,2] row_mask:0xf bank_mask:0xf
	v_cndmask_b32_e32 v7, v7, v18, vcc
	s_waitcnt lgkmcnt(0)
	v_min_u32_e32 v18, v6, v14
	v_max_u32_e32 v6, v6, v14
	s_nop 1
	v_mov_b32_dpp v14, v0 quad_perm:[1,0,3,2] row_mask:0xf bank_mask:0xf
	v_cndmask_b32_e32 v6, v6, v18, vcc
	s_waitcnt lgkmcnt(0)
	v_min_u32_e32 v18, v16, v17
	v_max_u32_e32 v16, v16, v17
	s_nop 1
	v_mov_b32_dpp v17, v2 quad_perm:[1,0,3,2] row_mask:0xf bank_mask:0xf
	v_cndmask_b32_e32 v16, v16, v18, vcc
	s_waitcnt lgkmcnt(0)
	v_min_u32_e32 v18, v0, v14
	v_max_u32_e32 v0, v0, v14
	s_nop 1
	v_mov_b32_dpp v14, v4 quad_perm:[1,0,3,2] row_mask:0xf bank_mask:0xf
	v_cndmask_b32_e32 v0, v0, v18, vcc
	s_waitcnt lgkmcnt(0)
	v_min_u32_e32 v18, v2, v17
	v_max_u32_e32 v2, v2, v17
	s_nop 1
	v_mov_b32_dpp v17, v1 quad_perm:[1,0,3,2] row_mask:0xf bank_mask:0xf
	v_cndmask_b32_e32 v2, v18, v2, vcc
	s_waitcnt lgkmcnt(0)
	v_min_u32_e32 v18, v4, v14
	v_max_u32_e32 v4, v4, v14
	s_nop 1
	v_mov_b32_dpp v14, v5 quad_perm:[1,0,3,2] row_mask:0xf bank_mask:0xf
	v_cndmask_b32_e32 v4, v18, v4, vcc
	s_waitcnt lgkmcnt(0)
	v_min_u32_e32 v18, v1, v17
	v_max_u32_e32 v1, v1, v17
	s_nop 1
	v_mov_b32_dpp v17, v8 quad_perm:[1,0,3,2] row_mask:0xf bank_mask:0xf
	v_cndmask_b32_e32 v1, v18, v1, vcc
	s_waitcnt lgkmcnt(0)
	v_min_u32_e32 v18, v5, v14
	v_max_u32_e32 v5, v5, v14
	s_nop 1
	v_mov_b32_dpp v14, v12 quad_perm:[1,0,3,2] row_mask:0xf bank_mask:0xf
	v_cndmask_b32_e32 v5, v18, v5, vcc
	s_waitcnt lgkmcnt(0)
	v_min_u32_e32 v18, v8, v17
	v_max_u32_e32 v8, v8, v17
	v_cndmask_b32_e32 v8, v18, v8, vcc
	s_nop 1
	v_mov_b32_dpp v17, v10 quad_perm:[1,0,3,2] row_mask:0xf bank_mask:0xf
	s_waitcnt lgkmcnt(0)
	v_min_u32_e32 v18, v12, v14
	v_max_u32_e32 v12, v12, v14
	s_nop 1
	v_mov_b32_dpp v14, v9 quad_perm:[1,0,3,2] row_mask:0xf bank_mask:0xf
	v_cndmask_b32_e32 v12, v18, v12, vcc
	s_waitcnt lgkmcnt(0)
	v_min_u32_e32 v18, v10, v17
	v_max_u32_e32 v10, v10, v17
	v_cndmask_b32_e32 v10, v18, v10, vcc
	s_waitcnt lgkmcnt(0)
	v_min_u32_e32 v17, v9, v14
	v_max_u32_e32 v9, v9, v14
	v_cndmask_b32_e32 v9, v17, v9, vcc
	v_min_u32_e32 v14, v13, v2
	v_max_u32_e32 v2, v13, v2
	v_min_u32_e32 v13, v11, v4
	v_max_u32_e32 v4, v11, v4
	v_min_u32_e32 v11, v15, v1
	v_max_u32_e32 v1, v15, v1
	v_min_u32_e32 v15, v3, v5
	v_max_u32_e32 v3, v3, v5
	v_min_u32_e32 v5, v7, v8
	v_max_u32_e32 v7, v7, v8
	v_min_u32_e32 v8, v6, v12
	v_max_u32_e32 v6, v6, v12
	v_min_u32_e32 v12, v16, v10
	v_max_u32_e32 v10, v16, v10
	v_min_u32_e32 v16, v0, v9
	v_max_u32_e32 v0, v0, v9
	v_min_u32_e32 v9, v14, v5
	v_max_u32_e32 v5, v14, v5
	v_min_u32_e32 v14, v13, v8
	v_max_u32_e32 v8, v13, v8
	v_min_u32_e32 v13, v11, v12
	v_max_u32_e32 v11, v11, v12
	v_min_u32_e32 v12, v15, v16
	v_max_u32_e32 v15, v15, v16
	v_min_u32_e32 v16, v2, v7
	v_max_u32_e32 v2, v2, v7
	v_min_u32_e32 v7, v4, v6
	v_max_u32_e32 v4, v4, v6
	v_min_u32_e32 v6, v1, v10
	v_max_u32_e32 v1, v1, v10
	v_min_u32_e32 v10, v3, v0
	v_max_u32_e32 v0, v3, v0
	v_min_u32_e32 v3, v9, v13
	v_max_u32_e32 v9, v9, v13
	v_min_u32_e32 v13, v14, v12
	v_max_u32_e32 v12, v14, v12
	v_min_u32_e32 v14, v5, v11
	v_max_u32_e32 v5, v5, v11
	v_min_u32_e32 v11, v8, v15
	v_max_u32_e32 v8, v8, v15
	v_min_u32_e32 v15, v16, v6
	v_max_u32_e32 v6, v16, v6
	v_min_u32_e32 v16, v7, v10
	v_max_u32_e32 v7, v7, v10
	v_min_u32_e32 v10, v2, v1
	v_max_u32_e32 v1, v2, v1
	v_min_u32_e32 v2, v4, v0
	v_max_u32_e32 v0, v4, v0
	v_min_u32_e32 v4, v3, v13
	ds_bpermute_b32 v17, v84, v4
	v_max_u32_e32 v3, v3, v13
	v_min_u32_e32 v13, v9, v12
	v_max_u32_e32 v9, v9, v12
	v_min_u32_e32 v12, v14, v11
	v_max_u32_e32 v11, v14, v11
	v_min_u32_e32 v14, v5, v8
	v_max_u32_e32 v5, v5, v8
	v_min_u32_e32 v8, v15, v16
	v_max_u32_e32 v15, v15, v16
	v_min_u32_e32 v16, v6, v7
	v_max_u32_e32 v6, v6, v7
	v_min_u32_e32 v7, v10, v2
	v_max_u32_e32 v2, v10, v2
	v_min_u32_e32 v10, v1, v0
	v_max_u32_e32 v0, v1, v0
	ds_bpermute_b32 v1, v84, v3
	s_waitcnt lgkmcnt(0)
	v_min_u32_e32 v18, v4, v17
	v_max_u32_e32 v4, v4, v17
	ds_bpermute_b32 v17, v84, v13
	v_cndmask_b32_e64 v4, v4, v18, s[8:9]
	s_waitcnt lgkmcnt(0)
	v_min_u32_e32 v18, v3, v1
	v_max_u32_e32 v1, v3, v1
	ds_bpermute_b32 v3, v84, v9
	v_cndmask_b32_e64 v1, v1, v18, s[8:9]
	s_waitcnt lgkmcnt(0)
	v_min_u32_e32 v18, v13, v17
	v_max_u32_e32 v13, v13, v17
	ds_bpermute_b32 v17, v84, v12
	v_cndmask_b32_e64 v13, v13, v18, s[8:9]
	s_waitcnt lgkmcnt(0)
	v_min_u32_e32 v18, v9, v3
	v_max_u32_e32 v3, v9, v3
	ds_bpermute_b32 v9, v84, v11
	v_cndmask_b32_e64 v3, v3, v18, s[8:9]
	s_waitcnt lgkmcnt(0)
	v_min_u32_e32 v18, v12, v17
	v_max_u32_e32 v12, v12, v17
	ds_bpermute_b32 v17, v84, v14
	v_cndmask_b32_e64 v12, v12, v18, s[8:9]
	s_waitcnt lgkmcnt(0)
	v_min_u32_e32 v18, v11, v9
	v_max_u32_e32 v9, v11, v9
	ds_bpermute_b32 v11, v84, v5
	v_cndmask_b32_e64 v9, v9, v18, s[8:9]
	s_waitcnt lgkmcnt(0)
	v_min_u32_e32 v18, v14, v17
	v_max_u32_e32 v14, v14, v17
	ds_bpermute_b32 v17, v84, v8
	v_cndmask_b32_e64 v14, v14, v18, s[8:9]
	s_waitcnt lgkmcnt(0)
	v_min_u32_e32 v18, v5, v11
	v_max_u32_e32 v5, v5, v11
	ds_bpermute_b32 v11, v84, v15
	v_cndmask_b32_e64 v5, v5, v18, s[8:9]
	s_waitcnt lgkmcnt(0)
	v_min_u32_e32 v18, v8, v17
	v_max_u32_e32 v8, v8, v17
	ds_bpermute_b32 v17, v84, v16
	v_cndmask_b32_e64 v8, v8, v18, s[8:9]
	s_waitcnt lgkmcnt(0)
	v_min_u32_e32 v18, v15, v11
	v_max_u32_e32 v11, v15, v11
	ds_bpermute_b32 v15, v84, v6
	v_cndmask_b32_e64 v11, v11, v18, s[8:9]
	s_waitcnt lgkmcnt(0)
	v_min_u32_e32 v18, v16, v17
	v_max_u32_e32 v16, v16, v17
	ds_bpermute_b32 v17, v84, v7
	v_cndmask_b32_e64 v16, v16, v18, s[8:9]
	s_waitcnt lgkmcnt(0)
	v_min_u32_e32 v18, v6, v15
	v_max_u32_e32 v6, v6, v15
	ds_bpermute_b32 v15, v84, v2
	v_cndmask_b32_e64 v6, v6, v18, s[8:9]
	s_waitcnt lgkmcnt(0)
	v_min_u32_e32 v18, v7, v17
	v_max_u32_e32 v7, v7, v17
	ds_bpermute_b32 v17, v84, v10
	v_cndmask_b32_e64 v7, v7, v18, s[8:9]
	s_waitcnt lgkmcnt(0)
	v_min_u32_e32 v18, v2, v15
	v_max_u32_e32 v2, v2, v15
	ds_bpermute_b32 v15, v84, v0
	v_cndmask_b32_e64 v2, v2, v18, s[8:9]
	s_waitcnt lgkmcnt(0)
	v_min_u32_e32 v18, v10, v17
	v_max_u32_e32 v10, v10, v17
	ds_bpermute_b32 v17, v83, v4
	v_cndmask_b32_e64 v10, v10, v18, s[8:9]
	s_waitcnt lgkmcnt(0)
	v_min_u32_e32 v18, v0, v15
	v_max_u32_e32 v0, v0, v15
	ds_bpermute_b32 v15, v83, v1
	v_cndmask_b32_e64 v0, v0, v18, s[8:9]
	s_waitcnt lgkmcnt(0)
	v_min_u32_e32 v18, v4, v17
	v_max_u32_e32 v4, v4, v17
	ds_bpermute_b32 v17, v83, v13
	v_cndmask_b32_e64 v4, v4, v18, s[6:7]
	s_waitcnt lgkmcnt(0)
	v_min_u32_e32 v18, v1, v15
	v_max_u32_e32 v1, v1, v15
	ds_bpermute_b32 v15, v83, v3
	v_cndmask_b32_e64 v1, v1, v18, s[6:7]
	s_waitcnt lgkmcnt(0)
	v_min_u32_e32 v18, v13, v17
	v_max_u32_e32 v13, v13, v17
	ds_bpermute_b32 v17, v83, v12
	v_cndmask_b32_e64 v13, v13, v18, s[6:7]
	s_waitcnt lgkmcnt(0)
	v_min_u32_e32 v18, v3, v15
	v_max_u32_e32 v3, v3, v15
	ds_bpermute_b32 v15, v83, v9
	v_cndmask_b32_e64 v3, v3, v18, s[6:7]
	s_waitcnt lgkmcnt(0)
	v_min_u32_e32 v18, v12, v17
	v_max_u32_e32 v12, v12, v17
	ds_bpermute_b32 v17, v83, v14
	v_cndmask_b32_e64 v12, v12, v18, s[6:7]
	s_waitcnt lgkmcnt(0)
	v_min_u32_e32 v18, v9, v15
	v_max_u32_e32 v9, v9, v15
	ds_bpermute_b32 v15, v83, v5
	v_cndmask_b32_e64 v9, v9, v18, s[6:7]
	s_waitcnt lgkmcnt(0)
	v_min_u32_e32 v18, v14, v17
	v_max_u32_e32 v14, v14, v17
	ds_bpermute_b32 v17, v83, v8
	v_cndmask_b32_e64 v14, v14, v18, s[6:7]
	s_waitcnt lgkmcnt(0)
	v_min_u32_e32 v18, v5, v15
	v_max_u32_e32 v5, v5, v15
	ds_bpermute_b32 v15, v83, v11
	v_cndmask_b32_e64 v5, v5, v18, s[6:7]
	s_waitcnt lgkmcnt(0)
	v_min_u32_e32 v18, v8, v17
	v_max_u32_e32 v8, v8, v17
	ds_bpermute_b32 v17, v83, v16
	v_cndmask_b32_e64 v8, v8, v18, s[6:7]
	s_waitcnt lgkmcnt(0)
	v_min_u32_e32 v18, v11, v15
	v_max_u32_e32 v11, v11, v15
	ds_bpermute_b32 v15, v83, v6
	v_cndmask_b32_e64 v11, v11, v18, s[6:7]
	s_waitcnt lgkmcnt(0)
	v_min_u32_e32 v18, v16, v17
	v_max_u32_e32 v16, v16, v17
	ds_bpermute_b32 v17, v83, v7
	v_cndmask_b32_e64 v16, v16, v18, s[6:7]
	s_waitcnt lgkmcnt(0)
	v_min_u32_e32 v18, v6, v15
	v_max_u32_e32 v6, v6, v15
	ds_bpermute_b32 v15, v83, v2
	v_cndmask_b32_e64 v6, v6, v18, s[6:7]
	s_waitcnt lgkmcnt(0)
	v_min_u32_e32 v18, v7, v17
	v_max_u32_e32 v7, v7, v17
	ds_bpermute_b32 v17, v83, v10
	v_cndmask_b32_e64 v7, v7, v18, s[6:7]
	s_waitcnt lgkmcnt(0)
	v_min_u32_e32 v18, v2, v15
	v_max_u32_e32 v2, v2, v15
	ds_bpermute_b32 v15, v83, v0
	v_cndmask_b32_e64 v2, v2, v18, s[6:7]
	s_waitcnt lgkmcnt(0)
	v_min_u32_e32 v18, v10, v17
	v_max_u32_e32 v10, v10, v17
	s_nop 1
	v_mov_b32_dpp v17, v4 row_ror:8 row_mask:0xf bank_mask:0xf
	v_cndmask_b32_e64 v10, v10, v18, s[6:7]
	s_waitcnt lgkmcnt(0)
	v_min_u32_e32 v18, v0, v15
	v_max_u32_e32 v0, v0, v15
	s_nop 1
	v_mov_b32_dpp v15, v1 row_ror:8 row_mask:0xf bank_mask:0xf
	v_cndmask_b32_e64 v0, v0, v18, s[6:7]
	s_waitcnt lgkmcnt(0)
	v_min_u32_e32 v18, v4, v17
	v_max_u32_e32 v4, v4, v17
	s_nop 1
	v_mov_b32_dpp v17, v13 row_ror:8 row_mask:0xf bank_mask:0xf
	v_cndmask_b32_e64 v4, v4, v18, s[4:5]
	s_waitcnt lgkmcnt(0)
	v_min_u32_e32 v18, v1, v15
	v_max_u32_e32 v1, v1, v15
	s_nop 1
	v_mov_b32_dpp v15, v3 row_ror:8 row_mask:0xf bank_mask:0xf
	v_cndmask_b32_e64 v1, v1, v18, s[4:5]
	s_waitcnt lgkmcnt(0)
	v_min_u32_e32 v18, v13, v17
	v_max_u32_e32 v13, v13, v17
	s_nop 1
	v_mov_b32_dpp v17, v12 row_ror:8 row_mask:0xf bank_mask:0xf
	v_cndmask_b32_e64 v13, v13, v18, s[4:5]
	s_waitcnt lgkmcnt(0)
	v_min_u32_e32 v18, v3, v15
	v_max_u32_e32 v3, v3, v15
	s_nop 1
	v_mov_b32_dpp v15, v9 row_ror:8 row_mask:0xf bank_mask:0xf
	v_cndmask_b32_e64 v3, v3, v18, s[4:5]
	s_waitcnt lgkmcnt(0)
	v_min_u32_e32 v18, v12, v17
	v_max_u32_e32 v12, v12, v17
	s_nop 1
	v_mov_b32_dpp v17, v14 row_ror:8 row_mask:0xf bank_mask:0xf
	v_cndmask_b32_e64 v12, v12, v18, s[4:5]
	s_waitcnt lgkmcnt(0)
	v_min_u32_e32 v18, v9, v15
	v_max_u32_e32 v9, v9, v15
	s_nop 1
	v_mov_b32_dpp v15, v5 row_ror:8 row_mask:0xf bank_mask:0xf
	v_cndmask_b32_e64 v9, v9, v18, s[4:5]
	s_waitcnt lgkmcnt(0)
	v_min_u32_e32 v18, v14, v17
	v_max_u32_e32 v14, v14, v17
	s_nop 1
	v_mov_b32_dpp v17, v8 row_ror:8 row_mask:0xf bank_mask:0xf
	v_cndmask_b32_e64 v14, v14, v18, s[4:5]
	s_waitcnt lgkmcnt(0)
	v_min_u32_e32 v18, v5, v15
	v_max_u32_e32 v5, v5, v15
	s_nop 1
	v_mov_b32_dpp v15, v11 row_ror:8 row_mask:0xf bank_mask:0xf
	v_cndmask_b32_e64 v5, v5, v18, s[4:5]
	s_waitcnt lgkmcnt(0)
	v_min_u32_e32 v18, v8, v17
	v_max_u32_e32 v8, v8, v17
	s_nop 1
	v_mov_b32_dpp v17, v16 row_ror:8 row_mask:0xf bank_mask:0xf
	v_cndmask_b32_e64 v8, v8, v18, s[4:5]
	s_waitcnt lgkmcnt(0)
	v_min_u32_e32 v18, v11, v15
	v_max_u32_e32 v11, v11, v15
	s_nop 1
	v_mov_b32_dpp v15, v6 row_ror:8 row_mask:0xf bank_mask:0xf
	v_cndmask_b32_e64 v11, v11, v18, s[4:5]
	s_waitcnt lgkmcnt(0)
	v_min_u32_e32 v18, v16, v17
	v_max_u32_e32 v16, v16, v17
	s_nop 1
	v_mov_b32_dpp v17, v7 row_ror:8 row_mask:0xf bank_mask:0xf
	v_cndmask_b32_e64 v16, v16, v18, s[4:5]
	s_waitcnt lgkmcnt(0)
	v_min_u32_e32 v18, v6, v15
	v_max_u32_e32 v6, v6, v15
	s_nop 1
	v_mov_b32_dpp v15, v2 row_ror:8 row_mask:0xf bank_mask:0xf
	v_cndmask_b32_e64 v6, v6, v18, s[4:5]
	s_waitcnt lgkmcnt(0)
	v_min_u32_e32 v18, v7, v17
	v_max_u32_e32 v7, v7, v17
	s_nop 1
	v_mov_b32_dpp v17, v10 row_ror:8 row_mask:0xf bank_mask:0xf
	v_cndmask_b32_e64 v7, v7, v18, s[4:5]
	s_waitcnt lgkmcnt(0)
	v_min_u32_e32 v18, v2, v15
	v_max_u32_e32 v2, v2, v15
	s_nop 1
	v_mov_b32_dpp v15, v0 row_ror:8 row_mask:0xf bank_mask:0xf
	v_cndmask_b32_e64 v2, v2, v18, s[4:5]
	s_waitcnt lgkmcnt(0)
	v_min_u32_e32 v18, v10, v17
	v_max_u32_e32 v10, v10, v17
	s_nop 1
	v_mov_b32_dpp v17, v4 row_shl:4 row_mask:0xf bank_mask:0x5
	v_mov_b32_dpp v17, v4 row_shr:4 row_mask:0xf bank_mask:0xa
	v_cndmask_b32_e64 v10, v10, v18, s[4:5]
	s_waitcnt lgkmcnt(0)
	v_min_u32_e32 v18, v0, v15
	v_max_u32_e32 v0, v0, v15
	s_nop 1
	v_mov_b32_dpp v15, v1 row_shl:4 row_mask:0xf bank_mask:0x5
	v_mov_b32_dpp v15, v1 row_shr:4 row_mask:0xf bank_mask:0xa
	v_cndmask_b32_e64 v0, v0, v18, s[4:5]
	s_waitcnt lgkmcnt(0)
	v_min_u32_e32 v18, v4, v17
	v_max_u32_e32 v4, v4, v17
	s_nop 1
	v_mov_b32_dpp v17, v13 row_shl:4 row_mask:0xf bank_mask:0x5
	v_mov_b32_dpp v17, v13 row_shr:4 row_mask:0xf bank_mask:0xa
	v_cndmask_b32_e64 v4, v4, v18, s[2:3]
	s_waitcnt lgkmcnt(0)
	v_min_u32_e32 v18, v1, v15
	v_max_u32_e32 v1, v1, v15
	s_nop 1
	v_mov_b32_dpp v15, v3 row_shl:4 row_mask:0xf bank_mask:0x5
	v_mov_b32_dpp v15, v3 row_shr:4 row_mask:0xf bank_mask:0xa
	v_cndmask_b32_e64 v1, v1, v18, s[2:3]
	s_waitcnt lgkmcnt(0)
	v_min_u32_e32 v18, v13, v17
	v_max_u32_e32 v13, v13, v17
	s_nop 1
	v_mov_b32_dpp v17, v12 row_shl:4 row_mask:0xf bank_mask:0x5
	v_mov_b32_dpp v17, v12 row_shr:4 row_mask:0xf bank_mask:0xa
	v_cndmask_b32_e64 v13, v13, v18, s[2:3]
	s_waitcnt lgkmcnt(0)
	v_min_u32_e32 v18, v3, v15
	v_max_u32_e32 v3, v3, v15
	s_nop 1
	v_mov_b32_dpp v15, v9 row_shl:4 row_mask:0xf bank_mask:0x5
	v_mov_b32_dpp v15, v9 row_shr:4 row_mask:0xf bank_mask:0xa
	v_cndmask_b32_e64 v3, v3, v18, s[2:3]
	s_waitcnt lgkmcnt(0)
	v_min_u32_e32 v18, v12, v17
	v_max_u32_e32 v12, v12, v17
	s_nop 1
	v_mov_b32_dpp v17, v14 row_shl:4 row_mask:0xf bank_mask:0x5
	v_mov_b32_dpp v17, v14 row_shr:4 row_mask:0xf bank_mask:0xa
	v_cndmask_b32_e64 v12, v12, v18, s[2:3]
	s_waitcnt lgkmcnt(0)
	v_min_u32_e32 v18, v9, v15
	v_max_u32_e32 v9, v9, v15
	s_nop 1
	v_mov_b32_dpp v15, v5 row_shl:4 row_mask:0xf bank_mask:0x5
	v_mov_b32_dpp v15, v5 row_shr:4 row_mask:0xf bank_mask:0xa
	v_cndmask_b32_e64 v9, v9, v18, s[2:3]
	s_waitcnt lgkmcnt(0)
	v_min_u32_e32 v18, v14, v17
	v_max_u32_e32 v14, v14, v17
	s_nop 1
	v_mov_b32_dpp v17, v8 row_shl:4 row_mask:0xf bank_mask:0x5
	v_mov_b32_dpp v17, v8 row_shr:4 row_mask:0xf bank_mask:0xa
	v_cndmask_b32_e64 v14, v14, v18, s[2:3]
	s_waitcnt lgkmcnt(0)
	v_min_u32_e32 v18, v5, v15
	v_max_u32_e32 v5, v5, v15
	s_nop 1
	v_mov_b32_dpp v15, v11 row_shl:4 row_mask:0xf bank_mask:0x5
	v_mov_b32_dpp v15, v11 row_shr:4 row_mask:0xf bank_mask:0xa
	v_cndmask_b32_e64 v5, v5, v18, s[2:3]
	s_waitcnt lgkmcnt(0)
	v_min_u32_e32 v18, v8, v17
	v_max_u32_e32 v8, v8, v17
	s_nop 1
	v_mov_b32_dpp v17, v16 row_shl:4 row_mask:0xf bank_mask:0x5
	v_mov_b32_dpp v17, v16 row_shr:4 row_mask:0xf bank_mask:0xa
	v_cndmask_b32_e64 v8, v8, v18, s[2:3]
	s_waitcnt lgkmcnt(0)
	v_min_u32_e32 v18, v11, v15
	v_max_u32_e32 v11, v11, v15
	s_nop 1
	v_mov_b32_dpp v15, v6 row_shl:4 row_mask:0xf bank_mask:0x5
	v_mov_b32_dpp v15, v6 row_shr:4 row_mask:0xf bank_mask:0xa
	v_cndmask_b32_e64 v11, v11, v18, s[2:3]
	s_waitcnt lgkmcnt(0)
	v_min_u32_e32 v18, v16, v17
	v_max_u32_e32 v16, v16, v17
	s_nop 1
	v_mov_b32_dpp v17, v7 row_shl:4 row_mask:0xf bank_mask:0x5
	v_mov_b32_dpp v17, v7 row_shr:4 row_mask:0xf bank_mask:0xa
	v_cndmask_b32_e64 v16, v16, v18, s[2:3]
	s_waitcnt lgkmcnt(0)
	v_min_u32_e32 v18, v6, v15
	v_max_u32_e32 v6, v6, v15
	s_nop 1
	v_mov_b32_dpp v15, v2 row_shl:4 row_mask:0xf bank_mask:0x5
	v_mov_b32_dpp v15, v2 row_shr:4 row_mask:0xf bank_mask:0xa
	v_cndmask_b32_e64 v6, v6, v18, s[2:3]
	s_waitcnt lgkmcnt(0)
	v_min_u32_e32 v18, v7, v17
	v_max_u32_e32 v7, v7, v17
	s_nop 1
	v_mov_b32_dpp v17, v10 row_shl:4 row_mask:0xf bank_mask:0x5
	v_mov_b32_dpp v17, v10 row_shr:4 row_mask:0xf bank_mask:0xa
	v_cndmask_b32_e64 v7, v7, v18, s[2:3]
	s_waitcnt lgkmcnt(0)
	v_min_u32_e32 v18, v2, v15
	v_max_u32_e32 v2, v2, v15
	s_nop 1
	v_mov_b32_dpp v15, v0 row_shl:4 row_mask:0xf bank_mask:0x5
	v_mov_b32_dpp v15, v0 row_shr:4 row_mask:0xf bank_mask:0xa
	v_cndmask_b32_e64 v2, v2, v18, s[2:3]
	s_waitcnt lgkmcnt(0)
	v_min_u32_e32 v18, v10, v17
	v_max_u32_e32 v10, v10, v17
	s_nop 1
	v_mov_b32_dpp v17, v4 quad_perm:[2,3,0,1] row_mask:0xf bank_mask:0xf
	v_cndmask_b32_e64 v10, v10, v18, s[2:3]
	s_waitcnt lgkmcnt(0)
	v_min_u32_e32 v18, v0, v15
	v_max_u32_e32 v0, v0, v15
	s_nop 1
	v_mov_b32_dpp v15, v1 quad_perm:[2,3,0,1] row_mask:0xf bank_mask:0xf
	v_cndmask_b32_e64 v0, v0, v18, s[2:3]
	s_waitcnt lgkmcnt(0)
	v_min_u32_e32 v18, v4, v17
	v_max_u32_e32 v4, v4, v17
	s_nop 1
	v_mov_b32_dpp v17, v13 quad_perm:[2,3,0,1] row_mask:0xf bank_mask:0xf
	v_cndmask_b32_e64 v4, v4, v18, s[0:1]
	s_waitcnt lgkmcnt(0)
	v_min_u32_e32 v18, v1, v15
	v_max_u32_e32 v1, v1, v15
	s_nop 1
	v_mov_b32_dpp v15, v3 quad_perm:[2,3,0,1] row_mask:0xf bank_mask:0xf
	v_cndmask_b32_e64 v1, v1, v18, s[0:1]
	s_waitcnt lgkmcnt(0)
	v_min_u32_e32 v18, v13, v17
	v_max_u32_e32 v13, v13, v17
	s_nop 1
	v_mov_b32_dpp v17, v12 quad_perm:[2,3,0,1] row_mask:0xf bank_mask:0xf
	v_cndmask_b32_e64 v13, v13, v18, s[0:1]
	s_waitcnt lgkmcnt(0)
	v_min_u32_e32 v18, v3, v15
	v_max_u32_e32 v3, v3, v15
	v_cndmask_b32_e64 v3, v3, v18, s[0:1]
	s_nop 1
	v_mov_b32_dpp v15, v9 quad_perm:[2,3,0,1] row_mask:0xf bank_mask:0xf
	s_waitcnt lgkmcnt(0)
	v_min_u32_e32 v18, v12, v17
	v_max_u32_e32 v12, v12, v17
	v_cndmask_b32_e64 v36, v12, v18, s[0:1]
	s_nop 1
	v_mov_b32_dpp v12, v14 quad_perm:[2,3,0,1] row_mask:0xf bank_mask:0xf
	s_waitcnt lgkmcnt(0)
	v_min_u32_e32 v17, v9, v15
	v_max_u32_e32 v9, v9, v15
	s_nop 1
	v_mov_b32_dpp v15, v5 quad_perm:[2,3,0,1] row_mask:0xf bank_mask:0xf
	v_cndmask_b32_e64 v9, v9, v17, s[0:1]
	s_waitcnt lgkmcnt(0)
	v_min_u32_e32 v17, v14, v12
	v_max_u32_e32 v12, v14, v12
	v_cndmask_b32_e64 v37, v12, v17, s[0:1]
	s_nop 1
	v_mov_b32_dpp v12, v8 quad_perm:[2,3,0,1] row_mask:0xf bank_mask:0xf
	s_waitcnt lgkmcnt(0)
	v_min_u32_e32 v14, v5, v15
	v_max_u32_e32 v5, v5, v15
	v_cndmask_b32_e64 v5, v5, v14, s[0:1]
	s_nop 1
	v_mov_b32_dpp v14, v11 quad_perm:[2,3,0,1] row_mask:0xf bank_mask:0xf
	s_waitcnt lgkmcnt(0)
	v_min_u32_e32 v15, v8, v12
	v_max_u32_e32 v8, v8, v12
	s_nop 1
	v_mov_b32_dpp v12, v16 quad_perm:[2,3,0,1] row_mask:0xf bank_mask:0xf
	v_cndmask_b32_e64 v8, v8, v15, s[0:1]
	s_waitcnt lgkmcnt(0)
	v_min_u32_e32 v15, v11, v14
	v_max_u32_e32 v11, v11, v14
	v_cndmask_b32_e64 v11, v11, v15, s[0:1]
	s_nop 1
	v_mov_b32_dpp v14, v6 quad_perm:[2,3,0,1] row_mask:0xf bank_mask:0xf
	s_waitcnt lgkmcnt(0)
	v_min_u32_e32 v15, v16, v12
	v_max_u32_e32 v12, v16, v12
	v_cndmask_b32_e64 v38, v12, v15, s[0:1]
	s_nop 1
	v_mov_b32_dpp v12, v7 quad_perm:[2,3,0,1] row_mask:0xf bank_mask:0xf
	s_waitcnt lgkmcnt(0)
	v_min_u32_e32 v15, v6, v14
	v_max_u32_e32 v6, v6, v14
	s_nop 1
	v_mov_b32_dpp v14, v2 quad_perm:[2,3,0,1] row_mask:0xf bank_mask:0xf
	v_cndmask_b32_e64 v6, v6, v15, s[0:1]
	s_waitcnt lgkmcnt(0)
	v_min_u32_e32 v15, v7, v12
	v_max_u32_e32 v7, v7, v12
	s_nop 1
	v_mov_b32_dpp v12, v10 quad_perm:[2,3,0,1] row_mask:0xf bank_mask:0xf
	v_cndmask_b32_e64 v7, v7, v15, s[0:1]
	s_waitcnt lgkmcnt(0)
	v_min_u32_e32 v15, v2, v14
	v_max_u32_e32 v2, v2, v14
	s_nop 1
	v_mov_b32_dpp v14, v0 quad_perm:[2,3,0,1] row_mask:0xf bank_mask:0xf
	v_cndmask_b32_e64 v2, v2, v15, s[0:1]
	s_waitcnt lgkmcnt(0)
	v_min_u32_e32 v15, v10, v12
	v_max_u32_e32 v10, v10, v12
	s_nop 1
	v_mov_b32_dpp v12, v4 quad_perm:[1,0,3,2] row_mask:0xf bank_mask:0xf
	v_cndmask_b32_e64 v10, v10, v15, s[0:1]
	s_waitcnt lgkmcnt(0)
	v_min_u32_e32 v15, v0, v14
	v_max_u32_e32 v0, v0, v14
	s_nop 1
	v_mov_b32_dpp v14, v1 quad_perm:[1,0,3,2] row_mask:0xf bank_mask:0xf
	v_cndmask_b32_e64 v39, v0, v15, s[0:1]
	s_waitcnt lgkmcnt(0)
	v_min_u32_e32 v0, v4, v12
	v_max_u32_e32 v4, v4, v12
	s_nop 1
	v_mov_b32_dpp v12, v13 quad_perm:[1,0,3,2] row_mask:0xf bank_mask:0xf
	v_cndmask_b32_e32 v0, v4, v0, vcc
	s_waitcnt lgkmcnt(0)
	v_min_u32_e32 v4, v1, v14
	v_max_u32_e32 v1, v1, v14
	v_cndmask_b32_e32 v108, v1, v4, vcc
	s_waitcnt lgkmcnt(0)
	v_min_u32_e32 v1, v13, v12
	v_max_u32_e32 v4, v13, v12
	v_cndmask_b32_e32 v106, v4, v1, vcc
	v_bfe_u32 v4, v46, 2, 2
	v_ashrrev_i32_e32 v12, 4, v46
	v_cmp_eq_u32_e64 s[6:7], v4, v12
	v_and_b32_e32 v4, 3, v46
	v_cmp_eq_u32_e64 s[8:9], 0, v4
	s_and_b64 s[8:9], s[8:9], s[6:7]
	s_nop 1
	v_mov_b32_dpp v1, v3 quad_perm:[1,0,3,2] row_mask:0xf bank_mask:0xf
	v_cndmask_b32_e64 v40, 0, 1.0, s[8:9]
	v_cmp_eq_u32_e64 s[8:9], 1, v4
	s_and_b64 s[8:9], s[8:9], s[6:7]
	v_mov_b32_e32 v60, 0
	v_cndmask_b32_e64 v42, 0, 1.0, s[8:9]
	v_cmp_eq_u32_e64 s[8:9], 2, v4
	s_and_b64 s[8:9], s[8:9], s[6:7]
	s_waitcnt lgkmcnt(0)
	v_min_u32_e32 v41, v3, v1
	v_cndmask_b32_e64 v48, 0, 1.0, s[8:9]
	v_cmp_eq_u32_e64 s[8:9], 3, v4
	s_and_b64 s[6:7], s[8:9], s[6:7]
	v_cndmask_b32_e64 v50, 0, 1.0, s[6:7]
	v_readlane_b32 s8, v0, 0
	s_waitcnt vmcnt(0) lgkmcnt(0)
	s_and_b32 s6, s8, 0xfffffc00
	v_readlane_b32 s7, v0, 1
	s_and_b32 s7, s7, 0xfffffc00
	buffer_load_dwordx4 v[12:15], v44, s[12:15], s6 offen
	s_nop 2
	buffer_load_dwordx4 v[28:31], v44, s[12:15], s7 offen
	v_readlane_b32 s6, v0, 2
	s_and_b32 s6, s6, 0xfffffc00
	v_readlane_b32 s7, v0, 3
	s_and_b32 s7, s7, 0xfffffc00
	s_nop 1
	buffer_load_dwordx4 v[16:19], v44, s[12:15], s6 offen
	s_nop 0
	buffer_load_dwordx4 v[32:35], v44, s[12:15], s7 offen
	v_readlane_b32 s6, v0, 4
	s_and_b32 s6, s6, 0xfffffc00
	v_readlane_b32 s7, v0, 5
	s_and_b32 s7, s7, 0xfffffc00
	s_nop 1
	buffer_load_dwordx4 v[24:27], v44, s[12:15], s6 offen
	s_nop 0
	buffer_load_dwordx4 v[20:23], v44, s[12:15], s7 offen
	s_nop 1
	v_mov_b32_dpp v4, v36 quad_perm:[1,0,3,2] row_mask:0xf bank_mask:0xf
	v_max_u32_e32 v1, v3, v1
	v_cndmask_b32_e32 v107, v1, v41, vcc
	s_nop 1
	v_mov_b32_dpp v1, v9 quad_perm:[1,0,3,2] row_mask:0xf bank_mask:0xf
	v_cmp_gt_i32_e64 s[6:7], 16, v46
	s_waitcnt lgkmcnt(0)
	v_min_u32_e32 v3, v36, v4
	v_max_u32_e32 v4, v36, v4
	v_cndmask_b32_e32 v105, v4, v3, vcc
	s_nop 1
	v_mov_b32_dpp v3, v37 quad_perm:[1,0,3,2] row_mask:0xf bank_mask:0xf
	s_waitcnt lgkmcnt(0)
	v_min_u32_e32 v4, v9, v1
	v_max_u32_e32 v1, v9, v1
	v_cndmask_b32_e32 v104, v1, v4, vcc
	s_nop 1
	v_mov_b32_dpp v1, v5 quad_perm:[1,0,3,2] row_mask:0xf bank_mask:0xf
	s_waitcnt lgkmcnt(0)
	v_min_u32_e32 v4, v37, v3
	v_max_u32_e32 v3, v37, v3
	v_cndmask_b32_e32 v103, v3, v4, vcc
	s_nop 1
	v_mov_b32_dpp v3, v8 quad_perm:[1,0,3,2] row_mask:0xf bank_mask:0xf
	s_waitcnt lgkmcnt(0)
	v_min_u32_e32 v4, v5, v1
	v_max_u32_e32 v1, v5, v1
	v_cndmask_b32_e32 v102, v1, v4, vcc
	s_nop 1
	v_mov_b32_dpp v1, v11 quad_perm:[1,0,3,2] row_mask:0xf bank_mask:0xf
	s_waitcnt lgkmcnt(0)
	v_min_u32_e32 v4, v8, v3
	v_max_u32_e32 v3, v8, v3
	v_cndmask_b32_e32 v101, v3, v4, vcc
	s_nop 1
	v_mov_b32_dpp v3, v38 quad_perm:[1,0,3,2] row_mask:0xf bank_mask:0xf
	s_waitcnt lgkmcnt(0)
	v_min_u32_e32 v4, v11, v1
	v_max_u32_e32 v1, v11, v1
	v_cndmask_b32_e32 v100, v1, v4, vcc
	s_nop 1
	v_mov_b32_dpp v1, v6 quad_perm:[1,0,3,2] row_mask:0xf bank_mask:0xf
	s_waitcnt lgkmcnt(0)
	v_min_u32_e32 v4, v38, v3
	v_max_u32_e32 v3, v38, v3
	v_cndmask_b32_e32 v99, v3, v4, vcc
	s_nop 1
	v_mov_b32_dpp v3, v7 quad_perm:[1,0,3,2] row_mask:0xf bank_mask:0xf
	s_waitcnt lgkmcnt(0)
	v_min_u32_e32 v4, v6, v1
	v_max_u32_e32 v1, v6, v1
	v_cndmask_b32_e32 v98, v1, v4, vcc
	s_nop 1
	v_mov_b32_dpp v1, v2 quad_perm:[1,0,3,2] row_mask:0xf bank_mask:0xf
	s_waitcnt lgkmcnt(0)
	v_min_u32_e32 v4, v7, v3
	v_max_u32_e32 v3, v7, v3
	v_cndmask_b32_e32 v97, v3, v4, vcc
	s_nop 1
	v_mov_b32_dpp v3, v10 quad_perm:[1,0,3,2] row_mask:0xf bank_mask:0xf
	s_waitcnt lgkmcnt(0)
	v_min_u32_e32 v4, v2, v1
	v_max_u32_e32 v1, v2, v1
	s_nop 1
	v_mov_b32_dpp v2, v39 quad_perm:[1,0,3,2] row_mask:0xf bank_mask:0xf
	v_cndmask_b32_e32 v96, v1, v4, vcc
	s_waitcnt lgkmcnt(0)
	v_min_u32_e32 v1, v10, v3
	v_max_u32_e32 v3, v10, v3
	v_cndmask_b32_e32 v95, v3, v1, vcc
	s_waitcnt lgkmcnt(0)
	v_min_u32_e32 v1, v39, v2
	v_max_u32_e32 v2, v39, v2
	v_cndmask_b32_e32 v93, v2, v1, vcc
	v_add_u32_e32 v1, s26, v109
	v_mov_b32_e32 v51, v50
	v_mov_b32_e32 v49, v48
	v_mov_b32_e32 v43, v42
	v_mov_b32_e32 v41, v40
	v_subrev_u32_e32 v89, 64, v1
	v_mov_b32_e32 v6, 0
	v_mov_b32_e32 v7, v91
	v_mov_b32_e32 v8, v91
	v_mov_b32_e32 v9, v91
	v_mov_b32_e32 v10, 0
	v_mov_b32_e32 v11, v91
	v_mov_b32_e32 v61, v91
	v_mov_b32_e32 v58, 0
	v_mov_b32_e32 v59, v91
	v_mov_b32_e32 v56, 0
	v_mov_b32_e32 v57, v91
	v_mov_b32_e32 v54, 0
	v_mov_b32_e32 v52, 0
	v_mov_b32_e32 v53, v91
